# GEMM K-loops: all per-segment s_setprio 1/0 toggles around the MMA blocks removed (no priority flips at all)
# speedup vs baseline: 1.0064x; 1.0049x over previous
.LBB0_398:
	s_add_u32 s48, s10, 0xfffc0080
	s_addc_u32 s49, s11, -1
	s_add_i32 s83, 0, 0x10000
	s_cmp_eq_u32 s67, 12
	s_cselect_b32 s61, s9, s49
	s_cselect_b32 s60, s55, s48
	v_add_u32_e32 v128, s83, v173
	s_cselect_b32 s49, s53, s66
	s_cselect_b32 s48, s64, s65
	s_add_i32 s85, 0, 0x14000
	ds_read_b128 v[168:171], v128
	ds_read_b128 v[176:179], v128 offset:1024
	ds_read_b128 v[180:183], v128 offset:2048
	ds_read_b128 v[184:187], v128 offset:3072
	v_add_u32_e32 v128, s85, v173
	ds_read_b128 v[188:191], v128
	ds_read_b128 v[192:195], v128 offset:1024
	ds_read_b128 v[196:199], v128 offset:2048
	ds_read_b128 v[202:205], v128 offset:3072
	s_add_i32 m0, s63, 0xc000
	ds_read_b128 v[206:209], v200
	ds_read_b128 v[210:213], v200 offset:1024
	ds_read_b128 v[218:221], v200 offset:2048
	ds_read_b128 v[222:225], v200 offset:3072
	ds_read_b128 v[226:229], v200 offset:4096
	ds_read_b128 v[234:237], v200 offset:5120
	ds_read_b128 v[238:241], v200 offset:6144
	ds_read_b128 v[242:245], v200 offset:7168
	global_load_lds_dwordx4 v148, s[10:11]
	s_add_i32 m0, s63, 0xe000
	s_nop 0
	global_load_lds_dwordx4 v150, s[10:11]
	s_waitcnt vmcnt(8)
	s_waitcnt lgkmcnt(0)
	s_barrier
	s_waitcnt lgkmcnt(0)
	v_mfma_f32_16x16x32_bf16 v[124:127], v[168:171], v[206:209], v[124:127]
	v_mfma_f32_16x16x32_bf16 v[120:123], v[180:183], v[206:209], v[120:123]
	v_mfma_f32_16x16x32_bf16 v[108:111], v[168:171], v[218:221], v[108:111]
	v_mfma_f32_16x16x32_bf16 v[104:107], v[180:183], v[218:221], v[104:107]
	v_mfma_f32_16x16x32_bf16 v[92:95], v[168:171], v[226:229], v[92:95]
	v_mfma_f32_16x16x32_bf16 v[88:91], v[180:183], v[226:229], v[88:91]
	v_mfma_f32_16x16x32_bf16 v[76:79], v[168:171], v[238:241], v[76:79]
	v_mfma_f32_16x16x32_bf16 v[72:75], v[180:183], v[238:241], v[72:75]
	v_mfma_f32_16x16x32_bf16 v[124:127], v[176:179], v[210:213], v[124:127]
	v_mfma_f32_16x16x32_bf16 v[120:123], v[184:187], v[210:213], v[120:123]
	v_mfma_f32_16x16x32_bf16 v[108:111], v[176:179], v[222:225], v[108:111]
	v_mfma_f32_16x16x32_bf16 v[104:107], v[184:187], v[222:225], v[104:107]
	v_mfma_f32_16x16x32_bf16 v[92:95], v[176:179], v[234:237], v[92:95]
	v_mfma_f32_16x16x32_bf16 v[88:91], v[184:187], v[234:237], v[88:91]
	v_mfma_f32_16x16x32_bf16 v[76:79], v[176:179], v[242:245], v[76:79]
	v_mfma_f32_16x16x32_bf16 v[72:75], v[184:187], v[242:245], v[72:75]
	v_mfma_f32_16x16x32_bf16 v[116:119], v[188:191], v[206:209], v[116:119]
	v_mfma_f32_16x16x32_bf16 v[112:115], v[196:199], v[206:209], v[112:115]
	v_mfma_f32_16x16x32_bf16 v[100:103], v[188:191], v[218:221], v[100:103]
	v_mfma_f32_16x16x32_bf16 v[96:99], v[196:199], v[218:221], v[96:99]
	v_mfma_f32_16x16x32_bf16 v[84:87], v[188:191], v[226:229], v[84:87]
	v_mfma_f32_16x16x32_bf16 v[80:83], v[196:199], v[226:229], v[80:83]
	v_mfma_f32_16x16x32_bf16 v[68:71], v[188:191], v[238:241], v[68:71]
	v_mfma_f32_16x16x32_bf16 v[64:67], v[196:199], v[238:241], v[64:67]
	v_mfma_f32_16x16x32_bf16 v[116:119], v[192:195], v[210:213], v[116:119]
	v_mfma_f32_16x16x32_bf16 v[112:115], v[202:205], v[210:213], v[112:115]
	v_mfma_f32_16x16x32_bf16 v[100:103], v[192:195], v[222:225], v[100:103]
	v_mfma_f32_16x16x32_bf16 v[96:99], v[202:205], v[222:225], v[96:99]
	v_mfma_f32_16x16x32_bf16 v[84:87], v[192:195], v[234:237], v[84:87]
	v_mfma_f32_16x16x32_bf16 v[80:83], v[202:205], v[234:237], v[80:83]
	v_mfma_f32_16x16x32_bf16 v[68:71], v[192:195], v[242:245], v[68:71]
	v_mfma_f32_16x16x32_bf16 v[64:67], v[202:205], v[242:245], v[64:67]
	s_barrier
	s_add_i32 s83, s83, s74
	s_mov_b64 s[98:99], s[48:49]
	s_mov_b32 m0, s83
	ds_read_b128 v[206:209], v200 offset:16384
	ds_read_b128 v[210:213], v200 offset:17408
	ds_read_b128 v[218:221], v200 offset:18432
	ds_read_b128 v[222:225], v200 offset:19456
	ds_read_b128 v[226:229], v200 offset:20480
	ds_read_b128 v[234:237], v200 offset:21504
	ds_read_b128 v[238:241], v200 offset:22528
	ds_read_b128 v[242:245], v200 offset:23552
	global_load_lds_dwordx4 v136, s[48:49]
	s_add_i32 m0, s83, 0x2000
	s_add_u32 s86, s48, 0x40000
	s_addc_u32 s87, s49, 0
	s_add_i32 s83, s85, s74
	global_load_lds_dwordx4 v140, s[48:49]
	s_mov_b32 m0, s83
	s_mov_b64 s[100:101], s[60:61]
	global_load_lds_dwordx4 v136, s[86:87]
	s_add_i32 m0, s83, 0x2000
	s_nop 0
	global_load_lds_dwordx4 v140, s[86:87]
	s_mov_b32 m0, s63
	s_nop 0
	global_load_lds_dwordx4 v134, s[60:61]
	s_mov_b32 m0, s75
	s_nop 0
	global_load_lds_dwordx4 v138, s[60:61]
	s_waitcnt vmcnt(8)
	s_waitcnt lgkmcnt(0)
	s_barrier
	s_waitcnt lgkmcnt(0)
	v_mfma_f32_16x16x32_bf16 v[60:63], v[168:171], v[206:209], v[60:63]
	v_mfma_f32_16x16x32_bf16 v[56:59], v[180:183], v[206:209], v[56:59]
	v_mfma_f32_16x16x32_bf16 v[44:47], v[168:171], v[218:221], v[44:47]
	v_mfma_f32_16x16x32_bf16 v[40:43], v[180:183], v[218:221], v[40:43]
	v_mfma_f32_16x16x32_bf16 v[28:31], v[168:171], v[226:229], v[28:31]
	v_mfma_f32_16x16x32_bf16 v[24:27], v[180:183], v[226:229], v[24:27]
	v_mfma_f32_16x16x32_bf16 v[12:15], v[168:171], v[238:241], v[12:15]
	v_mfma_f32_16x16x32_bf16 v[8:11], v[180:183], v[238:241], v[8:11]
	v_mfma_f32_16x16x32_bf16 v[60:63], v[176:179], v[210:213], v[60:63]
	v_mfma_f32_16x16x32_bf16 v[56:59], v[184:187], v[210:213], v[56:59]
	v_mfma_f32_16x16x32_bf16 v[44:47], v[176:179], v[222:225], v[44:47]
	v_mfma_f32_16x16x32_bf16 v[40:43], v[184:187], v[222:225], v[40:43]
	v_mfma_f32_16x16x32_bf16 v[28:31], v[176:179], v[234:237], v[28:31]
	v_mfma_f32_16x16x32_bf16 v[24:27], v[184:187], v[234:237], v[24:27]
	v_mfma_f32_16x16x32_bf16 v[12:15], v[176:179], v[242:245], v[12:15]
	v_mfma_f32_16x16x32_bf16 v[8:11], v[184:187], v[242:245], v[8:11]
	v_mfma_f32_16x16x32_bf16 v[52:55], v[188:191], v[206:209], v[52:55]
	v_mfma_f32_16x16x32_bf16 v[48:51], v[196:199], v[206:209], v[48:51]
	v_mfma_f32_16x16x32_bf16 v[36:39], v[188:191], v[218:221], v[36:39]
	v_mfma_f32_16x16x32_bf16 v[32:35], v[196:199], v[218:221], v[32:35]
	v_mfma_f32_16x16x32_bf16 v[20:23], v[188:191], v[226:229], v[20:23]
	v_mfma_f32_16x16x32_bf16 v[16:19], v[196:199], v[226:229], v[16:19]
	v_mfma_f32_16x16x32_bf16 v[4:7], v[188:191], v[238:241], v[4:7]
	v_mfma_f32_16x16x32_bf16 v[0:3], v[196:199], v[238:241], v[0:3]
	v_mfma_f32_16x16x32_bf16 v[52:55], v[192:195], v[210:213], v[52:55]
	v_mfma_f32_16x16x32_bf16 v[48:51], v[202:205], v[210:213], v[48:51]
	v_mfma_f32_16x16x32_bf16 v[36:39], v[192:195], v[222:225], v[36:39]
	v_mfma_f32_16x16x32_bf16 v[32:35], v[202:205], v[222:225], v[32:35]
	v_mfma_f32_16x16x32_bf16 v[20:23], v[192:195], v[234:237], v[20:23]
	v_mfma_f32_16x16x32_bf16 v[16:19], v[202:205], v[234:237], v[16:19]
	v_mfma_f32_16x16x32_bf16 v[4:7], v[192:195], v[242:245], v[4:7]
	v_mfma_f32_16x16x32_bf16 v[0:3], v[202:205], v[242:245], v[0:3]
	s_barrier
	v_add_u32_e32 v128, s0, v173
	s_add_i32 s83, 0, 0x1c000
	ds_read_b128 v[168:171], v128
	ds_read_b128 v[176:179], v128 offset:1024
	ds_read_b128 v[180:183], v128 offset:2048
	ds_read_b128 v[184:187], v128 offset:3072
	v_add_u32_e32 v128, s83, v173
	ds_read_b128 v[188:191], v128
	ds_read_b128 v[192:195], v128 offset:1024
	ds_read_b128 v[196:199], v128 offset:2048
	ds_read_b128 v[202:205], v128 offset:3072
	s_add_u32 s60, s60, 0x40000
	s_addc_u32 s61, s61, 0
	s_mov_b32 m0, s76
	ds_read_b128 v[206:209], v200 offset:32768
	ds_read_b128 v[210:213], v200 offset:33792
	ds_read_b128 v[218:221], v200 offset:34816
	ds_read_b128 v[222:225], v200 offset:35840
	ds_read_b128 v[226:229], v200 offset:36864
	ds_read_b128 v[234:237], v200 offset:37888
	ds_read_b128 v[238:241], v200 offset:38912
	ds_read_b128 v[242:245], v200 offset:39936
	global_load_lds_dwordx4 v134, s[60:61]
	v_lshl_add_u64 v[250:251], s[60:61], 0, v[138:139]
	s_mov_b32 m0, s77
	s_nop 0
	global_load_lds_dwordx4 v[250:251], off
	s_waitcnt vmcnt(8)
	s_waitcnt lgkmcnt(0)
	s_barrier
	s_waitcnt lgkmcnt(0)
	v_mfma_f32_16x16x32_bf16 v[124:127], v[168:171], v[206:209], v[124:127]
	v_mfma_f32_16x16x32_bf16 v[120:123], v[180:183], v[206:209], v[120:123]
	v_mfma_f32_16x16x32_bf16 v[108:111], v[168:171], v[218:221], v[108:111]
	v_mfma_f32_16x16x32_bf16 v[104:107], v[180:183], v[218:221], v[104:107]
	v_mfma_f32_16x16x32_bf16 v[92:95], v[168:171], v[226:229], v[92:95]
	v_mfma_f32_16x16x32_bf16 v[88:91], v[180:183], v[226:229], v[88:91]
	v_mfma_f32_16x16x32_bf16 v[76:79], v[168:171], v[238:241], v[76:79]
	v_mfma_f32_16x16x32_bf16 v[72:75], v[180:183], v[238:241], v[72:75]
	v_mfma_f32_16x16x32_bf16 v[124:127], v[176:179], v[210:213], v[124:127]
	v_mfma_f32_16x16x32_bf16 v[120:123], v[184:187], v[210:213], v[120:123]
	v_mfma_f32_16x16x32_bf16 v[108:111], v[176:179], v[222:225], v[108:111]
	v_mfma_f32_16x16x32_bf16 v[104:107], v[184:187], v[222:225], v[104:107]
	v_mfma_f32_16x16x32_bf16 v[92:95], v[176:179], v[234:237], v[92:95]
	v_mfma_f32_16x16x32_bf16 v[88:91], v[184:187], v[234:237], v[88:91]
	v_mfma_f32_16x16x32_bf16 v[76:79], v[176:179], v[242:245], v[76:79]
	v_mfma_f32_16x16x32_bf16 v[72:75], v[184:187], v[242:245], v[72:75]
	v_mfma_f32_16x16x32_bf16 v[116:119], v[188:191], v[206:209], v[116:119]
	v_mfma_f32_16x16x32_bf16 v[112:115], v[196:199], v[206:209], v[112:115]
	v_mfma_f32_16x16x32_bf16 v[100:103], v[188:191], v[218:221], v[100:103]
	v_mfma_f32_16x16x32_bf16 v[96:99], v[196:199], v[218:221], v[96:99]
	v_mfma_f32_16x16x32_bf16 v[84:87], v[188:191], v[226:229], v[84:87]
	v_mfma_f32_16x16x32_bf16 v[80:83], v[196:199], v[226:229], v[80:83]
	v_mfma_f32_16x16x32_bf16 v[68:71], v[188:191], v[238:241], v[68:71]
	v_mfma_f32_16x16x32_bf16 v[64:67], v[196:199], v[238:241], v[64:67]
	v_mfma_f32_16x16x32_bf16 v[116:119], v[192:195], v[210:213], v[116:119]
	v_mfma_f32_16x16x32_bf16 v[112:115], v[202:205], v[210:213], v[112:115]
	v_mfma_f32_16x16x32_bf16 v[100:103], v[192:195], v[222:225], v[100:103]
	v_mfma_f32_16x16x32_bf16 v[96:99], v[202:205], v[222:225], v[96:99]
	v_mfma_f32_16x16x32_bf16 v[84:87], v[192:195], v[234:237], v[84:87]
	v_mfma_f32_16x16x32_bf16 v[80:83], v[202:205], v[234:237], v[80:83]
	v_mfma_f32_16x16x32_bf16 v[68:71], v[192:195], v[242:245], v[68:71]
	v_mfma_f32_16x16x32_bf16 v[64:67], v[202:205], v[242:245], v[64:67]
	s_barrier
	s_add_i32 s60, s0, s74
	s_add_u32 s98, s98, s12
	s_addc_u32 s99, s99, s13
	s_mov_b32 m0, s60
	ds_read_b128 v[206:209], v200 offset:49152
	ds_read_b128 v[210:213], v200 offset:50176
	ds_read_b128 v[218:221], v200 offset:51200
	ds_read_b128 v[222:225], v200 offset:52224
	ds_read_b128 v[226:229], v200 offset:53248
	ds_read_b128 v[234:237], v200 offset:54272
	ds_read_b128 v[238:241], v200 offset:55296
	ds_read_b128 v[242:245], v200 offset:56320
	global_load_lds_dwordx4 v136, s[98:99]
	s_add_i32 m0, s60, 0x2000
	s_add_u32 s48, s48, 0x40080
	s_addc_u32 s49, s49, 0
	s_add_i32 s60, s83, s74
	global_load_lds_dwordx4 v140, s[98:99]
	s_mov_b32 m0, s60
	s_nop 0
	global_load_lds_dwordx4 v136, s[48:49]
	s_add_i32 m0, s60, 0x2000
	s_nop 0
	global_load_lds_dwordx4 v140, s[48:49]
	s_add_u32 s100, s100, s12
	s_addc_u32 s101, s101, s13
	s_mov_b32 m0, s78
	s_nop 0
	global_load_lds_dwordx4 v134, s[100:101]
	s_mov_b32 m0, s79
	s_nop 0
	global_load_lds_dwordx4 v138, s[100:101]
	s_waitcnt vmcnt(8)
	s_waitcnt lgkmcnt(0)
	s_barrier
	s_waitcnt lgkmcnt(0)
	v_mfma_f32_16x16x32_bf16 v[60:63], v[168:171], v[206:209], v[60:63]
	v_mfma_f32_16x16x32_bf16 v[56:59], v[180:183], v[206:209], v[56:59]
	v_mfma_f32_16x16x32_bf16 v[44:47], v[168:171], v[218:221], v[44:47]
	v_mfma_f32_16x16x32_bf16 v[40:43], v[180:183], v[218:221], v[40:43]
	v_mfma_f32_16x16x32_bf16 v[28:31], v[168:171], v[226:229], v[28:31]
	v_mfma_f32_16x16x32_bf16 v[24:27], v[180:183], v[226:229], v[24:27]
	v_mfma_f32_16x16x32_bf16 v[12:15], v[168:171], v[238:241], v[12:15]
	v_mfma_f32_16x16x32_bf16 v[8:11], v[180:183], v[238:241], v[8:11]
	v_mfma_f32_16x16x32_bf16 v[60:63], v[176:179], v[210:213], v[60:63]
	v_mfma_f32_16x16x32_bf16 v[56:59], v[184:187], v[210:213], v[56:59]
	v_mfma_f32_16x16x32_bf16 v[44:47], v[176:179], v[222:225], v[44:47]
	v_mfma_f32_16x16x32_bf16 v[40:43], v[184:187], v[222:225], v[40:43]
	v_mfma_f32_16x16x32_bf16 v[28:31], v[176:179], v[234:237], v[28:31]
	v_mfma_f32_16x16x32_bf16 v[24:27], v[184:187], v[234:237], v[24:27]
	v_mfma_f32_16x16x32_bf16 v[12:15], v[176:179], v[242:245], v[12:15]
	v_mfma_f32_16x16x32_bf16 v[8:11], v[184:187], v[242:245], v[8:11]
	v_mfma_f32_16x16x32_bf16 v[52:55], v[188:191], v[206:209], v[52:55]
	v_mfma_f32_16x16x32_bf16 v[48:51], v[196:199], v[206:209], v[48:51]
	v_mfma_f32_16x16x32_bf16 v[36:39], v[188:191], v[218:221], v[36:39]
	v_mfma_f32_16x16x32_bf16 v[32:35], v[196:199], v[218:221], v[32:35]
	v_mfma_f32_16x16x32_bf16 v[20:23], v[188:191], v[226:229], v[20:23]
	v_mfma_f32_16x16x32_bf16 v[16:19], v[196:199], v[226:229], v[16:19]
	v_mfma_f32_16x16x32_bf16 v[4:7], v[188:191], v[238:241], v[4:7]
	v_mfma_f32_16x16x32_bf16 v[0:3], v[196:199], v[238:241], v[0:3]
	v_mfma_f32_16x16x32_bf16 v[52:55], v[192:195], v[210:213], v[52:55]
	v_mfma_f32_16x16x32_bf16 v[48:51], v[202:205], v[210:213], v[48:51]
	v_mfma_f32_16x16x32_bf16 v[36:39], v[192:195], v[222:225], v[36:39]
	v_mfma_f32_16x16x32_bf16 v[32:35], v[202:205], v[222:225], v[32:35]
	v_mfma_f32_16x16x32_bf16 v[20:23], v[192:195], v[234:237], v[20:23]
	v_mfma_f32_16x16x32_bf16 v[16:19], v[202:205], v[234:237], v[16:19]
	v_mfma_f32_16x16x32_bf16 v[4:7], v[192:195], v[242:245], v[4:7]
	v_mfma_f32_16x16x32_bf16 v[0:3], v[202:205], v[242:245], v[0:3]
	s_barrier
	s_add_i32 s67, s67, 2
	s_add_u32 s10, s10, 0x100
	s_addc_u32 s11, s11, 0
	s_add_u32 s65, s65, 0x100
	s_addc_u32 s66, s66, 0
	s_cmp_gt_u32 s67, 13
	s_cbranch_scc0 .LBB0_398
	s_and_b64 vcc, exec, s[50:51]
	s_cbranch_vccz .LBB0_401
	s_barrier

.LBB0_479:
	s_add_u32 s66, s48, 0xfffe0080
	s_addc_u32 s67, s49, -1
	s_add_i32 s90, 0, 0x10000
	s_cmp_eq_u32 vcc_lo, 4
	s_cselect_b32 s71, s9, s67
	s_cselect_b32 s70, s61, s66
	s_cselect_b32 s67, s59, s83
	s_cselect_b32 s66, s72, s73
	s_add_i32 vcc_hi, 0, 0x14000
	v_add_u32_e32 v140, s90, v225
	v_add_u32_e32 v144, vcc_hi, v225
	ds_read_b128 v[128:131], v140
	ds_read_b128 v[132:135], v140 offset:1024
	ds_read_b128 v[136:139], v140 offset:2048
	ds_read_b128 v[140:143], v140 offset:3072
	ds_read_b128 v[174:177], v144
	ds_read_b128 v[178:181], v144 offset:1024
	ds_read_b128 v[182:185], v144 offset:2048
	ds_read_b128 v[186:189], v144 offset:3072
	s_add_i32 m0, s4, 0xc000
	ds_read_b128 v[190:193], v228
	ds_read_b128 v[194:197], v228 offset:1024
	ds_read_b128 v[198:201], v228 offset:2048
	ds_read_b128 v[202:205], v228 offset:3072
	ds_read_b128 v[206:209], v228 offset:4096
	ds_read_b128 v[210:213], v228 offset:5120
	ds_read_b128 v[234:237], v228 offset:6144
	ds_read_b128 v[238:241], v228 offset:7168
	global_load_lds_dwordx4 v168, s[48:49]
	s_add_i32 m0, s4, 0xe000
	s_nop 0
	global_load_lds_dwordx4 v170, s[48:49]
	s_waitcnt vmcnt(8)
	s_waitcnt lgkmcnt(0)
	s_barrier
	s_waitcnt lgkmcnt(0)
	v_mfma_i32_16x16x64_i8 v[124:127], v[128:131], v[190:193], v[124:127]
	v_mfma_i32_16x16x64_i8 v[120:123], v[136:139], v[190:193], v[120:123]
	v_mfma_i32_16x16x64_i8 v[116:119], v[128:131], v[198:201], v[116:119]
	v_mfma_i32_16x16x64_i8 v[112:115], v[136:139], v[198:201], v[112:115]
	v_mfma_i32_16x16x64_i8 v[108:111], v[128:131], v[206:209], v[108:111]
	v_mfma_i32_16x16x64_i8 v[104:107], v[136:139], v[206:209], v[104:107]
	v_mfma_i32_16x16x64_i8 v[100:103], v[128:131], v[234:237], v[100:103]
	v_mfma_i32_16x16x64_i8 v[96:99], v[136:139], v[234:237], v[96:99]
	v_mfma_i32_16x16x64_i8 v[124:127], v[132:135], v[194:197], v[124:127]
	v_mfma_i32_16x16x64_i8 v[120:123], v[140:143], v[194:197], v[120:123]
	v_mfma_i32_16x16x64_i8 v[116:119], v[132:135], v[202:205], v[116:119]
	v_mfma_i32_16x16x64_i8 v[112:115], v[140:143], v[202:205], v[112:115]
	v_mfma_i32_16x16x64_i8 v[108:111], v[132:135], v[210:213], v[108:111]
	v_mfma_i32_16x16x64_i8 v[104:107], v[140:143], v[210:213], v[104:107]
	v_mfma_i32_16x16x64_i8 v[100:103], v[132:135], v[238:241], v[100:103]
	v_mfma_i32_16x16x64_i8 v[96:99], v[140:143], v[238:241], v[96:99]
	v_mfma_i32_16x16x64_i8 v[92:95], v[174:177], v[190:193], v[92:95]
	v_mfma_i32_16x16x64_i8 v[88:91], v[182:185], v[190:193], v[88:91]
	v_mfma_i32_16x16x64_i8 v[84:87], v[174:177], v[198:201], v[84:87]
	v_mfma_i32_16x16x64_i8 v[80:83], v[182:185], v[198:201], v[80:83]
	v_mfma_i32_16x16x64_i8 v[76:79], v[174:177], v[206:209], v[76:79]
	v_mfma_i32_16x16x64_i8 v[72:75], v[182:185], v[206:209], v[72:75]
	v_mfma_i32_16x16x64_i8 v[68:71], v[174:177], v[234:237], v[68:71]
	v_mfma_i32_16x16x64_i8 v[64:67], v[182:185], v[234:237], v[64:67]
	v_mfma_i32_16x16x64_i8 v[92:95], v[178:181], v[194:197], v[92:95]
	v_mfma_i32_16x16x64_i8 v[88:91], v[186:189], v[194:197], v[88:91]
	v_mfma_i32_16x16x64_i8 v[84:87], v[178:181], v[202:205], v[84:87]
	v_mfma_i32_16x16x64_i8 v[80:83], v[186:189], v[202:205], v[80:83]
	v_mfma_i32_16x16x64_i8 v[76:79], v[178:181], v[210:213], v[76:79]
	v_mfma_i32_16x16x64_i8 v[72:75], v[186:189], v[210:213], v[72:75]
	v_mfma_i32_16x16x64_i8 v[68:71], v[178:181], v[238:241], v[68:71]
	v_mfma_i32_16x16x64_i8 v[64:67], v[186:189], v[238:241], v[64:67]
	s_barrier
	s_add_i32 s90, s90, s77
	s_mov_b64 s[98:99], s[66:67]
	s_mov_b32 m0, s90
	ds_read_b128 v[190:193], v228 offset:16384
	ds_read_b128 v[194:197], v228 offset:17408
	ds_read_b128 v[198:201], v228 offset:18432
	ds_read_b128 v[202:205], v228 offset:19456
	ds_read_b128 v[206:209], v228 offset:20480
	ds_read_b128 v[210:213], v228 offset:21504
	ds_read_b128 v[234:237], v228 offset:22528
	ds_read_b128 v[238:241], v228 offset:23552
	global_load_lds_dwordx4 v154, s[66:67]
	s_add_i32 m0, s90, 0x2000
	s_add_u32 s90, s66, 0x20000
	s_addc_u32 s91, s67, 0
	s_add_i32 vcc_hi, vcc_hi, s77
	global_load_lds_dwordx4 v158, s[66:67]
	s_mov_b32 m0, vcc_hi
	s_mov_b64 s[100:101], s[70:71]
	global_load_lds_dwordx4 v154, s[90:91]
	s_add_i32 m0, vcc_hi, 0x2000
	s_nop 0
	global_load_lds_dwordx4 v158, s[90:91]
	s_mov_b32 m0, s4
	s_nop 0
	global_load_lds_dwordx4 v152, s[70:71]
	s_mov_b32 m0, s5
	s_nop 0
	global_load_lds_dwordx4 v156, s[70:71]
	s_waitcnt vmcnt(8)
	s_waitcnt lgkmcnt(0)
	s_barrier
	s_waitcnt lgkmcnt(0)
	v_mfma_i32_16x16x64_i8 v[60:63], v[128:131], v[190:193], v[60:63]
	v_mfma_i32_16x16x64_i8 v[56:59], v[136:139], v[190:193], v[56:59]
	v_mfma_i32_16x16x64_i8 v[52:55], v[128:131], v[198:201], v[52:55]
	v_mfma_i32_16x16x64_i8 v[48:51], v[136:139], v[198:201], v[48:51]
	v_mfma_i32_16x16x64_i8 v[44:47], v[128:131], v[206:209], v[44:47]
	v_mfma_i32_16x16x64_i8 v[40:43], v[136:139], v[206:209], v[40:43]
	v_mfma_i32_16x16x64_i8 v[36:39], v[128:131], v[234:237], v[36:39]
	v_mfma_i32_16x16x64_i8 v[32:35], v[136:139], v[234:237], v[32:35]
	v_mfma_i32_16x16x64_i8 v[60:63], v[132:135], v[194:197], v[60:63]
	v_mfma_i32_16x16x64_i8 v[56:59], v[140:143], v[194:197], v[56:59]
	v_mfma_i32_16x16x64_i8 v[52:55], v[132:135], v[202:205], v[52:55]
	v_mfma_i32_16x16x64_i8 v[48:51], v[140:143], v[202:205], v[48:51]
	v_mfma_i32_16x16x64_i8 v[44:47], v[132:135], v[210:213], v[44:47]
	v_mfma_i32_16x16x64_i8 v[40:43], v[140:143], v[210:213], v[40:43]
	v_mfma_i32_16x16x64_i8 v[36:39], v[132:135], v[238:241], v[36:39]
	v_mfma_i32_16x16x64_i8 v[32:35], v[140:143], v[238:241], v[32:35]
	v_mfma_i32_16x16x64_i8 v[28:31], v[174:177], v[190:193], v[28:31]
	v_mfma_i32_16x16x64_i8 v[24:27], v[182:185], v[190:193], v[24:27]
	v_mfma_i32_16x16x64_i8 v[20:23], v[174:177], v[198:201], v[20:23]
	v_mfma_i32_16x16x64_i8 v[16:19], v[182:185], v[198:201], v[16:19]
	v_mfma_i32_16x16x64_i8 v[12:15], v[174:177], v[206:209], v[12:15]
	v_mfma_i32_16x16x64_i8 v[8:11], v[182:185], v[206:209], v[8:11]
	v_mfma_i32_16x16x64_i8 v[4:7], v[174:177], v[234:237], v[4:7]
	v_mfma_i32_16x16x64_i8 v[0:3], v[182:185], v[234:237], v[0:3]
	v_mfma_i32_16x16x64_i8 v[28:31], v[178:181], v[194:197], v[28:31]
	v_mfma_i32_16x16x64_i8 v[24:27], v[186:189], v[194:197], v[24:27]
	v_mfma_i32_16x16x64_i8 v[20:23], v[178:181], v[202:205], v[20:23]
	v_mfma_i32_16x16x64_i8 v[16:19], v[186:189], v[202:205], v[16:19]
	v_mfma_i32_16x16x64_i8 v[12:15], v[178:181], v[210:213], v[12:15]
	v_mfma_i32_16x16x64_i8 v[8:11], v[186:189], v[210:213], v[8:11]
	v_mfma_i32_16x16x64_i8 v[4:7], v[178:181], v[238:241], v[4:7]
	v_mfma_i32_16x16x64_i8 v[0:3], v[186:189], v[238:241], v[0:3]
	s_barrier
	s_add_i32 s90, 0, 0x1c000
	v_add_u32_e32 v140, s0, v225
	v_add_u32_e32 v144, s90, v225
	ds_read_b128 v[128:131], v140
	ds_read_b128 v[132:135], v140 offset:1024
	ds_read_b128 v[136:139], v140 offset:2048
	ds_read_b128 v[140:143], v140 offset:3072
	ds_read_b128 v[174:177], v144
	ds_read_b128 v[178:181], v144 offset:1024
	ds_read_b128 v[182:185], v144 offset:2048
	ds_read_b128 v[186:189], v144 offset:3072
	s_add_u32 s70, s70, 0x20000
	s_addc_u32 s71, s71, 0
	s_mov_b32 m0, s80
	ds_read_b128 v[190:193], v228 offset:32768
	ds_read_b128 v[194:197], v228 offset:33792
	ds_read_b128 v[198:201], v228 offset:34816
	ds_read_b128 v[202:205], v228 offset:35840
	ds_read_b128 v[206:209], v228 offset:36864
	ds_read_b128 v[210:213], v228 offset:37888
	ds_read_b128 v[234:237], v228 offset:38912
	ds_read_b128 v[238:241], v228 offset:39936
	global_load_lds_dwordx4 v152, s[70:71]
	v_lshl_add_u64 v[248:249], s[70:71], 0, v[156:157]
	s_mov_b32 m0, s82
	s_nop 0
	global_load_lds_dwordx4 v[248:249], off
	s_waitcnt vmcnt(8)
	s_waitcnt lgkmcnt(0)
	s_barrier
	s_waitcnt lgkmcnt(0)
	v_mfma_i32_16x16x64_i8 v[124:127], v[128:131], v[190:193], v[124:127]
	v_mfma_i32_16x16x64_i8 v[120:123], v[136:139], v[190:193], v[120:123]
	v_mfma_i32_16x16x64_i8 v[116:119], v[128:131], v[198:201], v[116:119]
	v_mfma_i32_16x16x64_i8 v[112:115], v[136:139], v[198:201], v[112:115]
	v_mfma_i32_16x16x64_i8 v[108:111], v[128:131], v[206:209], v[108:111]
	v_mfma_i32_16x16x64_i8 v[104:107], v[136:139], v[206:209], v[104:107]
	v_mfma_i32_16x16x64_i8 v[100:103], v[128:131], v[234:237], v[100:103]
	v_mfma_i32_16x16x64_i8 v[96:99], v[136:139], v[234:237], v[96:99]
	v_mfma_i32_16x16x64_i8 v[124:127], v[132:135], v[194:197], v[124:127]
	v_mfma_i32_16x16x64_i8 v[120:123], v[140:143], v[194:197], v[120:123]
	v_mfma_i32_16x16x64_i8 v[116:119], v[132:135], v[202:205], v[116:119]
	v_mfma_i32_16x16x64_i8 v[112:115], v[140:143], v[202:205], v[112:115]
	v_mfma_i32_16x16x64_i8 v[108:111], v[132:135], v[210:213], v[108:111]
	v_mfma_i32_16x16x64_i8 v[104:107], v[140:143], v[210:213], v[104:107]
	v_mfma_i32_16x16x64_i8 v[100:103], v[132:135], v[238:241], v[100:103]
	v_mfma_i32_16x16x64_i8 v[96:99], v[140:143], v[238:241], v[96:99]
	v_mfma_i32_16x16x64_i8 v[92:95], v[174:177], v[190:193], v[92:95]
	v_mfma_i32_16x16x64_i8 v[88:91], v[182:185], v[190:193], v[88:91]
	v_mfma_i32_16x16x64_i8 v[84:87], v[174:177], v[198:201], v[84:87]
	v_mfma_i32_16x16x64_i8 v[80:83], v[182:185], v[198:201], v[80:83]
	v_mfma_i32_16x16x64_i8 v[76:79], v[174:177], v[206:209], v[76:79]
	v_mfma_i32_16x16x64_i8 v[72:75], v[182:185], v[206:209], v[72:75]
	v_mfma_i32_16x16x64_i8 v[68:71], v[174:177], v[234:237], v[68:71]
	v_mfma_i32_16x16x64_i8 v[64:67], v[182:185], v[234:237], v[64:67]
	v_mfma_i32_16x16x64_i8 v[92:95], v[178:181], v[194:197], v[92:95]
	v_mfma_i32_16x16x64_i8 v[88:91], v[186:189], v[194:197], v[88:91]
	v_mfma_i32_16x16x64_i8 v[84:87], v[178:181], v[202:205], v[84:87]
	v_mfma_i32_16x16x64_i8 v[80:83], v[186:189], v[202:205], v[80:83]
	v_mfma_i32_16x16x64_i8 v[76:79], v[178:181], v[210:213], v[76:79]
	v_mfma_i32_16x16x64_i8 v[72:75], v[186:189], v[210:213], v[72:75]
	v_mfma_i32_16x16x64_i8 v[68:71], v[178:181], v[238:241], v[68:71]
	v_mfma_i32_16x16x64_i8 v[64:67], v[186:189], v[238:241], v[64:67]
	s_barrier
	s_add_i32 s70, s0, s77
	s_add_u32 s98, s98, s14
	s_addc_u32 s99, s99, s15
	s_mov_b32 m0, s70
	ds_read_b128 v[190:193], v228 offset:49152
	ds_read_b128 v[194:197], v228 offset:50176
	ds_read_b128 v[198:201], v228 offset:51200
	ds_read_b128 v[202:205], v228 offset:52224
	ds_read_b128 v[206:209], v228 offset:53248
	ds_read_b128 v[210:213], v228 offset:54272
	ds_read_b128 v[234:237], v228 offset:55296
	ds_read_b128 v[238:241], v228 offset:56320
	global_load_lds_dwordx4 v154, s[98:99]
	s_add_i32 m0, s70, 0x2000
	s_add_u32 s66, s66, 0x20080
	s_addc_u32 s67, s67, 0
	s_add_i32 s70, s90, s77
	global_load_lds_dwordx4 v158, s[98:99]
	s_mov_b32 m0, s70
	s_nop 0
	global_load_lds_dwordx4 v154, s[66:67]
	s_add_i32 m0, s70, 0x2000
	s_nop 0
	global_load_lds_dwordx4 v158, s[66:67]
	s_add_u32 s100, s100, s14
	s_addc_u32 s101, s101, s15
	s_mov_b32 m0, s84
	s_nop 0
	global_load_lds_dwordx4 v152, s[100:101]
	s_mov_b32 m0, s74
	s_nop 0
	global_load_lds_dwordx4 v156, s[100:101]
	s_waitcnt vmcnt(8)
	s_waitcnt lgkmcnt(0)
	s_barrier
	s_waitcnt lgkmcnt(0)
	v_mfma_i32_16x16x64_i8 v[60:63], v[128:131], v[190:193], v[60:63]
	v_mfma_i32_16x16x64_i8 v[56:59], v[136:139], v[190:193], v[56:59]
	v_mfma_i32_16x16x64_i8 v[52:55], v[128:131], v[198:201], v[52:55]
	v_mfma_i32_16x16x64_i8 v[48:51], v[136:139], v[198:201], v[48:51]
	v_mfma_i32_16x16x64_i8 v[44:47], v[128:131], v[206:209], v[44:47]
	v_mfma_i32_16x16x64_i8 v[40:43], v[136:139], v[206:209], v[40:43]
	v_mfma_i32_16x16x64_i8 v[36:39], v[128:131], v[234:237], v[36:39]
	v_mfma_i32_16x16x64_i8 v[32:35], v[136:139], v[234:237], v[32:35]
	v_mfma_i32_16x16x64_i8 v[60:63], v[132:135], v[194:197], v[60:63]
	v_mfma_i32_16x16x64_i8 v[56:59], v[140:143], v[194:197], v[56:59]
	v_mfma_i32_16x16x64_i8 v[52:55], v[132:135], v[202:205], v[52:55]
	v_mfma_i32_16x16x64_i8 v[48:51], v[140:143], v[202:205], v[48:51]
	v_mfma_i32_16x16x64_i8 v[44:47], v[132:135], v[210:213], v[44:47]
	v_mfma_i32_16x16x64_i8 v[40:43], v[140:143], v[210:213], v[40:43]
	v_mfma_i32_16x16x64_i8 v[36:39], v[132:135], v[238:241], v[36:39]
	v_mfma_i32_16x16x64_i8 v[32:35], v[140:143], v[238:241], v[32:35]
	v_mfma_i32_16x16x64_i8 v[28:31], v[174:177], v[190:193], v[28:31]
	v_mfma_i32_16x16x64_i8 v[24:27], v[182:185], v[190:193], v[24:27]
	v_mfma_i32_16x16x64_i8 v[20:23], v[174:177], v[198:201], v[20:23]
	v_mfma_i32_16x16x64_i8 v[16:19], v[182:185], v[198:201], v[16:19]
	v_mfma_i32_16x16x64_i8 v[12:15], v[174:177], v[206:209], v[12:15]
	v_mfma_i32_16x16x64_i8 v[8:11], v[182:185], v[206:209], v[8:11]
	v_mfma_i32_16x16x64_i8 v[4:7], v[174:177], v[234:237], v[4:7]
	v_mfma_i32_16x16x64_i8 v[0:3], v[182:185], v[234:237], v[0:3]
	v_mfma_i32_16x16x64_i8 v[28:31], v[178:181], v[194:197], v[28:31]
	v_mfma_i32_16x16x64_i8 v[24:27], v[186:189], v[194:197], v[24:27]
	v_mfma_i32_16x16x64_i8 v[20:23], v[178:181], v[202:205], v[20:23]
	v_mfma_i32_16x16x64_i8 v[16:19], v[186:189], v[202:205], v[16:19]
	v_mfma_i32_16x16x64_i8 v[12:15], v[178:181], v[210:213], v[12:15]
	v_mfma_i32_16x16x64_i8 v[8:11], v[186:189], v[210:213], v[8:11]
	v_mfma_i32_16x16x64_i8 v[4:7], v[178:181], v[238:241], v[4:7]
	v_mfma_i32_16x16x64_i8 v[0:3], v[186:189], v[238:241], v[0:3]
	s_barrier
	s_add_i32 vcc_lo, vcc_lo, 2
	s_add_u32 s48, s48, 0x100
	s_addc_u32 s49, s49, 0
	s_add_u32 s73, s73, 0x100
	s_addc_u32 s83, s83, 0
	s_cmp_gt_u32 vcc_lo, 5
	s_cbranch_scc0 .LBB0_479
	s_and_b64 vcc, exec, s[56:57]
	s_cbranch_vccz .LBB0_482
	s_barrier

.LBB0_925:
	s_add_u32 s58, s56, 0xfffe0080
	s_addc_u32 s59, s57, -1
	s_add_i32 s83, 0, 0x10000
	s_cmp_eq_u32 s82, 4
	s_cselect_b32 s61, s51, s59
	s_cselect_b32 s60, s79, s58
	s_cselect_b32 s59, s43, s81
	s_cselect_b32 s58, s45, s80
	s_add_i32 s86, 0, 0x14000
	v_add_u32_e32 v150, s83, v182
	v_add_u32_e32 v154, s86, v182
	ds_read_b128 v[138:141], v150
	ds_read_b128 v[142:145], v150 offset:1024
	ds_read_b128 v[146:149], v150 offset:2048
	ds_read_b128 v[150:153], v150 offset:3072
	ds_read_b128 v[166:169], v154
	ds_read_b128 v[190:193], v154 offset:1024
	ds_read_b128 v[194:197], v154 offset:2048
	ds_read_b128 v[198:201], v154 offset:3072
	s_add_i32 m0, s12, 0xc000
	ds_read_b128 v[202:205], v185
	ds_read_b128 v[206:209], v185 offset:1024
	ds_read_b128 v[210:213], v185 offset:2048
	ds_read_b128 v[214:217], v185 offset:3072
	ds_read_b128 v[218:221], v185 offset:4096
	ds_read_b128 v[222:225], v185 offset:5120
	ds_read_b128 v[226:229], v185 offset:6144
	ds_read_b128 v[234:237], v185 offset:7168
	global_load_lds_dwordx4 v134, s[56:57]
	s_add_i32 m0, s12, 0xe000
	s_nop 0
	global_load_lds_dwordx4 v136, s[56:57]
	s_waitcnt vmcnt(8)
	s_waitcnt lgkmcnt(0)
	s_barrier
	s_waitcnt lgkmcnt(0)
	v_mfma_i32_16x16x64_i8 v[126:129], v[138:141], v[202:205], v[126:129]
	v_mfma_i32_16x16x64_i8 v[122:125], v[146:149], v[202:205], v[122:125]
	v_mfma_i32_16x16x64_i8 v[110:113], v[138:141], v[210:213], v[110:113]
	v_mfma_i32_16x16x64_i8 v[106:109], v[146:149], v[210:213], v[106:109]
	v_mfma_i32_16x16x64_i8 v[94:97], v[138:141], v[218:221], v[94:97]
	v_mfma_i32_16x16x64_i8 v[90:93], v[146:149], v[218:221], v[90:93]
	v_mfma_i32_16x16x64_i8 v[78:81], v[138:141], v[226:229], v[78:81]
	v_mfma_i32_16x16x64_i8 v[74:77], v[146:149], v[226:229], v[74:77]
	v_mfma_i32_16x16x64_i8 v[126:129], v[142:145], v[206:209], v[126:129]
	v_mfma_i32_16x16x64_i8 v[122:125], v[150:153], v[206:209], v[122:125]
	v_mfma_i32_16x16x64_i8 v[110:113], v[142:145], v[214:217], v[110:113]
	v_mfma_i32_16x16x64_i8 v[106:109], v[150:153], v[214:217], v[106:109]
	v_mfma_i32_16x16x64_i8 v[94:97], v[142:145], v[222:225], v[94:97]
	v_mfma_i32_16x16x64_i8 v[90:93], v[150:153], v[222:225], v[90:93]
	v_mfma_i32_16x16x64_i8 v[78:81], v[142:145], v[234:237], v[78:81]
	v_mfma_i32_16x16x64_i8 v[74:77], v[150:153], v[234:237], v[74:77]
	v_mfma_i32_16x16x64_i8 v[118:121], v[166:169], v[202:205], v[118:121]
	v_mfma_i32_16x16x64_i8 v[114:117], v[194:197], v[202:205], v[114:117]
	v_mfma_i32_16x16x64_i8 v[102:105], v[166:169], v[210:213], v[102:105]
	v_mfma_i32_16x16x64_i8 v[98:101], v[194:197], v[210:213], v[98:101]
	v_mfma_i32_16x16x64_i8 v[86:89], v[166:169], v[218:221], v[86:89]
	v_mfma_i32_16x16x64_i8 v[82:85], v[194:197], v[218:221], v[82:85]
	v_mfma_i32_16x16x64_i8 v[70:73], v[166:169], v[226:229], v[70:73]
	v_mfma_i32_16x16x64_i8 v[66:69], v[194:197], v[226:229], v[66:69]
	v_mfma_i32_16x16x64_i8 v[118:121], v[190:193], v[206:209], v[118:121]
	v_mfma_i32_16x16x64_i8 v[114:117], v[198:201], v[206:209], v[114:117]
	v_mfma_i32_16x16x64_i8 v[102:105], v[190:193], v[214:217], v[102:105]
	v_mfma_i32_16x16x64_i8 v[98:101], v[198:201], v[214:217], v[98:101]
	v_mfma_i32_16x16x64_i8 v[86:89], v[190:193], v[222:225], v[86:89]
	v_mfma_i32_16x16x64_i8 v[82:85], v[198:201], v[222:225], v[82:85]
	v_mfma_i32_16x16x64_i8 v[70:73], v[190:193], v[234:237], v[70:73]
	v_mfma_i32_16x16x64_i8 v[66:69], v[198:201], v[234:237], v[66:69]
	s_barrier
	s_add_i32 s83, s83, s69
	s_mov_b64 s[98:99], s[58:59]
	s_mov_b32 m0, s83
	ds_read_b128 v[202:205], v185 offset:16384
	ds_read_b128 v[206:209], v185 offset:17408
	ds_read_b128 v[210:213], v185 offset:18432
	ds_read_b128 v[214:217], v185 offset:19456
	ds_read_b128 v[218:221], v185 offset:20480
	ds_read_b128 v[222:225], v185 offset:21504
	ds_read_b128 v[226:229], v185 offset:22528
	ds_read_b128 v[234:237], v185 offset:23552
	global_load_lds_dwordx4 v0, s[58:59]
	s_add_i32 m0, s83, 0x2000
	s_add_u32 s84, s58, 0x20000
	s_addc_u32 s85, s59, 0
	s_add_i32 s83, s86, s69
	global_load_lds_dwordx4 v164, s[58:59]
	s_mov_b32 m0, s83
	s_mov_b64 s[100:101], s[60:61]
	global_load_lds_dwordx4 v0, s[84:85]
	s_add_i32 m0, s83, 0x2000
	s_nop 0
	global_load_lds_dwordx4 v164, s[84:85]
	s_mov_b32 m0, s12
	s_nop 0
	global_load_lds_dwordx4 v160, s[60:61]
	s_mov_b32 m0, s49
	s_nop 0
	global_load_lds_dwordx4 v162, s[60:61]
	s_waitcnt vmcnt(8)
	s_waitcnt lgkmcnt(0)
	s_barrier
	s_waitcnt lgkmcnt(0)
	v_mfma_i32_16x16x64_i8 v[62:65], v[138:141], v[202:205], v[62:65]
	v_mfma_i32_16x16x64_i8 v[58:61], v[146:149], v[202:205], v[58:61]
	v_mfma_i32_16x16x64_i8 v[46:49], v[138:141], v[210:213], v[46:49]
	v_mfma_i32_16x16x64_i8 v[42:45], v[146:149], v[210:213], v[42:45]
	v_mfma_i32_16x16x64_i8 v[30:33], v[138:141], v[218:221], v[30:33]
	v_mfma_i32_16x16x64_i8 v[26:29], v[146:149], v[218:221], v[26:29]
	v_mfma_i32_16x16x64_i8 v[10:13], v[138:141], v[226:229], v[10:13]
	v_mfma_i32_16x16x64_i8 v[2:5], v[146:149], v[226:229], v[2:5]
	v_mfma_i32_16x16x64_i8 v[62:65], v[142:145], v[206:209], v[62:65]
	v_mfma_i32_16x16x64_i8 v[58:61], v[150:153], v[206:209], v[58:61]
	v_mfma_i32_16x16x64_i8 v[46:49], v[142:145], v[214:217], v[46:49]
	v_mfma_i32_16x16x64_i8 v[42:45], v[150:153], v[214:217], v[42:45]
	v_mfma_i32_16x16x64_i8 v[30:33], v[142:145], v[222:225], v[30:33]
	v_mfma_i32_16x16x64_i8 v[26:29], v[150:153], v[222:225], v[26:29]
	v_mfma_i32_16x16x64_i8 v[10:13], v[142:145], v[234:237], v[10:13]
	v_mfma_i32_16x16x64_i8 v[2:5], v[150:153], v[234:237], v[2:5]
	v_mfma_i32_16x16x64_i8 v[54:57], v[166:169], v[202:205], v[54:57]
	v_mfma_i32_16x16x64_i8 v[50:53], v[194:197], v[202:205], v[50:53]
	v_mfma_i32_16x16x64_i8 v[38:41], v[166:169], v[210:213], v[38:41]
	v_mfma_i32_16x16x64_i8 v[34:37], v[194:197], v[210:213], v[34:37]
	v_mfma_i32_16x16x64_i8 v[22:25], v[166:169], v[218:221], v[22:25]
	v_mfma_i32_16x16x64_i8 v[18:21], v[194:197], v[218:221], v[18:21]
	v_mfma_i32_16x16x64_i8 v[14:17], v[166:169], v[226:229], v[14:17]
	v_mfma_i32_16x16x64_i8 v[6:9], v[194:197], v[226:229], v[6:9]
	v_mfma_i32_16x16x64_i8 v[54:57], v[190:193], v[206:209], v[54:57]
	v_mfma_i32_16x16x64_i8 v[50:53], v[198:201], v[206:209], v[50:53]
	v_mfma_i32_16x16x64_i8 v[38:41], v[190:193], v[214:217], v[38:41]
	v_mfma_i32_16x16x64_i8 v[34:37], v[198:201], v[214:217], v[34:37]
	v_mfma_i32_16x16x64_i8 v[22:25], v[190:193], v[222:225], v[22:25]
	v_mfma_i32_16x16x64_i8 v[18:21], v[198:201], v[222:225], v[18:21]
	v_mfma_i32_16x16x64_i8 v[14:17], v[190:193], v[234:237], v[14:17]
	v_mfma_i32_16x16x64_i8 v[6:9], v[198:201], v[234:237], v[6:9]
	s_barrier
	s_add_i32 s83, 0, 0x18000
	s_add_i32 s84, 0, 0x1c000
	v_add_u32_e32 v150, s83, v182
	v_add_u32_e32 v189, s84, v182
	ds_read_b128 v[138:141], v150
	ds_read_b128 v[142:145], v150 offset:1024
	ds_read_b128 v[146:149], v150 offset:2048
	ds_read_b128 v[150:153], v150 offset:3072
	ds_read_b128 v[166:169], v189
	ds_read_b128 v[190:193], v189 offset:1024
	ds_read_b128 v[194:197], v189 offset:2048
	ds_read_b128 v[198:201], v189 offset:3072
	s_add_u32 s60, s60, 0x20000
	s_addc_u32 s61, s61, 0
	s_mov_b32 m0, s70
	ds_read_b128 v[202:205], v185 offset:32768
	ds_read_b128 v[206:209], v185 offset:33792
	ds_read_b128 v[210:213], v185 offset:34816
	ds_read_b128 v[214:217], v185 offset:35840
	ds_read_b128 v[218:221], v185 offset:36864
	ds_read_b128 v[222:225], v185 offset:37888
	ds_read_b128 v[226:229], v185 offset:38912
	ds_read_b128 v[234:237], v185 offset:39936
	global_load_lds_dwordx4 v160, s[60:61]
	s_mov_b32 m0, s71
	s_nop 0
	global_load_lds_dwordx4 v162, s[60:61]
	s_waitcnt vmcnt(8)
	s_waitcnt lgkmcnt(0)
	s_barrier
	s_waitcnt lgkmcnt(0)
	v_mfma_i32_16x16x64_i8 v[126:129], v[138:141], v[202:205], v[126:129]
	v_mfma_i32_16x16x64_i8 v[122:125], v[146:149], v[202:205], v[122:125]
	v_mfma_i32_16x16x64_i8 v[110:113], v[138:141], v[210:213], v[110:113]
	v_mfma_i32_16x16x64_i8 v[106:109], v[146:149], v[210:213], v[106:109]
	v_mfma_i32_16x16x64_i8 v[94:97], v[138:141], v[218:221], v[94:97]
	v_mfma_i32_16x16x64_i8 v[90:93], v[146:149], v[218:221], v[90:93]
	v_mfma_i32_16x16x64_i8 v[78:81], v[138:141], v[226:229], v[78:81]
	v_mfma_i32_16x16x64_i8 v[74:77], v[146:149], v[226:229], v[74:77]
	v_mfma_i32_16x16x64_i8 v[126:129], v[142:145], v[206:209], v[126:129]
	v_mfma_i32_16x16x64_i8 v[122:125], v[150:153], v[206:209], v[122:125]
	v_mfma_i32_16x16x64_i8 v[110:113], v[142:145], v[214:217], v[110:113]
	v_mfma_i32_16x16x64_i8 v[106:109], v[150:153], v[214:217], v[106:109]
	v_mfma_i32_16x16x64_i8 v[94:97], v[142:145], v[222:225], v[94:97]
	v_mfma_i32_16x16x64_i8 v[90:93], v[150:153], v[222:225], v[90:93]
	v_mfma_i32_16x16x64_i8 v[78:81], v[142:145], v[234:237], v[78:81]
	v_mfma_i32_16x16x64_i8 v[74:77], v[150:153], v[234:237], v[74:77]
	v_mfma_i32_16x16x64_i8 v[118:121], v[166:169], v[202:205], v[118:121]
	v_mfma_i32_16x16x64_i8 v[114:117], v[194:197], v[202:205], v[114:117]
	v_mfma_i32_16x16x64_i8 v[102:105], v[166:169], v[210:213], v[102:105]
	v_mfma_i32_16x16x64_i8 v[98:101], v[194:197], v[210:213], v[98:101]
	v_mfma_i32_16x16x64_i8 v[86:89], v[166:169], v[218:221], v[86:89]
	v_mfma_i32_16x16x64_i8 v[82:85], v[194:197], v[218:221], v[82:85]
	v_mfma_i32_16x16x64_i8 v[70:73], v[166:169], v[226:229], v[70:73]
	v_mfma_i32_16x16x64_i8 v[66:69], v[194:197], v[226:229], v[66:69]
	v_mfma_i32_16x16x64_i8 v[118:121], v[190:193], v[206:209], v[118:121]
	v_mfma_i32_16x16x64_i8 v[114:117], v[198:201], v[206:209], v[114:117]
	v_mfma_i32_16x16x64_i8 v[102:105], v[190:193], v[214:217], v[102:105]
	v_mfma_i32_16x16x64_i8 v[98:101], v[198:201], v[214:217], v[98:101]
	v_mfma_i32_16x16x64_i8 v[86:89], v[190:193], v[222:225], v[86:89]
	v_mfma_i32_16x16x64_i8 v[82:85], v[198:201], v[222:225], v[82:85]
	v_mfma_i32_16x16x64_i8 v[70:73], v[190:193], v[234:237], v[70:73]
	v_mfma_i32_16x16x64_i8 v[66:69], v[198:201], v[234:237], v[66:69]
	s_barrier
	s_add_i32 s60, s83, s69
	s_add_u32 s98, s98, s14
	s_addc_u32 s99, s99, s15
	s_mov_b32 m0, s60
	ds_read_b128 v[202:205], v185 offset:49152
	ds_read_b128 v[206:209], v185 offset:50176
	ds_read_b128 v[210:213], v185 offset:51200
	ds_read_b128 v[214:217], v185 offset:52224
	ds_read_b128 v[218:221], v185 offset:53248
	ds_read_b128 v[222:225], v185 offset:54272
	ds_read_b128 v[226:229], v185 offset:55296
	ds_read_b128 v[234:237], v185 offset:56320
	global_load_lds_dwordx4 v0, s[98:99]
	s_add_i32 m0, s60, 0x2000
	s_add_u32 s58, s58, 0x20080
	s_addc_u32 s59, s59, 0
	s_add_i32 s60, s84, s69
	global_load_lds_dwordx4 v164, s[98:99]
	s_mov_b32 m0, s60
	s_nop 0
	global_load_lds_dwordx4 v0, s[58:59]
	s_add_i32 m0, s60, 0x2000
	s_nop 0
	global_load_lds_dwordx4 v164, s[58:59]
	s_add_u32 s100, s100, s14
	s_addc_u32 s101, s101, s15
	s_mov_b32 m0, s72
	s_nop 0
	global_load_lds_dwordx4 v160, s[100:101]
	s_mov_b32 m0, s73
	s_nop 0
	global_load_lds_dwordx4 v162, s[100:101]
	s_waitcnt vmcnt(8)
	s_waitcnt lgkmcnt(0)
	s_barrier
	s_waitcnt lgkmcnt(0)
	v_mfma_i32_16x16x64_i8 v[62:65], v[138:141], v[202:205], v[62:65]
	v_mfma_i32_16x16x64_i8 v[58:61], v[146:149], v[202:205], v[58:61]
	v_mfma_i32_16x16x64_i8 v[46:49], v[138:141], v[210:213], v[46:49]
	v_mfma_i32_16x16x64_i8 v[42:45], v[146:149], v[210:213], v[42:45]
	v_mfma_i32_16x16x64_i8 v[30:33], v[138:141], v[218:221], v[30:33]
	v_mfma_i32_16x16x64_i8 v[26:29], v[146:149], v[218:221], v[26:29]
	v_mfma_i32_16x16x64_i8 v[10:13], v[138:141], v[226:229], v[10:13]
	v_mfma_i32_16x16x64_i8 v[2:5], v[146:149], v[226:229], v[2:5]
	v_mfma_i32_16x16x64_i8 v[62:65], v[142:145], v[206:209], v[62:65]
	v_mfma_i32_16x16x64_i8 v[58:61], v[150:153], v[206:209], v[58:61]
	v_mfma_i32_16x16x64_i8 v[46:49], v[142:145], v[214:217], v[46:49]
	v_mfma_i32_16x16x64_i8 v[42:45], v[150:153], v[214:217], v[42:45]
	v_mfma_i32_16x16x64_i8 v[30:33], v[142:145], v[222:225], v[30:33]
	v_mfma_i32_16x16x64_i8 v[26:29], v[150:153], v[222:225], v[26:29]
	v_mfma_i32_16x16x64_i8 v[10:13], v[142:145], v[234:237], v[10:13]
	v_mfma_i32_16x16x64_i8 v[2:5], v[150:153], v[234:237], v[2:5]
	v_mfma_i32_16x16x64_i8 v[54:57], v[166:169], v[202:205], v[54:57]
	v_mfma_i32_16x16x64_i8 v[50:53], v[194:197], v[202:205], v[50:53]
	v_mfma_i32_16x16x64_i8 v[38:41], v[166:169], v[210:213], v[38:41]
	v_mfma_i32_16x16x64_i8 v[34:37], v[194:197], v[210:213], v[34:37]
	v_mfma_i32_16x16x64_i8 v[22:25], v[166:169], v[218:221], v[22:25]
	v_mfma_i32_16x16x64_i8 v[18:21], v[194:197], v[218:221], v[18:21]
	v_mfma_i32_16x16x64_i8 v[14:17], v[166:169], v[226:229], v[14:17]
	v_mfma_i32_16x16x64_i8 v[6:9], v[194:197], v[226:229], v[6:9]
	v_mfma_i32_16x16x64_i8 v[54:57], v[190:193], v[206:209], v[54:57]
	v_mfma_i32_16x16x64_i8 v[50:53], v[198:201], v[206:209], v[50:53]
	v_mfma_i32_16x16x64_i8 v[38:41], v[190:193], v[214:217], v[38:41]
	v_mfma_i32_16x16x64_i8 v[34:37], v[198:201], v[214:217], v[34:37]
	v_mfma_i32_16x16x64_i8 v[22:25], v[190:193], v[222:225], v[22:25]
	v_mfma_i32_16x16x64_i8 v[18:21], v[198:201], v[222:225], v[18:21]
	v_mfma_i32_16x16x64_i8 v[14:17], v[190:193], v[234:237], v[14:17]
	v_mfma_i32_16x16x64_i8 v[6:9], v[198:201], v[234:237], v[6:9]
	s_barrier
	s_add_i32 s82, s82, 2
	s_add_u32 s56, s56, 0x100
	s_addc_u32 s57, s57, 0
	s_add_u32 s80, s80, 0x100
	s_addc_u32 s81, s81, 0
	s_cmp_gt_u32 s82, 5
	s_cbranch_scc0 .LBB0_925
	s_and_b64 vcc, exec, s[40:41]
	s_cbranch_vccz .LBB0_928
	s_barrier

.LBB0_955:
	s_add_u32 s8, s6, 0xfffe0080
	s_addc_u32 s9, s7, -1
	s_add_i32 s70, 0, 0x10000
	s_cmp_eq_u32 s69, 4
	s_cselect_b32 s55, s43, s9
	s_cselect_b32 s54, s49, s8
	v_add_u32_e32 v0, s70, v188
	s_cselect_b32 s9, s39, s68
	s_cselect_b32 s8, s41, s67
	s_add_i32 s72, 0, 0x14000
	ds_read_b128 v[132:135], v0
	ds_read_b128 v[136:139], v0 offset:1024
	ds_read_b128 v[140:143], v0 offset:2048
	ds_read_b128 v[144:147], v0 offset:3072
	v_add_u32_e32 v0, s72, v188
	ds_read_b128 v[148:151], v0
	ds_read_b128 v[152:155], v0 offset:1024
	ds_read_b128 v[176:179], v0 offset:2048
	ds_read_b128 v[180:183], v0 offset:3072
	s_add_i32 m0, s45, 0xc000
	ds_read_b128 v[198:201], v196
	ds_read_b128 v[202:205], v196 offset:1024
	ds_read_b128 v[206:209], v196 offset:2048
	ds_read_b128 v[210:213], v196 offset:3072
	ds_read_b128 v[214:217], v196 offset:4096
	ds_read_b128 v[218:221], v196 offset:5120
	ds_read_b128 v[222:225], v196 offset:6144
	ds_read_b128 v[226:229], v196 offset:7168
	global_load_lds_dwordx4 v172, s[6:7]
	s_add_i32 m0, s45, 0xe000
	s_nop 0
	global_load_lds_dwordx4 v174, s[6:7]
	s_waitcnt vmcnt(8)
	s_waitcnt lgkmcnt(0)
	s_barrier
	s_waitcnt lgkmcnt(0)
	v_mfma_f32_16x16x32_bf16 v[128:131], v[132:135], v[198:201], v[128:131]
	v_mfma_f32_16x16x32_bf16 v[124:127], v[140:143], v[198:201], v[124:127]
	v_mfma_f32_16x16x32_bf16 v[120:123], v[132:135], v[206:209], v[120:123]
	v_mfma_f32_16x16x32_bf16 v[116:119], v[140:143], v[206:209], v[116:119]
	v_mfma_f32_16x16x32_bf16 v[112:115], v[132:135], v[214:217], v[112:115]
	v_mfma_f32_16x16x32_bf16 v[108:111], v[140:143], v[214:217], v[108:111]
	v_mfma_f32_16x16x32_bf16 v[104:107], v[132:135], v[222:225], v[104:107]
	v_mfma_f32_16x16x32_bf16 v[100:103], v[140:143], v[222:225], v[100:103]
	v_mfma_f32_16x16x32_bf16 v[128:131], v[136:139], v[202:205], v[128:131]
	v_mfma_f32_16x16x32_bf16 v[124:127], v[144:147], v[202:205], v[124:127]
	v_mfma_f32_16x16x32_bf16 v[120:123], v[136:139], v[210:213], v[120:123]
	v_mfma_f32_16x16x32_bf16 v[116:119], v[144:147], v[210:213], v[116:119]
	v_mfma_f32_16x16x32_bf16 v[112:115], v[136:139], v[218:221], v[112:115]
	v_mfma_f32_16x16x32_bf16 v[108:111], v[144:147], v[218:221], v[108:111]
	v_mfma_f32_16x16x32_bf16 v[104:107], v[136:139], v[226:229], v[104:107]
	v_mfma_f32_16x16x32_bf16 v[100:103], v[144:147], v[226:229], v[100:103]
	v_mfma_f32_16x16x32_bf16 v[96:99], v[148:151], v[198:201], v[96:99]
	v_mfma_f32_16x16x32_bf16 v[92:95], v[176:179], v[198:201], v[92:95]
	v_mfma_f32_16x16x32_bf16 v[88:91], v[148:151], v[206:209], v[88:91]
	v_mfma_f32_16x16x32_bf16 v[84:87], v[176:179], v[206:209], v[84:87]
	v_mfma_f32_16x16x32_bf16 v[80:83], v[148:151], v[214:217], v[80:83]
	v_mfma_f32_16x16x32_bf16 v[76:79], v[176:179], v[214:217], v[76:79]
	v_mfma_f32_16x16x32_bf16 v[72:75], v[148:151], v[222:225], v[72:75]
	v_mfma_f32_16x16x32_bf16 v[68:71], v[176:179], v[222:225], v[68:71]
	v_mfma_f32_16x16x32_bf16 v[96:99], v[152:155], v[202:205], v[96:99]
	v_mfma_f32_16x16x32_bf16 v[92:95], v[180:183], v[202:205], v[92:95]
	v_mfma_f32_16x16x32_bf16 v[88:91], v[152:155], v[210:213], v[88:91]
	v_mfma_f32_16x16x32_bf16 v[84:87], v[180:183], v[210:213], v[84:87]
	v_mfma_f32_16x16x32_bf16 v[80:83], v[152:155], v[218:221], v[80:83]
	v_mfma_f32_16x16x32_bf16 v[76:79], v[180:183], v[218:221], v[76:79]
	v_mfma_f32_16x16x32_bf16 v[72:75], v[152:155], v[226:229], v[72:75]
	v_mfma_f32_16x16x32_bf16 v[68:71], v[180:183], v[226:229], v[68:71]
	s_barrier
	s_add_i32 s70, s70, s58
	s_mov_b64 s[98:99], s[8:9]
	s_mov_b32 m0, s70
	ds_read_b128 v[198:201], v196 offset:16384
	ds_read_b128 v[202:205], v196 offset:17408
	ds_read_b128 v[206:209], v196 offset:18432
	ds_read_b128 v[210:213], v196 offset:19456
	ds_read_b128 v[214:217], v196 offset:20480
	ds_read_b128 v[218:221], v196 offset:21504
	ds_read_b128 v[222:225], v196 offset:22528
	ds_read_b128 v[226:229], v196 offset:23552
	global_load_lds_dwordx4 v166, s[8:9]
	s_add_i32 m0, s70, 0x2000
	s_add_u32 s70, s8, 0x20000
	s_addc_u32 s71, s9, 0
	s_add_i32 s72, s72, s58
	global_load_lds_dwordx4 v164, s[8:9]
	s_mov_b32 m0, s72
	s_mov_b64 s[100:101], s[54:55]
	global_load_lds_dwordx4 v166, s[70:71]
	s_add_i32 m0, s72, 0x2000
	s_nop 0
	global_load_lds_dwordx4 v164, s[70:71]
	s_mov_b32 m0, s45
	s_nop 0
	global_load_lds_dwordx4 v160, s[54:55]
	s_mov_b32 m0, s59
	s_nop 0
	global_load_lds_dwordx4 v162, s[54:55]
	s_waitcnt vmcnt(8)
	s_waitcnt lgkmcnt(0)
	s_barrier
	s_waitcnt lgkmcnt(0)
	v_mfma_f32_16x16x32_bf16 v[64:67], v[132:135], v[198:201], v[64:67]
	v_mfma_f32_16x16x32_bf16 v[60:63], v[140:143], v[198:201], v[60:63]
	v_mfma_f32_16x16x32_bf16 v[56:59], v[132:135], v[206:209], v[56:59]
	v_mfma_f32_16x16x32_bf16 v[52:55], v[140:143], v[206:209], v[52:55]
	v_mfma_f32_16x16x32_bf16 v[48:51], v[132:135], v[214:217], v[48:51]
	v_mfma_f32_16x16x32_bf16 v[44:47], v[140:143], v[214:217], v[44:47]
	v_mfma_f32_16x16x32_bf16 v[40:43], v[132:135], v[222:225], v[40:43]
	v_mfma_f32_16x16x32_bf16 v[36:39], v[140:143], v[222:225], v[36:39]
	v_mfma_f32_16x16x32_bf16 v[64:67], v[136:139], v[202:205], v[64:67]
	v_mfma_f32_16x16x32_bf16 v[60:63], v[144:147], v[202:205], v[60:63]
	v_mfma_f32_16x16x32_bf16 v[56:59], v[136:139], v[210:213], v[56:59]
	v_mfma_f32_16x16x32_bf16 v[52:55], v[144:147], v[210:213], v[52:55]
	v_mfma_f32_16x16x32_bf16 v[48:51], v[136:139], v[218:221], v[48:51]
	v_mfma_f32_16x16x32_bf16 v[44:47], v[144:147], v[218:221], v[44:47]
	v_mfma_f32_16x16x32_bf16 v[40:43], v[136:139], v[226:229], v[40:43]
	v_mfma_f32_16x16x32_bf16 v[36:39], v[144:147], v[226:229], v[36:39]
	v_mfma_f32_16x16x32_bf16 v[32:35], v[148:151], v[198:201], v[32:35]
	v_mfma_f32_16x16x32_bf16 v[28:31], v[176:179], v[198:201], v[28:31]
	v_mfma_f32_16x16x32_bf16 v[24:27], v[148:151], v[206:209], v[24:27]
	v_mfma_f32_16x16x32_bf16 v[20:23], v[176:179], v[206:209], v[20:23]
	v_mfma_f32_16x16x32_bf16 v[16:19], v[148:151], v[214:217], v[16:19]
	v_mfma_f32_16x16x32_bf16 v[12:15], v[176:179], v[214:217], v[12:15]
	v_mfma_f32_16x16x32_bf16 v[8:11], v[148:151], v[222:225], v[8:11]
	v_mfma_f32_16x16x32_bf16 v[2:5], v[176:179], v[222:225], v[4:7]
	v_mfma_f32_16x16x32_bf16 v[32:35], v[152:155], v[202:205], v[32:35]
	v_mfma_f32_16x16x32_bf16 v[28:31], v[180:183], v[202:205], v[28:31]
	v_mfma_f32_16x16x32_bf16 v[24:27], v[152:155], v[210:213], v[24:27]
	v_mfma_f32_16x16x32_bf16 v[20:23], v[180:183], v[210:213], v[20:23]
	v_mfma_f32_16x16x32_bf16 v[16:19], v[152:155], v[218:221], v[16:19]
	v_mfma_f32_16x16x32_bf16 v[12:15], v[180:183], v[218:221], v[12:15]
	v_mfma_f32_16x16x32_bf16 v[8:11], v[152:155], v[226:229], v[8:11]
	v_mfma_f32_16x16x32_bf16 v[2:5], v[180:183], v[226:229], v[2:5]
	s_barrier
	s_add_i32 s70, 0, 0x18000
	v_add_u32_e32 v0, s70, v188
	s_add_i32 s71, 0, 0x1c000
	ds_read_b128 v[132:135], v0
	ds_read_b128 v[136:139], v0 offset:1024
	ds_read_b128 v[140:143], v0 offset:2048
	ds_read_b128 v[144:147], v0 offset:3072
	v_add_u32_e32 v0, s71, v188
	ds_read_b128 v[148:151], v0
	ds_read_b128 v[152:155], v0 offset:1024
	ds_read_b128 v[176:179], v0 offset:2048
	ds_read_b128 v[180:183], v0 offset:3072
	s_add_u32 s54, s54, 0x20000
	s_addc_u32 s55, s55, 0
	s_mov_b32 m0, s60
	ds_read_b128 v[198:201], v196 offset:32768
	ds_read_b128 v[202:205], v196 offset:33792
	ds_read_b128 v[206:209], v196 offset:34816
	ds_read_b128 v[210:213], v196 offset:35840
	ds_read_b128 v[214:217], v196 offset:36864
	ds_read_b128 v[218:221], v196 offset:37888
	ds_read_b128 v[222:225], v196 offset:38912
	ds_read_b128 v[226:229], v196 offset:39936
	global_load_lds_dwordx4 v160, s[54:55]
	s_mov_b32 m0, s61
	s_nop 0
	global_load_lds_dwordx4 v162, s[54:55]
	s_waitcnt vmcnt(8)
	s_waitcnt lgkmcnt(0)
	s_barrier
	s_waitcnt lgkmcnt(0)
	v_mfma_f32_16x16x32_bf16 v[128:131], v[132:135], v[198:201], v[128:131]
	v_mfma_f32_16x16x32_bf16 v[124:127], v[140:143], v[198:201], v[124:127]
	v_mfma_f32_16x16x32_bf16 v[120:123], v[132:135], v[206:209], v[120:123]
	v_mfma_f32_16x16x32_bf16 v[116:119], v[140:143], v[206:209], v[116:119]
	v_mfma_f32_16x16x32_bf16 v[112:115], v[132:135], v[214:217], v[112:115]
	v_mfma_f32_16x16x32_bf16 v[108:111], v[140:143], v[214:217], v[108:111]
	v_mfma_f32_16x16x32_bf16 v[104:107], v[132:135], v[222:225], v[104:107]
	v_mfma_f32_16x16x32_bf16 v[100:103], v[140:143], v[222:225], v[100:103]
	v_mfma_f32_16x16x32_bf16 v[128:131], v[136:139], v[202:205], v[128:131]
	v_mfma_f32_16x16x32_bf16 v[124:127], v[144:147], v[202:205], v[124:127]
	v_mfma_f32_16x16x32_bf16 v[120:123], v[136:139], v[210:213], v[120:123]
	v_mfma_f32_16x16x32_bf16 v[116:119], v[144:147], v[210:213], v[116:119]
	v_mfma_f32_16x16x32_bf16 v[112:115], v[136:139], v[218:221], v[112:115]
	v_mfma_f32_16x16x32_bf16 v[108:111], v[144:147], v[218:221], v[108:111]
	v_mfma_f32_16x16x32_bf16 v[104:107], v[136:139], v[226:229], v[104:107]
	v_mfma_f32_16x16x32_bf16 v[100:103], v[144:147], v[226:229], v[100:103]
	v_mfma_f32_16x16x32_bf16 v[96:99], v[148:151], v[198:201], v[96:99]
	v_mfma_f32_16x16x32_bf16 v[92:95], v[176:179], v[198:201], v[92:95]
	v_mfma_f32_16x16x32_bf16 v[88:91], v[148:151], v[206:209], v[88:91]
	v_mfma_f32_16x16x32_bf16 v[84:87], v[176:179], v[206:209], v[84:87]
	v_mfma_f32_16x16x32_bf16 v[80:83], v[148:151], v[214:217], v[80:83]
	v_mfma_f32_16x16x32_bf16 v[76:79], v[176:179], v[214:217], v[76:79]
	v_mfma_f32_16x16x32_bf16 v[72:75], v[148:151], v[222:225], v[72:75]
	v_mfma_f32_16x16x32_bf16 v[68:71], v[176:179], v[222:225], v[68:71]
	v_mfma_f32_16x16x32_bf16 v[96:99], v[152:155], v[202:205], v[96:99]
	v_mfma_f32_16x16x32_bf16 v[92:95], v[180:183], v[202:205], v[92:95]
	v_mfma_f32_16x16x32_bf16 v[88:91], v[152:155], v[210:213], v[88:91]
	v_mfma_f32_16x16x32_bf16 v[84:87], v[180:183], v[210:213], v[84:87]
	v_mfma_f32_16x16x32_bf16 v[80:83], v[152:155], v[218:221], v[80:83]
	v_mfma_f32_16x16x32_bf16 v[76:79], v[180:183], v[218:221], v[76:79]
	v_mfma_f32_16x16x32_bf16 v[72:75], v[152:155], v[226:229], v[72:75]
	v_mfma_f32_16x16x32_bf16 v[68:71], v[180:183], v[226:229], v[68:71]
	s_barrier
	s_add_i32 s54, s70, s58
	s_add_u32 s98, s98, s14
	s_addc_u32 s99, s99, s15
	s_mov_b32 m0, s54
	ds_read_b128 v[198:201], v196 offset:49152
	ds_read_b128 v[202:205], v196 offset:50176
	ds_read_b128 v[206:209], v196 offset:51200
	ds_read_b128 v[210:213], v196 offset:52224
	ds_read_b128 v[214:217], v196 offset:53248
	ds_read_b128 v[218:221], v196 offset:54272
	ds_read_b128 v[222:225], v196 offset:55296
	ds_read_b128 v[226:229], v196 offset:56320
	global_load_lds_dwordx4 v166, s[98:99]
	s_add_i32 m0, s54, 0x2000
	s_add_u32 s8, s8, 0x20080
	s_addc_u32 s9, s9, 0
	s_add_i32 s54, s71, s58
	global_load_lds_dwordx4 v164, s[98:99]
	s_mov_b32 m0, s54
	s_nop 0
	global_load_lds_dwordx4 v166, s[8:9]
	s_add_i32 m0, s54, 0x2000
	s_nop 0
	global_load_lds_dwordx4 v164, s[8:9]
	s_add_u32 s100, s100, s14
	s_addc_u32 s101, s101, s15
	s_mov_b32 m0, s63
	s_nop 0
	global_load_lds_dwordx4 v160, s[100:101]
	s_mov_b32 m0, s64
	s_nop 0
	global_load_lds_dwordx4 v162, s[100:101]
	s_waitcnt vmcnt(8)
	s_waitcnt lgkmcnt(0)
	s_barrier
	s_waitcnt lgkmcnt(0)
	v_mfma_f32_16x16x32_bf16 v[64:67], v[132:135], v[198:201], v[64:67]
	v_mfma_f32_16x16x32_bf16 v[60:63], v[140:143], v[198:201], v[60:63]
	v_mfma_f32_16x16x32_bf16 v[56:59], v[132:135], v[206:209], v[56:59]
	v_mfma_f32_16x16x32_bf16 v[52:55], v[140:143], v[206:209], v[52:55]
	v_mfma_f32_16x16x32_bf16 v[48:51], v[132:135], v[214:217], v[48:51]
	v_mfma_f32_16x16x32_bf16 v[44:47], v[140:143], v[214:217], v[44:47]
	v_mfma_f32_16x16x32_bf16 v[40:43], v[132:135], v[222:225], v[40:43]
	v_mfma_f32_16x16x32_bf16 v[36:39], v[140:143], v[222:225], v[36:39]
	v_mfma_f32_16x16x32_bf16 v[64:67], v[136:139], v[202:205], v[64:67]
	v_mfma_f32_16x16x32_bf16 v[60:63], v[144:147], v[202:205], v[60:63]
	v_mfma_f32_16x16x32_bf16 v[56:59], v[136:139], v[210:213], v[56:59]
	v_mfma_f32_16x16x32_bf16 v[52:55], v[144:147], v[210:213], v[52:55]
	v_mfma_f32_16x16x32_bf16 v[48:51], v[136:139], v[218:221], v[48:51]
	v_mfma_f32_16x16x32_bf16 v[44:47], v[144:147], v[218:221], v[44:47]
	v_mfma_f32_16x16x32_bf16 v[40:43], v[136:139], v[226:229], v[40:43]
	v_mfma_f32_16x16x32_bf16 v[36:39], v[144:147], v[226:229], v[36:39]
	v_mfma_f32_16x16x32_bf16 v[32:35], v[148:151], v[198:201], v[32:35]
	v_mfma_f32_16x16x32_bf16 v[28:31], v[176:179], v[198:201], v[28:31]
	v_mfma_f32_16x16x32_bf16 v[24:27], v[148:151], v[206:209], v[24:27]
	v_mfma_f32_16x16x32_bf16 v[20:23], v[176:179], v[206:209], v[20:23]
	v_mfma_f32_16x16x32_bf16 v[16:19], v[148:151], v[214:217], v[16:19]
	v_mfma_f32_16x16x32_bf16 v[12:15], v[176:179], v[214:217], v[12:15]
	v_mfma_f32_16x16x32_bf16 v[6:9], v[148:151], v[222:225], v[8:11]
	v_mfma_f32_16x16x32_bf16 v[2:5], v[176:179], v[222:225], v[2:5]
	v_mfma_f32_16x16x32_bf16 v[32:35], v[152:155], v[202:205], v[32:35]
	v_mfma_f32_16x16x32_bf16 v[28:31], v[180:183], v[202:205], v[28:31]
	v_mfma_f32_16x16x32_bf16 v[24:27], v[152:155], v[210:213], v[24:27]
	v_mfma_f32_16x16x32_bf16 v[20:23], v[180:183], v[210:213], v[20:23]
	v_mfma_f32_16x16x32_bf16 v[16:19], v[152:155], v[218:221], v[16:19]
	v_mfma_f32_16x16x32_bf16 v[12:15], v[180:183], v[218:221], v[12:15]
	v_mfma_f32_16x16x32_bf16 v[8:11], v[152:155], v[226:229], v[6:9]
	v_mfma_f32_16x16x32_bf16 v[4:7], v[180:183], v[226:229], v[2:5]
	s_barrier
	s_add_i32 s69, s69, 2
	s_add_u32 s6, s6, 0x100
	s_addc_u32 s7, s7, 0
	s_add_u32 s67, s67, 0x100
	s_addc_u32 s68, s68, 0
	s_cmp_gt_u32 s69, 5
	s_cbranch_scc0 .LBB0_955
	s_and_b64 vcc, exec, s[34:35]
	s_cbranch_vccz .LBB0_958
	s_barrier

.LBB0_1167:
	s_add_u32 s60, s48, 0xfffc0080
	s_addc_u32 s61, s49, -1
	s_add_i32 s66, 0, 0x10000
	s_cmp_eq_u32 s65, 12
	s_cselect_b32 s63, s14, s61
	s_cselect_b32 s62, s51, s60
	v_add_u32_e32 v0, s66, v169
	s_cselect_b32 s61, s45, s64
	s_cselect_b32 s60, s57, s59
	s_add_i32 s68, 0, 0x14000
	ds_read_b128 v[148:151], v0
	ds_read_b128 v[152:155], v0 offset:1024
	ds_read_b128 v[156:159], v0 offset:2048
	ds_read_b128 v[190:193], v0 offset:3072
	v_add_u32_e32 v0, s68, v169
	ds_read_b128 v[194:197], v0
	ds_read_b128 v[198:201], v0 offset:1024
	ds_read_b128 v[202:205], v0 offset:2048
	ds_read_b128 v[206:209], v0 offset:3072
	s_add_i32 m0, s79, 0xc000
	ds_read_b128 v[210:213], v188
	ds_read_b128 v[214:217], v188 offset:1024
	ds_read_b128 v[218:221], v188 offset:2048
	ds_read_b128 v[222:225], v188 offset:3072
	ds_read_b128 v[226:229], v188 offset:4096
	ds_read_b128 v[234:237], v188 offset:5120
	ds_read_b128 v[238:241], v188 offset:6144
	ds_read_b128 v[242:245], v188 offset:7168
	global_load_lds_dwordx4 v144, s[48:49]
	s_add_i32 m0, s79, 0xe000
	s_nop 0
	global_load_lds_dwordx4 v146, s[48:49]
	s_waitcnt vmcnt(8)
	s_waitcnt lgkmcnt(0)
	s_barrier
	s_waitcnt lgkmcnt(0)
	v_mfma_f32_16x16x32_bf16 v[126:129], v[148:151], v[210:213], v[126:129]
	v_mfma_f32_16x16x32_bf16 v[122:125], v[156:159], v[210:213], v[122:125]
	v_mfma_f32_16x16x32_bf16 v[110:113], v[148:151], v[218:221], v[110:113]
	v_mfma_f32_16x16x32_bf16 v[106:109], v[156:159], v[218:221], v[106:109]
	v_mfma_f32_16x16x32_bf16 v[94:97], v[148:151], v[226:229], v[94:97]
	v_mfma_f32_16x16x32_bf16 v[90:93], v[156:159], v[226:229], v[90:93]
	v_mfma_f32_16x16x32_bf16 v[78:81], v[148:151], v[238:241], v[78:81]
	v_mfma_f32_16x16x32_bf16 v[74:77], v[156:159], v[238:241], v[74:77]
	v_mfma_f32_16x16x32_bf16 v[126:129], v[152:155], v[214:217], v[126:129]
	v_mfma_f32_16x16x32_bf16 v[122:125], v[190:193], v[214:217], v[122:125]
	v_mfma_f32_16x16x32_bf16 v[110:113], v[152:155], v[222:225], v[110:113]
	v_mfma_f32_16x16x32_bf16 v[106:109], v[190:193], v[222:225], v[106:109]
	v_mfma_f32_16x16x32_bf16 v[94:97], v[152:155], v[234:237], v[94:97]
	v_mfma_f32_16x16x32_bf16 v[90:93], v[190:193], v[234:237], v[90:93]
	v_mfma_f32_16x16x32_bf16 v[78:81], v[152:155], v[242:245], v[78:81]
	v_mfma_f32_16x16x32_bf16 v[74:77], v[190:193], v[242:245], v[74:77]
	v_mfma_f32_16x16x32_bf16 v[118:121], v[194:197], v[210:213], v[118:121]
	v_mfma_f32_16x16x32_bf16 v[114:117], v[202:205], v[210:213], v[114:117]
	v_mfma_f32_16x16x32_bf16 v[102:105], v[194:197], v[218:221], v[102:105]
	v_mfma_f32_16x16x32_bf16 v[98:101], v[202:205], v[218:221], v[98:101]
	v_mfma_f32_16x16x32_bf16 v[86:89], v[194:197], v[226:229], v[86:89]
	v_mfma_f32_16x16x32_bf16 v[82:85], v[202:205], v[226:229], v[82:85]
	v_mfma_f32_16x16x32_bf16 v[70:73], v[194:197], v[238:241], v[70:73]
	v_mfma_f32_16x16x32_bf16 v[66:69], v[202:205], v[238:241], v[66:69]
	v_mfma_f32_16x16x32_bf16 v[118:121], v[198:201], v[214:217], v[118:121]
	v_mfma_f32_16x16x32_bf16 v[114:117], v[206:209], v[214:217], v[114:117]
	v_mfma_f32_16x16x32_bf16 v[102:105], v[198:201], v[222:225], v[102:105]
	v_mfma_f32_16x16x32_bf16 v[98:101], v[206:209], v[222:225], v[98:101]
	v_mfma_f32_16x16x32_bf16 v[86:89], v[198:201], v[234:237], v[86:89]
	v_mfma_f32_16x16x32_bf16 v[82:85], v[206:209], v[234:237], v[82:85]
	v_mfma_f32_16x16x32_bf16 v[70:73], v[198:201], v[242:245], v[70:73]
	v_mfma_f32_16x16x32_bf16 v[66:69], v[206:209], v[242:245], v[66:69]
	s_barrier
	s_add_i32 s66, s66, s78
	s_mov_b64 s[98:99], s[60:61]
	s_mov_b32 m0, s66
	ds_read_b128 v[210:213], v188 offset:16384
	ds_read_b128 v[214:217], v188 offset:17408
	ds_read_b128 v[218:221], v188 offset:18432
	ds_read_b128 v[222:225], v188 offset:19456
	ds_read_b128 v[226:229], v188 offset:20480
	ds_read_b128 v[234:237], v188 offset:21504
	ds_read_b128 v[238:241], v188 offset:22528
	ds_read_b128 v[242:245], v188 offset:23552
	global_load_lds_dwordx4 v136, s[60:61]
	s_add_i32 m0, s66, 0x2000
	s_add_u32 s66, s60, 0x40000
	s_addc_u32 s67, s61, 0
	s_add_i32 s68, s68, s78
	global_load_lds_dwordx4 v140, s[60:61]
	s_mov_b32 m0, s68
	s_mov_b64 s[100:101], s[62:63]
	global_load_lds_dwordx4 v136, s[66:67]
	s_add_i32 m0, s68, 0x2000
	s_nop 0
	global_load_lds_dwordx4 v140, s[66:67]
	s_mov_b32 m0, s79
	s_nop 0
	global_load_lds_dwordx4 v134, s[62:63]
	s_mov_b32 m0, s80
	s_nop 0
	global_load_lds_dwordx4 v138, s[62:63]
	s_waitcnt vmcnt(8)
	s_waitcnt lgkmcnt(0)
	s_barrier
	s_waitcnt lgkmcnt(0)
	v_mfma_f32_16x16x32_bf16 v[62:65], v[148:151], v[210:213], v[62:65]
	v_mfma_f32_16x16x32_bf16 v[58:61], v[156:159], v[210:213], v[58:61]
	v_mfma_f32_16x16x32_bf16 v[46:49], v[148:151], v[218:221], v[46:49]
	v_mfma_f32_16x16x32_bf16 v[42:45], v[156:159], v[218:221], v[42:45]
	v_mfma_f32_16x16x32_bf16 v[30:33], v[148:151], v[226:229], v[30:33]
	v_mfma_f32_16x16x32_bf16 v[26:29], v[156:159], v[226:229], v[26:29]
	v_mfma_f32_16x16x32_bf16 v[14:17], v[148:151], v[238:241], v[14:17]
	v_mfma_f32_16x16x32_bf16 v[10:13], v[156:159], v[238:241], v[10:13]
	v_mfma_f32_16x16x32_bf16 v[62:65], v[152:155], v[214:217], v[62:65]
	v_mfma_f32_16x16x32_bf16 v[58:61], v[190:193], v[214:217], v[58:61]
	v_mfma_f32_16x16x32_bf16 v[46:49], v[152:155], v[222:225], v[46:49]
	v_mfma_f32_16x16x32_bf16 v[42:45], v[190:193], v[222:225], v[42:45]
	v_mfma_f32_16x16x32_bf16 v[30:33], v[152:155], v[234:237], v[30:33]
	v_mfma_f32_16x16x32_bf16 v[26:29], v[190:193], v[234:237], v[26:29]
	v_mfma_f32_16x16x32_bf16 v[14:17], v[152:155], v[242:245], v[14:17]
	v_mfma_f32_16x16x32_bf16 v[10:13], v[190:193], v[242:245], v[10:13]
	v_mfma_f32_16x16x32_bf16 v[54:57], v[194:197], v[210:213], v[54:57]
	v_mfma_f32_16x16x32_bf16 v[50:53], v[202:205], v[210:213], v[50:53]
	v_mfma_f32_16x16x32_bf16 v[38:41], v[194:197], v[218:221], v[38:41]
	v_mfma_f32_16x16x32_bf16 v[34:37], v[202:205], v[218:221], v[34:37]
	v_mfma_f32_16x16x32_bf16 v[22:25], v[194:197], v[226:229], v[22:25]
	v_mfma_f32_16x16x32_bf16 v[18:21], v[202:205], v[226:229], v[18:21]
	v_mfma_f32_16x16x32_bf16 v[6:9], v[194:197], v[238:241], v[6:9]
	v_mfma_f32_16x16x32_bf16 v[2:5], v[202:205], v[238:241], v[2:5]
	v_mfma_f32_16x16x32_bf16 v[54:57], v[198:201], v[214:217], v[54:57]
	v_mfma_f32_16x16x32_bf16 v[50:53], v[206:209], v[214:217], v[50:53]
	v_mfma_f32_16x16x32_bf16 v[38:41], v[198:201], v[222:225], v[38:41]
	v_mfma_f32_16x16x32_bf16 v[34:37], v[206:209], v[222:225], v[34:37]
	v_mfma_f32_16x16x32_bf16 v[22:25], v[198:201], v[234:237], v[22:25]
	v_mfma_f32_16x16x32_bf16 v[18:21], v[206:209], v[234:237], v[18:21]
	v_mfma_f32_16x16x32_bf16 v[6:9], v[198:201], v[242:245], v[6:9]
	v_mfma_f32_16x16x32_bf16 v[2:5], v[206:209], v[242:245], v[2:5]
	s_barrier
	s_add_i32 s66, 0, 0x18000
	v_add_u32_e32 v0, s66, v169
	s_add_i32 s67, 0, 0x1c000
	ds_read_b128 v[148:151], v0
	ds_read_b128 v[152:155], v0 offset:1024
	ds_read_b128 v[156:159], v0 offset:2048
	ds_read_b128 v[190:193], v0 offset:3072
	v_add_u32_e32 v0, s67, v169
	ds_read_b128 v[194:197], v0
	ds_read_b128 v[198:201], v0 offset:1024
	ds_read_b128 v[202:205], v0 offset:2048
	ds_read_b128 v[206:209], v0 offset:3072
	s_add_u32 s62, s62, 0x40000
	s_addc_u32 s63, s63, 0
	s_mov_b32 m0, s81
	ds_read_b128 v[210:213], v188 offset:32768
	ds_read_b128 v[214:217], v188 offset:33792
	ds_read_b128 v[218:221], v188 offset:34816
	ds_read_b128 v[222:225], v188 offset:35840
	ds_read_b128 v[226:229], v188 offset:36864
	ds_read_b128 v[234:237], v188 offset:37888
	ds_read_b128 v[238:241], v188 offset:38912
	ds_read_b128 v[242:245], v188 offset:39936
	global_load_lds_dwordx4 v134, s[62:63]
	s_mov_b32 m0, s82
	s_nop 0
	global_load_lds_dwordx4 v138, s[62:63]
	s_waitcnt vmcnt(8)
	s_waitcnt lgkmcnt(0)
	s_barrier
	s_waitcnt lgkmcnt(0)
	v_mfma_f32_16x16x32_bf16 v[126:129], v[148:151], v[210:213], v[126:129]
	v_mfma_f32_16x16x32_bf16 v[122:125], v[156:159], v[210:213], v[122:125]
	v_mfma_f32_16x16x32_bf16 v[110:113], v[148:151], v[218:221], v[110:113]
	v_mfma_f32_16x16x32_bf16 v[106:109], v[156:159], v[218:221], v[106:109]
	v_mfma_f32_16x16x32_bf16 v[94:97], v[148:151], v[226:229], v[94:97]
	v_mfma_f32_16x16x32_bf16 v[90:93], v[156:159], v[226:229], v[90:93]
	v_mfma_f32_16x16x32_bf16 v[78:81], v[148:151], v[238:241], v[78:81]
	v_mfma_f32_16x16x32_bf16 v[74:77], v[156:159], v[238:241], v[74:77]
	v_mfma_f32_16x16x32_bf16 v[126:129], v[152:155], v[214:217], v[126:129]
	v_mfma_f32_16x16x32_bf16 v[122:125], v[190:193], v[214:217], v[122:125]
	v_mfma_f32_16x16x32_bf16 v[110:113], v[152:155], v[222:225], v[110:113]
	v_mfma_f32_16x16x32_bf16 v[106:109], v[190:193], v[222:225], v[106:109]
	v_mfma_f32_16x16x32_bf16 v[94:97], v[152:155], v[234:237], v[94:97]
	v_mfma_f32_16x16x32_bf16 v[90:93], v[190:193], v[234:237], v[90:93]
	v_mfma_f32_16x16x32_bf16 v[78:81], v[152:155], v[242:245], v[78:81]
	v_mfma_f32_16x16x32_bf16 v[74:77], v[190:193], v[242:245], v[74:77]
	v_mfma_f32_16x16x32_bf16 v[118:121], v[194:197], v[210:213], v[118:121]
	v_mfma_f32_16x16x32_bf16 v[114:117], v[202:205], v[210:213], v[114:117]
	v_mfma_f32_16x16x32_bf16 v[102:105], v[194:197], v[218:221], v[102:105]
	v_mfma_f32_16x16x32_bf16 v[98:101], v[202:205], v[218:221], v[98:101]
	v_mfma_f32_16x16x32_bf16 v[86:89], v[194:197], v[226:229], v[86:89]
	v_mfma_f32_16x16x32_bf16 v[82:85], v[202:205], v[226:229], v[82:85]
	v_mfma_f32_16x16x32_bf16 v[70:73], v[194:197], v[238:241], v[70:73]
	v_mfma_f32_16x16x32_bf16 v[66:69], v[202:205], v[238:241], v[66:69]
	v_mfma_f32_16x16x32_bf16 v[118:121], v[198:201], v[214:217], v[118:121]
	v_mfma_f32_16x16x32_bf16 v[114:117], v[206:209], v[214:217], v[114:117]
	v_mfma_f32_16x16x32_bf16 v[102:105], v[198:201], v[222:225], v[102:105]
	v_mfma_f32_16x16x32_bf16 v[98:101], v[206:209], v[222:225], v[98:101]
	v_mfma_f32_16x16x32_bf16 v[86:89], v[198:201], v[234:237], v[86:89]
	v_mfma_f32_16x16x32_bf16 v[82:85], v[206:209], v[234:237], v[82:85]
	v_mfma_f32_16x16x32_bf16 v[70:73], v[198:201], v[242:245], v[70:73]
	v_mfma_f32_16x16x32_bf16 v[66:69], v[206:209], v[242:245], v[66:69]
	s_barrier
	s_add_i32 s62, s66, s78
	s_add_u32 s98, s98, s16
	s_addc_u32 s99, s99, s17
	s_mov_b32 m0, s62
	ds_read_b128 v[210:213], v188 offset:49152
	ds_read_b128 v[214:217], v188 offset:50176
	ds_read_b128 v[218:221], v188 offset:51200
	ds_read_b128 v[222:225], v188 offset:52224
	ds_read_b128 v[226:229], v188 offset:53248
	ds_read_b128 v[234:237], v188 offset:54272
	ds_read_b128 v[238:241], v188 offset:55296
	ds_read_b128 v[242:245], v188 offset:56320
	global_load_lds_dwordx4 v136, s[98:99]
	s_add_i32 m0, s62, 0x2000
	s_add_u32 s60, s60, 0x40080
	s_addc_u32 s61, s61, 0
	s_add_i32 s62, s67, s78
	global_load_lds_dwordx4 v140, s[98:99]
	s_mov_b32 m0, s62
	s_nop 0
	global_load_lds_dwordx4 v136, s[60:61]
	s_add_i32 m0, s62, 0x2000
	s_nop 0
	global_load_lds_dwordx4 v140, s[60:61]
	s_add_u32 s100, s100, s16
	s_addc_u32 s101, s101, s17
	s_mov_b32 m0, s85
	s_nop 0
	global_load_lds_dwordx4 v134, s[100:101]
	s_mov_b32 m0, s86
	s_nop 0
	global_load_lds_dwordx4 v138, s[100:101]
	s_waitcnt vmcnt(8)
	s_waitcnt lgkmcnt(0)
	s_barrier
	s_waitcnt lgkmcnt(0)
	v_mfma_f32_16x16x32_bf16 v[62:65], v[148:151], v[210:213], v[62:65]
	v_mfma_f32_16x16x32_bf16 v[58:61], v[156:159], v[210:213], v[58:61]
	v_mfma_f32_16x16x32_bf16 v[46:49], v[148:151], v[218:221], v[46:49]
	v_mfma_f32_16x16x32_bf16 v[42:45], v[156:159], v[218:221], v[42:45]
	v_mfma_f32_16x16x32_bf16 v[30:33], v[148:151], v[226:229], v[30:33]
	v_mfma_f32_16x16x32_bf16 v[26:29], v[156:159], v[226:229], v[26:29]
	v_mfma_f32_16x16x32_bf16 v[14:17], v[148:151], v[238:241], v[14:17]
	v_mfma_f32_16x16x32_bf16 v[10:13], v[156:159], v[238:241], v[10:13]
	v_mfma_f32_16x16x32_bf16 v[62:65], v[152:155], v[214:217], v[62:65]
	v_mfma_f32_16x16x32_bf16 v[58:61], v[190:193], v[214:217], v[58:61]
	v_mfma_f32_16x16x32_bf16 v[46:49], v[152:155], v[222:225], v[46:49]
	v_mfma_f32_16x16x32_bf16 v[42:45], v[190:193], v[222:225], v[42:45]
	v_mfma_f32_16x16x32_bf16 v[30:33], v[152:155], v[234:237], v[30:33]
	v_mfma_f32_16x16x32_bf16 v[26:29], v[190:193], v[234:237], v[26:29]
	v_mfma_f32_16x16x32_bf16 v[14:17], v[152:155], v[242:245], v[14:17]
	v_mfma_f32_16x16x32_bf16 v[10:13], v[190:193], v[242:245], v[10:13]
	v_mfma_f32_16x16x32_bf16 v[54:57], v[194:197], v[210:213], v[54:57]
	v_mfma_f32_16x16x32_bf16 v[50:53], v[202:205], v[210:213], v[50:53]
	v_mfma_f32_16x16x32_bf16 v[38:41], v[194:197], v[218:221], v[38:41]
	v_mfma_f32_16x16x32_bf16 v[34:37], v[202:205], v[218:221], v[34:37]
	v_mfma_f32_16x16x32_bf16 v[22:25], v[194:197], v[226:229], v[22:25]
	v_mfma_f32_16x16x32_bf16 v[18:21], v[202:205], v[226:229], v[18:21]
	v_mfma_f32_16x16x32_bf16 v[6:9], v[194:197], v[238:241], v[6:9]
	v_mfma_f32_16x16x32_bf16 v[2:5], v[202:205], v[238:241], v[2:5]
	v_mfma_f32_16x16x32_bf16 v[54:57], v[198:201], v[214:217], v[54:57]
	v_mfma_f32_16x16x32_bf16 v[50:53], v[206:209], v[214:217], v[50:53]
	v_mfma_f32_16x16x32_bf16 v[38:41], v[198:201], v[222:225], v[38:41]
	v_mfma_f32_16x16x32_bf16 v[34:37], v[206:209], v[222:225], v[34:37]
	v_mfma_f32_16x16x32_bf16 v[22:25], v[198:201], v[234:237], v[22:25]
	v_mfma_f32_16x16x32_bf16 v[18:21], v[206:209], v[234:237], v[18:21]
	v_mfma_f32_16x16x32_bf16 v[6:9], v[198:201], v[242:245], v[6:9]
	v_mfma_f32_16x16x32_bf16 v[2:5], v[206:209], v[242:245], v[2:5]
	s_barrier
	s_add_i32 s65, s65, 2
	s_add_u32 s48, s48, 0x100
	s_addc_u32 s49, s49, 0
	s_add_u32 s59, s59, 0x100
	s_addc_u32 s64, s64, 0
	s_cmp_gt_u32 s65, 13
	s_cbranch_scc0 .LBB0_1167
	s_and_b64 vcc, exec, s[38:39]
	s_cbranch_vccz .LBB0_1171
	s_barrier
	s_andn2_b64 vcc, exec, s[20:21]
	s_cbranch_vccz .LBB0_1172

.LBB0_1478:
	s_add_i32 m0, s55, 0xc000
	s_and_b64 vcc, exec, s[8:9]
	global_load_lds_dwordx4 v210, s[60:61]
	s_add_i32 m0, s55, 0xe000
	s_nop 0
	global_load_lds_dwordx4 v212, s[60:61]
	s_waitcnt vmcnt(8)
	s_waitcnt lgkmcnt(0)
	s_barrier
	s_cbranch_vccnz .LBB0_1480
	s_waitcnt lgkmcnt(0)
	v_mfma_i32_16x16x64_i8 v[176:179], v[180:183], v[4:7], v[176:179]
	v_mfma_i32_16x16x64_i8 v[168:171], v[188:191], v[4:7], v[168:171]
	v_mfma_i32_16x16x64_i8 v[160:163], v[180:183], v[12:15], v[160:163]
	v_mfma_i32_16x16x64_i8 v[152:155], v[188:191], v[12:15], v[152:155]
	v_mfma_i32_16x16x64_i8 v[144:147], v[180:183], v[20:23], v[144:147]
	v_mfma_i32_16x16x64_i8 v[136:139], v[188:191], v[20:23], v[136:139]
	v_mfma_i32_16x16x64_i8 v[120:123], v[180:183], v[28:31], v[120:123]
	v_mfma_i32_16x16x64_i8 v[104:107], v[188:191], v[28:31], v[104:107]
	v_mfma_i32_16x16x64_i8 v[176:179], v[184:187], v[8:11], v[176:179]
	v_mfma_i32_16x16x64_i8 v[168:171], v[192:195], v[8:11], v[168:171]
	v_mfma_i32_16x16x64_i8 v[160:163], v[184:187], v[16:19], v[160:163]
	v_mfma_i32_16x16x64_i8 v[152:155], v[192:195], v[16:19], v[152:155]
	v_mfma_i32_16x16x64_i8 v[144:147], v[184:187], v[24:27], v[144:147]
	v_mfma_i32_16x16x64_i8 v[136:139], v[192:195], v[24:27], v[136:139]
	v_mfma_i32_16x16x64_i8 v[120:123], v[184:187], v[32:35], v[120:123]
	v_mfma_i32_16x16x64_i8 v[104:107], v[192:195], v[32:35], v[104:107]
	v_mfma_i32_16x16x64_i8 v[172:175], v[108:111], v[4:7], v[172:175]
	v_mfma_i32_16x16x64_i8 v[164:167], v[124:127], v[4:7], v[164:167]
	v_mfma_i32_16x16x64_i8 v[156:159], v[108:111], v[12:15], v[156:159]
	v_mfma_i32_16x16x64_i8 v[148:151], v[124:127], v[12:15], v[148:151]
	v_mfma_i32_16x16x64_i8 v[140:143], v[108:111], v[20:23], v[140:143]
	v_mfma_i32_16x16x64_i8 v[132:135], v[124:127], v[20:23], v[132:135]
	v_mfma_i32_16x16x64_i8 v[116:119], v[108:111], v[28:31], v[116:119]
	v_mfma_i32_16x16x64_i8 v[100:103], v[124:127], v[28:31], v[100:103]
	v_mfma_i32_16x16x64_i8 v[172:175], v[112:115], v[8:11], v[172:175]
	v_mfma_i32_16x16x64_i8 v[164:167], v[128:131], v[8:11], v[164:167]
	v_mfma_i32_16x16x64_i8 v[156:159], v[112:115], v[16:19], v[156:159]
	v_mfma_i32_16x16x64_i8 v[148:151], v[128:131], v[16:19], v[148:151]
	v_mfma_i32_16x16x64_i8 v[140:143], v[112:115], v[24:27], v[140:143]
	v_mfma_i32_16x16x64_i8 v[132:135], v[128:131], v[24:27], v[132:135]
	v_mfma_i32_16x16x64_i8 v[116:119], v[112:115], v[32:35], v[116:119]
	v_mfma_i32_16x16x64_i8 v[100:103], v[128:131], v[32:35], v[100:103]

.LBB0_1482:
	s_add_u32 s62, s60, 0xfffe0080
	s_addc_u32 s63, s61, -1
	s_cmp_eq_u32 s97, 4
	s_cselect_b32 s65, s43, s63
	s_cselect_b32 s64, s93, s62
	s_cselect_b32 s63, s41, s96
	s_cselect_b32 s62, s94, s95
	s_mov_b32 m0, s57
	s_mov_b64 s[98:99], s[62:63]
	s_add_u32 vcc_lo, s62, 0x20000
	global_load_lds_dwordx4 v200, s[62:63]
	s_mov_b32 m0, s73
	s_addc_u32 vcc_hi, s63, 0
	global_load_lds_dwordx4 v204, s[62:63]
	v_lshl_add_u64 v[216:217], vcc, 0, v[200:201]
	s_mov_b32 m0, s74
	s_mov_b64 s[100:101], s[64:65]
	global_load_lds_dwordx4 v[216:217], off
	v_lshl_add_u64 v[216:217], vcc, 0, v[204:205]
	s_mov_b32 m0, s75
	s_and_b64 vcc, exec, s[6:7]
	global_load_lds_dwordx4 v[216:217], off
	s_mov_b32 m0, s55
	s_nop 0
	global_load_lds_dwordx4 v198, s[64:65]
	s_mov_b32 m0, s76
	s_nop 0
	global_load_lds_dwordx4 v202, s[64:65]
	s_waitcnt vmcnt(8)
	s_waitcnt lgkmcnt(0)
	s_barrier
	s_cbranch_vccnz .LBB0_1484
	s_waitcnt lgkmcnt(0)
	v_mfma_i32_16x16x64_i8 v[96:99], v[180:183], v[4:7], v[96:99]
	v_mfma_i32_16x16x64_i8 v[88:91], v[188:191], v[4:7], v[88:91]
	v_mfma_i32_16x16x64_i8 v[80:83], v[180:183], v[12:15], v[80:83]
	v_mfma_i32_16x16x64_i8 v[72:75], v[188:191], v[12:15], v[72:75]
	v_mfma_i32_16x16x64_i8 v[64:67], v[180:183], v[20:23], v[64:67]
	v_mfma_i32_16x16x64_i8 v[56:59], v[188:191], v[20:23], v[56:59]
	v_mfma_i32_16x16x64_i8 v[48:51], v[180:183], v[28:31], v[48:51]
	v_mfma_i32_16x16x64_i8 v[40:43], v[188:191], v[28:31], v[40:43]
	v_mfma_i32_16x16x64_i8 v[96:99], v[184:187], v[8:11], v[96:99]
	v_mfma_i32_16x16x64_i8 v[88:91], v[192:195], v[8:11], v[88:91]
	v_mfma_i32_16x16x64_i8 v[80:83], v[184:187], v[16:19], v[80:83]
	v_mfma_i32_16x16x64_i8 v[72:75], v[192:195], v[16:19], v[72:75]
	v_mfma_i32_16x16x64_i8 v[64:67], v[184:187], v[24:27], v[64:67]
	v_mfma_i32_16x16x64_i8 v[56:59], v[192:195], v[24:27], v[56:59]
	v_mfma_i32_16x16x64_i8 v[48:51], v[184:187], v[32:35], v[48:51]
	v_mfma_i32_16x16x64_i8 v[40:43], v[192:195], v[32:35], v[40:43]
	v_mfma_i32_16x16x64_i8 v[92:95], v[108:111], v[4:7], v[92:95]
	v_mfma_i32_16x16x64_i8 v[84:87], v[124:127], v[4:7], v[84:87]
	v_mfma_i32_16x16x64_i8 v[76:79], v[108:111], v[12:15], v[76:79]
	v_mfma_i32_16x16x64_i8 v[68:71], v[124:127], v[12:15], v[68:71]
	v_mfma_i32_16x16x64_i8 v[60:63], v[108:111], v[20:23], v[60:63]
	v_mfma_i32_16x16x64_i8 v[52:55], v[124:127], v[20:23], v[52:55]
	v_mfma_i32_16x16x64_i8 v[44:47], v[108:111], v[28:31], v[44:47]
	v_mfma_i32_16x16x64_i8 v[36:39], v[124:127], v[28:31], v[36:39]
	v_mfma_i32_16x16x64_i8 v[92:95], v[112:115], v[8:11], v[92:95]
	v_mfma_i32_16x16x64_i8 v[84:87], v[128:131], v[8:11], v[84:87]
	v_mfma_i32_16x16x64_i8 v[76:79], v[112:115], v[16:19], v[76:79]
	v_mfma_i32_16x16x64_i8 v[68:71], v[128:131], v[16:19], v[68:71]
	v_mfma_i32_16x16x64_i8 v[60:63], v[112:115], v[24:27], v[60:63]
	v_mfma_i32_16x16x64_i8 v[52:55], v[128:131], v[24:27], v[52:55]
	v_mfma_i32_16x16x64_i8 v[44:47], v[112:115], v[32:35], v[44:47]
	v_mfma_i32_16x16x64_i8 v[36:39], v[128:131], v[32:35], v[36:39]

.LBB0_1486:
	s_add_u32 s64, s64, 0x20000
	s_addc_u32 s65, s65, 0
	s_mov_b32 m0, s77
	s_nop 0
	global_load_lds_dwordx4 v198, s[64:65]
	s_mov_b32 m0, s78
	s_and_b64 vcc, exec, s[8:9]
	global_load_lds_dwordx4 v202, s[64:65]
	s_waitcnt vmcnt(8)
	s_waitcnt lgkmcnt(0)
	s_barrier
	s_cbranch_vccnz .LBB0_1488
	s_waitcnt lgkmcnt(0)
	v_mfma_i32_16x16x64_i8 v[176:179], v[180:183], v[4:7], v[176:179]
	v_mfma_i32_16x16x64_i8 v[168:171], v[188:191], v[4:7], v[168:171]
	v_mfma_i32_16x16x64_i8 v[160:163], v[180:183], v[12:15], v[160:163]
	v_mfma_i32_16x16x64_i8 v[152:155], v[188:191], v[12:15], v[152:155]
	v_mfma_i32_16x16x64_i8 v[144:147], v[180:183], v[20:23], v[144:147]
	v_mfma_i32_16x16x64_i8 v[136:139], v[188:191], v[20:23], v[136:139]
	v_mfma_i32_16x16x64_i8 v[120:123], v[180:183], v[28:31], v[120:123]
	v_mfma_i32_16x16x64_i8 v[104:107], v[188:191], v[28:31], v[104:107]
	v_mfma_i32_16x16x64_i8 v[176:179], v[184:187], v[8:11], v[176:179]
	v_mfma_i32_16x16x64_i8 v[168:171], v[192:195], v[8:11], v[168:171]
	v_mfma_i32_16x16x64_i8 v[160:163], v[184:187], v[16:19], v[160:163]
	v_mfma_i32_16x16x64_i8 v[152:155], v[192:195], v[16:19], v[152:155]
	v_mfma_i32_16x16x64_i8 v[144:147], v[184:187], v[24:27], v[144:147]
	v_mfma_i32_16x16x64_i8 v[136:139], v[192:195], v[24:27], v[136:139]
	v_mfma_i32_16x16x64_i8 v[120:123], v[184:187], v[32:35], v[120:123]
	v_mfma_i32_16x16x64_i8 v[104:107], v[192:195], v[32:35], v[104:107]
	v_mfma_i32_16x16x64_i8 v[172:175], v[108:111], v[4:7], v[172:175]
	v_mfma_i32_16x16x64_i8 v[164:167], v[124:127], v[4:7], v[164:167]
	v_mfma_i32_16x16x64_i8 v[156:159], v[108:111], v[12:15], v[156:159]
	v_mfma_i32_16x16x64_i8 v[148:151], v[124:127], v[12:15], v[148:151]
	v_mfma_i32_16x16x64_i8 v[140:143], v[108:111], v[20:23], v[140:143]
	v_mfma_i32_16x16x64_i8 v[132:135], v[124:127], v[20:23], v[132:135]
	v_mfma_i32_16x16x64_i8 v[116:119], v[108:111], v[28:31], v[116:119]
	v_mfma_i32_16x16x64_i8 v[100:103], v[124:127], v[28:31], v[100:103]
	v_mfma_i32_16x16x64_i8 v[172:175], v[112:115], v[8:11], v[172:175]
	v_mfma_i32_16x16x64_i8 v[164:167], v[128:131], v[8:11], v[164:167]
	v_mfma_i32_16x16x64_i8 v[156:159], v[112:115], v[16:19], v[156:159]
	v_mfma_i32_16x16x64_i8 v[148:151], v[128:131], v[16:19], v[148:151]
	v_mfma_i32_16x16x64_i8 v[140:143], v[112:115], v[24:27], v[140:143]
	v_mfma_i32_16x16x64_i8 v[132:135], v[128:131], v[24:27], v[132:135]
	v_mfma_i32_16x16x64_i8 v[116:119], v[112:115], v[32:35], v[116:119]
	v_mfma_i32_16x16x64_i8 v[100:103], v[128:131], v[32:35], v[100:103]

.LBB0_1490:
	s_mov_b32 m0, s80
	s_add_u32 s98, s98, s20
	s_addc_u32 s99, s99, s21
	s_add_u32 s8, s62, 0x20080
	global_load_lds_dwordx4 v200, s[98:99]
	s_mov_b32 m0, s81
	s_addc_u32 s9, s63, 0
	global_load_lds_dwordx4 v204, s[98:99]
	s_mov_b32 m0, s84
	s_and_b64 vcc, exec, s[6:7]
	global_load_lds_dwordx4 v200, s[8:9]
	s_mov_b32 m0, s85
	s_nop 0
	global_load_lds_dwordx4 v204, s[8:9]
	s_add_u32 s100, s100, s20
	s_addc_u32 s101, s101, s21
	s_mov_b32 m0, s82
	s_nop 0
	global_load_lds_dwordx4 v198, s[100:101]
	s_mov_b32 m0, s83
	s_nop 0
	global_load_lds_dwordx4 v202, s[100:101]
	s_waitcnt vmcnt(8)
	s_waitcnt lgkmcnt(0)
	s_barrier
	s_cbranch_vccnz .LBB0_1475
	s_waitcnt lgkmcnt(0)
	v_mfma_i32_16x16x64_i8 v[96:99], v[180:183], v[4:7], v[96:99]
	v_mfma_i32_16x16x64_i8 v[88:91], v[188:191], v[4:7], v[88:91]
	v_mfma_i32_16x16x64_i8 v[80:83], v[180:183], v[12:15], v[80:83]
	v_mfma_i32_16x16x64_i8 v[72:75], v[188:191], v[12:15], v[72:75]
	v_mfma_i32_16x16x64_i8 v[64:67], v[180:183], v[20:23], v[64:67]
	v_mfma_i32_16x16x64_i8 v[56:59], v[188:191], v[20:23], v[56:59]
	v_mfma_i32_16x16x64_i8 v[48:51], v[180:183], v[28:31], v[48:51]
	v_mfma_i32_16x16x64_i8 v[40:43], v[188:191], v[28:31], v[40:43]
	v_mfma_i32_16x16x64_i8 v[96:99], v[184:187], v[8:11], v[96:99]
	v_mfma_i32_16x16x64_i8 v[88:91], v[192:195], v[8:11], v[88:91]
	v_mfma_i32_16x16x64_i8 v[80:83], v[184:187], v[16:19], v[80:83]
	v_mfma_i32_16x16x64_i8 v[72:75], v[192:195], v[16:19], v[72:75]
	v_mfma_i32_16x16x64_i8 v[64:67], v[184:187], v[24:27], v[64:67]
	v_mfma_i32_16x16x64_i8 v[56:59], v[192:195], v[24:27], v[56:59]
	v_mfma_i32_16x16x64_i8 v[48:51], v[184:187], v[32:35], v[48:51]
	v_mfma_i32_16x16x64_i8 v[40:43], v[192:195], v[32:35], v[40:43]
	v_mfma_i32_16x16x64_i8 v[92:95], v[108:111], v[4:7], v[92:95]
	v_mfma_i32_16x16x64_i8 v[84:87], v[124:127], v[4:7], v[84:87]
	v_mfma_i32_16x16x64_i8 v[76:79], v[108:111], v[12:15], v[76:79]
	v_mfma_i32_16x16x64_i8 v[68:71], v[124:127], v[12:15], v[68:71]
	v_mfma_i32_16x16x64_i8 v[60:63], v[108:111], v[20:23], v[60:63]
	v_mfma_i32_16x16x64_i8 v[52:55], v[124:127], v[20:23], v[52:55]
	v_mfma_i32_16x16x64_i8 v[44:47], v[108:111], v[28:31], v[44:47]
	v_mfma_i32_16x16x64_i8 v[36:39], v[124:127], v[28:31], v[36:39]
	v_mfma_i32_16x16x64_i8 v[92:95], v[112:115], v[8:11], v[92:95]
	v_mfma_i32_16x16x64_i8 v[84:87], v[128:131], v[8:11], v[84:87]
	v_mfma_i32_16x16x64_i8 v[76:79], v[112:115], v[16:19], v[76:79]
	v_mfma_i32_16x16x64_i8 v[68:71], v[128:131], v[16:19], v[68:71]
	v_mfma_i32_16x16x64_i8 v[60:63], v[112:115], v[24:27], v[60:63]
	v_mfma_i32_16x16x64_i8 v[52:55], v[128:131], v[24:27], v[52:55]
	v_mfma_i32_16x16x64_i8 v[44:47], v[112:115], v[32:35], v[44:47]
	v_mfma_i32_16x16x64_i8 v[36:39], v[128:131], v[32:35], v[36:39]
	s_branch .LBB0_1475

.LBB0_1636:
	s_add_u32 s56, s48, 0x100
	s_addc_u32 s57, s49, 0
	s_add_i32 s64, 0, 0x10000
	s_cmp_eq_u32 s63, 40
	s_cselect_b32 s61, s13, s57
	s_cselect_b32 s60, s12, s56
	v_add_u32_e32 v0, s64, v169
	s_cselect_b32 s59, s53, s55
	s_cselect_b32 s58, s52, s16
	s_add_i32 s65, 0, 0x14000
	ds_read_b128 v[148:151], v0
	ds_read_b128 v[152:155], v0 offset:1024
	ds_read_b128 v[156:159], v0 offset:2048
	ds_read_b128 v[190:193], v0 offset:3072
	v_add_u32_e32 v0, s65, v169
	ds_read_b128 v[194:197], v0
	ds_read_b128 v[198:201], v0 offset:1024
	ds_read_b128 v[202:205], v0 offset:2048
	ds_read_b128 v[206:209], v0 offset:3072
	v_lshl_add_u64 v[230:231], s[48:49], 0, v[144:145]
	s_add_i32 m0, s79, 0xc000
	ds_read_b128 v[210:213], v188
	ds_read_b128 v[214:217], v188 offset:1024
	ds_read_b128 v[218:221], v188 offset:2048
	ds_read_b128 v[222:225], v188 offset:3072
	ds_read_b128 v[226:229], v188 offset:4096
	ds_read_b128 v[234:237], v188 offset:5120
	ds_read_b128 v[238:241], v188 offset:6144
	ds_read_b128 v[242:245], v188 offset:7168
	global_load_lds_dwordx4 v[230:231], off
	v_lshl_add_u64 v[230:231], s[48:49], 0, v[146:147]
	s_add_i32 m0, s79, 0xe000
	s_nop 0
	global_load_lds_dwordx4 v[230:231], off
	s_waitcnt vmcnt(8)
	s_waitcnt lgkmcnt(0)
	s_barrier
	s_waitcnt lgkmcnt(0)
	v_mfma_f32_16x16x32_bf16 v[126:129], v[148:151], v[210:213], v[126:129]
	v_mfma_f32_16x16x32_bf16 v[122:125], v[156:159], v[210:213], v[122:125]
	v_mfma_f32_16x16x32_bf16 v[110:113], v[148:151], v[218:221], v[110:113]
	v_mfma_f32_16x16x32_bf16 v[106:109], v[156:159], v[218:221], v[106:109]
	v_mfma_f32_16x16x32_bf16 v[94:97], v[148:151], v[226:229], v[94:97]
	v_mfma_f32_16x16x32_bf16 v[90:93], v[156:159], v[226:229], v[90:93]
	v_mfma_f32_16x16x32_bf16 v[78:81], v[148:151], v[238:241], v[78:81]
	v_mfma_f32_16x16x32_bf16 v[74:77], v[156:159], v[238:241], v[74:77]
	v_mfma_f32_16x16x32_bf16 v[126:129], v[152:155], v[214:217], v[126:129]
	v_mfma_f32_16x16x32_bf16 v[122:125], v[190:193], v[214:217], v[122:125]
	v_mfma_f32_16x16x32_bf16 v[110:113], v[152:155], v[222:225], v[110:113]
	v_mfma_f32_16x16x32_bf16 v[106:109], v[190:193], v[222:225], v[106:109]
	v_mfma_f32_16x16x32_bf16 v[94:97], v[152:155], v[234:237], v[94:97]
	v_mfma_f32_16x16x32_bf16 v[90:93], v[190:193], v[234:237], v[90:93]
	v_mfma_f32_16x16x32_bf16 v[78:81], v[152:155], v[242:245], v[78:81]
	v_mfma_f32_16x16x32_bf16 v[74:77], v[190:193], v[242:245], v[74:77]
	v_mfma_f32_16x16x32_bf16 v[118:121], v[194:197], v[210:213], v[118:121]
	v_mfma_f32_16x16x32_bf16 v[114:117], v[202:205], v[210:213], v[114:117]
	v_mfma_f32_16x16x32_bf16 v[102:105], v[194:197], v[218:221], v[102:105]
	v_mfma_f32_16x16x32_bf16 v[98:101], v[202:205], v[218:221], v[98:101]
	v_mfma_f32_16x16x32_bf16 v[86:89], v[194:197], v[226:229], v[86:89]
	v_mfma_f32_16x16x32_bf16 v[82:85], v[202:205], v[226:229], v[82:85]
	v_mfma_f32_16x16x32_bf16 v[70:73], v[194:197], v[238:241], v[70:73]
	v_mfma_f32_16x16x32_bf16 v[66:69], v[202:205], v[238:241], v[66:69]
	v_mfma_f32_16x16x32_bf16 v[118:121], v[198:201], v[214:217], v[118:121]
	v_mfma_f32_16x16x32_bf16 v[114:117], v[206:209], v[214:217], v[114:117]
	v_mfma_f32_16x16x32_bf16 v[102:105], v[198:201], v[222:225], v[102:105]
	v_mfma_f32_16x16x32_bf16 v[98:101], v[206:209], v[222:225], v[98:101]
	v_mfma_f32_16x16x32_bf16 v[86:89], v[198:201], v[234:237], v[86:89]
	v_mfma_f32_16x16x32_bf16 v[82:85], v[206:209], v[234:237], v[82:85]
	v_mfma_f32_16x16x32_bf16 v[70:73], v[198:201], v[242:245], v[70:73]
	v_mfma_f32_16x16x32_bf16 v[66:69], v[206:209], v[242:245], v[66:69]
	s_barrier
	s_add_i32 s48, s64, s78
	s_mov_b64 s[98:99], s[58:59]
	s_mov_b32 m0, s48
	ds_read_b128 v[210:213], v188 offset:16384
	ds_read_b128 v[214:217], v188 offset:17408
	ds_read_b128 v[218:221], v188 offset:18432
	ds_read_b128 v[222:225], v188 offset:19456
	ds_read_b128 v[226:229], v188 offset:20480
	ds_read_b128 v[234:237], v188 offset:21504
	ds_read_b128 v[238:241], v188 offset:22528
	ds_read_b128 v[242:245], v188 offset:23552
	global_load_lds_dwordx4 v136, s[58:59]
	s_add_i32 m0, s48, 0x2000
	s_add_u32 s48, s58, 0xb0000
	s_addc_u32 s49, s59, 0
	s_add_i32 s64, s65, s78
	global_load_lds_dwordx4 v140, s[58:59]
	s_mov_b32 m0, s64
	s_mov_b64 s[100:101], s[60:61]
	global_load_lds_dwordx4 v136, s[48:49]
	s_add_i32 m0, s64, 0x2000
	s_nop 0
	global_load_lds_dwordx4 v140, s[48:49]
	s_mov_b32 m0, s79
	s_nop 0
	global_load_lds_dwordx4 v134, s[60:61]
	s_mov_b32 m0, s80
	s_nop 0
	global_load_lds_dwordx4 v138, s[60:61]
	s_waitcnt vmcnt(8)
	s_waitcnt lgkmcnt(0)
	s_barrier
	s_waitcnt lgkmcnt(0)
	v_mfma_f32_16x16x32_bf16 v[62:65], v[148:151], v[210:213], v[62:65]
	v_mfma_f32_16x16x32_bf16 v[58:61], v[156:159], v[210:213], v[58:61]
	v_mfma_f32_16x16x32_bf16 v[46:49], v[148:151], v[218:221], v[46:49]
	v_mfma_f32_16x16x32_bf16 v[42:45], v[156:159], v[218:221], v[42:45]
	v_mfma_f32_16x16x32_bf16 v[30:33], v[148:151], v[226:229], v[30:33]
	v_mfma_f32_16x16x32_bf16 v[26:29], v[156:159], v[226:229], v[26:29]
	v_mfma_f32_16x16x32_bf16 v[14:17], v[148:151], v[238:241], v[14:17]
	v_mfma_f32_16x16x32_bf16 v[10:13], v[156:159], v[238:241], v[10:13]
	v_mfma_f32_16x16x32_bf16 v[62:65], v[152:155], v[214:217], v[62:65]
	v_mfma_f32_16x16x32_bf16 v[58:61], v[190:193], v[214:217], v[58:61]
	v_mfma_f32_16x16x32_bf16 v[46:49], v[152:155], v[222:225], v[46:49]
	v_mfma_f32_16x16x32_bf16 v[42:45], v[190:193], v[222:225], v[42:45]
	v_mfma_f32_16x16x32_bf16 v[30:33], v[152:155], v[234:237], v[30:33]
	v_mfma_f32_16x16x32_bf16 v[26:29], v[190:193], v[234:237], v[26:29]
	v_mfma_f32_16x16x32_bf16 v[14:17], v[152:155], v[242:245], v[14:17]
	v_mfma_f32_16x16x32_bf16 v[10:13], v[190:193], v[242:245], v[10:13]
	v_mfma_f32_16x16x32_bf16 v[54:57], v[194:197], v[210:213], v[54:57]
	v_mfma_f32_16x16x32_bf16 v[50:53], v[202:205], v[210:213], v[50:53]
	v_mfma_f32_16x16x32_bf16 v[38:41], v[194:197], v[218:221], v[38:41]
	v_mfma_f32_16x16x32_bf16 v[34:37], v[202:205], v[218:221], v[34:37]
	v_mfma_f32_16x16x32_bf16 v[22:25], v[194:197], v[226:229], v[22:25]
	v_mfma_f32_16x16x32_bf16 v[18:21], v[202:205], v[226:229], v[18:21]
	v_mfma_f32_16x16x32_bf16 v[6:9], v[194:197], v[238:241], v[6:9]
	v_mfma_f32_16x16x32_bf16 v[2:5], v[202:205], v[238:241], v[2:5]
	v_mfma_f32_16x16x32_bf16 v[54:57], v[198:201], v[214:217], v[54:57]
	v_mfma_f32_16x16x32_bf16 v[50:53], v[206:209], v[214:217], v[50:53]
	v_mfma_f32_16x16x32_bf16 v[38:41], v[198:201], v[222:225], v[38:41]
	v_mfma_f32_16x16x32_bf16 v[34:37], v[206:209], v[222:225], v[34:37]
	v_mfma_f32_16x16x32_bf16 v[22:25], v[198:201], v[234:237], v[22:25]
	v_mfma_f32_16x16x32_bf16 v[18:21], v[206:209], v[234:237], v[18:21]
	v_mfma_f32_16x16x32_bf16 v[6:9], v[198:201], v[242:245], v[6:9]
	v_mfma_f32_16x16x32_bf16 v[2:5], v[206:209], v[242:245], v[2:5]
	s_barrier
	s_add_i32 s64, 0, 0x18000
	v_add_u32_e32 v0, s64, v169
	s_add_i32 s65, 0, 0x1c000
	ds_read_b128 v[148:151], v0
	ds_read_b128 v[152:155], v0 offset:1024
	ds_read_b128 v[156:159], v0 offset:2048
	ds_read_b128 v[190:193], v0 offset:3072
	v_add_u32_e32 v0, s65, v169
	ds_read_b128 v[194:197], v0
	ds_read_b128 v[198:201], v0 offset:1024
	ds_read_b128 v[202:205], v0 offset:2048
	ds_read_b128 v[206:209], v0 offset:3072
	s_add_u32 s48, s60, 0xb0000
	s_addc_u32 s49, s61, 0
	s_mov_b32 m0, s81
	ds_read_b128 v[210:213], v188 offset:32768
	ds_read_b128 v[214:217], v188 offset:33792
	ds_read_b128 v[218:221], v188 offset:34816
	ds_read_b128 v[222:225], v188 offset:35840
	ds_read_b128 v[226:229], v188 offset:36864
	ds_read_b128 v[234:237], v188 offset:37888
	ds_read_b128 v[238:241], v188 offset:38912
	ds_read_b128 v[242:245], v188 offset:39936
	global_load_lds_dwordx4 v134, s[48:49]
	s_mov_b32 m0, s82
	s_nop 0
	global_load_lds_dwordx4 v138, s[48:49]
	s_waitcnt vmcnt(8)
	s_waitcnt lgkmcnt(0)
	s_barrier
	s_waitcnt lgkmcnt(0)
	v_mfma_f32_16x16x32_bf16 v[126:129], v[148:151], v[210:213], v[126:129]
	v_mfma_f32_16x16x32_bf16 v[122:125], v[156:159], v[210:213], v[122:125]
	v_mfma_f32_16x16x32_bf16 v[110:113], v[148:151], v[218:221], v[110:113]
	v_mfma_f32_16x16x32_bf16 v[106:109], v[156:159], v[218:221], v[106:109]
	v_mfma_f32_16x16x32_bf16 v[94:97], v[148:151], v[226:229], v[94:97]
	v_mfma_f32_16x16x32_bf16 v[90:93], v[156:159], v[226:229], v[90:93]
	v_mfma_f32_16x16x32_bf16 v[78:81], v[148:151], v[238:241], v[78:81]
	v_mfma_f32_16x16x32_bf16 v[74:77], v[156:159], v[238:241], v[74:77]
	v_mfma_f32_16x16x32_bf16 v[126:129], v[152:155], v[214:217], v[126:129]
	v_mfma_f32_16x16x32_bf16 v[122:125], v[190:193], v[214:217], v[122:125]
	v_mfma_f32_16x16x32_bf16 v[110:113], v[152:155], v[222:225], v[110:113]
	v_mfma_f32_16x16x32_bf16 v[106:109], v[190:193], v[222:225], v[106:109]
	v_mfma_f32_16x16x32_bf16 v[94:97], v[152:155], v[234:237], v[94:97]
	v_mfma_f32_16x16x32_bf16 v[90:93], v[190:193], v[234:237], v[90:93]
	v_mfma_f32_16x16x32_bf16 v[78:81], v[152:155], v[242:245], v[78:81]
	v_mfma_f32_16x16x32_bf16 v[74:77], v[190:193], v[242:245], v[74:77]
	v_mfma_f32_16x16x32_bf16 v[118:121], v[194:197], v[210:213], v[118:121]
	v_mfma_f32_16x16x32_bf16 v[114:117], v[202:205], v[210:213], v[114:117]
	v_mfma_f32_16x16x32_bf16 v[102:105], v[194:197], v[218:221], v[102:105]
	v_mfma_f32_16x16x32_bf16 v[98:101], v[202:205], v[218:221], v[98:101]
	v_mfma_f32_16x16x32_bf16 v[86:89], v[194:197], v[226:229], v[86:89]
	v_mfma_f32_16x16x32_bf16 v[82:85], v[202:205], v[226:229], v[82:85]
	v_mfma_f32_16x16x32_bf16 v[70:73], v[194:197], v[238:241], v[70:73]
	v_mfma_f32_16x16x32_bf16 v[66:69], v[202:205], v[238:241], v[66:69]
	v_mfma_f32_16x16x32_bf16 v[118:121], v[198:201], v[214:217], v[118:121]
	v_mfma_f32_16x16x32_bf16 v[114:117], v[206:209], v[214:217], v[114:117]
	v_mfma_f32_16x16x32_bf16 v[102:105], v[198:201], v[222:225], v[102:105]
	v_mfma_f32_16x16x32_bf16 v[98:101], v[206:209], v[222:225], v[98:101]
	v_mfma_f32_16x16x32_bf16 v[86:89], v[198:201], v[234:237], v[86:89]
	v_mfma_f32_16x16x32_bf16 v[82:85], v[206:209], v[234:237], v[82:85]
	v_mfma_f32_16x16x32_bf16 v[70:73], v[198:201], v[242:245], v[70:73]
	v_mfma_f32_16x16x32_bf16 v[66:69], v[206:209], v[242:245], v[66:69]
	s_barrier
	s_add_i32 s48, s64, s78
	s_add_u32 s98, s98, s18
	s_addc_u32 s99, s99, s19
	s_mov_b32 m0, s48
	ds_read_b128 v[210:213], v188 offset:49152
	ds_read_b128 v[214:217], v188 offset:50176
	ds_read_b128 v[218:221], v188 offset:51200
	ds_read_b128 v[222:225], v188 offset:52224
	ds_read_b128 v[226:229], v188 offset:53248
	ds_read_b128 v[234:237], v188 offset:54272
	ds_read_b128 v[238:241], v188 offset:55296
	ds_read_b128 v[242:245], v188 offset:56320
	global_load_lds_dwordx4 v136, s[98:99]
	s_add_i32 m0, s48, 0x2000
	s_add_u32 s48, s58, 0xb0080
	s_addc_u32 s49, s59, 0
	s_add_i32 s58, s65, s78
	global_load_lds_dwordx4 v140, s[98:99]
	s_mov_b32 m0, s58
	s_nop 0
	global_load_lds_dwordx4 v136, s[48:49]
	s_add_i32 m0, s58, 0x2000
	s_nop 0
	global_load_lds_dwordx4 v140, s[48:49]
	s_add_u32 s100, s100, s18
	s_addc_u32 s101, s101, s19
	s_mov_b32 m0, s85
	s_nop 0
	global_load_lds_dwordx4 v134, s[100:101]
	s_mov_b32 m0, s86
	s_nop 0
	global_load_lds_dwordx4 v138, s[100:101]
	s_waitcnt vmcnt(8)
	s_waitcnt lgkmcnt(0)
	s_barrier
	s_waitcnt lgkmcnt(0)
	v_mfma_f32_16x16x32_bf16 v[62:65], v[148:151], v[210:213], v[62:65]
	v_mfma_f32_16x16x32_bf16 v[58:61], v[156:159], v[210:213], v[58:61]
	v_mfma_f32_16x16x32_bf16 v[46:49], v[148:151], v[218:221], v[46:49]
	v_mfma_f32_16x16x32_bf16 v[42:45], v[156:159], v[218:221], v[42:45]
	v_mfma_f32_16x16x32_bf16 v[30:33], v[148:151], v[226:229], v[30:33]
	v_mfma_f32_16x16x32_bf16 v[26:29], v[156:159], v[226:229], v[26:29]
	v_mfma_f32_16x16x32_bf16 v[14:17], v[148:151], v[238:241], v[14:17]
	v_mfma_f32_16x16x32_bf16 v[10:13], v[156:159], v[238:241], v[10:13]
	v_mfma_f32_16x16x32_bf16 v[62:65], v[152:155], v[214:217], v[62:65]
	v_mfma_f32_16x16x32_bf16 v[58:61], v[190:193], v[214:217], v[58:61]
	v_mfma_f32_16x16x32_bf16 v[46:49], v[152:155], v[222:225], v[46:49]
	v_mfma_f32_16x16x32_bf16 v[42:45], v[190:193], v[222:225], v[42:45]
	v_mfma_f32_16x16x32_bf16 v[30:33], v[152:155], v[234:237], v[30:33]
	v_mfma_f32_16x16x32_bf16 v[26:29], v[190:193], v[234:237], v[26:29]
	v_mfma_f32_16x16x32_bf16 v[14:17], v[152:155], v[242:245], v[14:17]
	v_mfma_f32_16x16x32_bf16 v[10:13], v[190:193], v[242:245], v[10:13]
	v_mfma_f32_16x16x32_bf16 v[54:57], v[194:197], v[210:213], v[54:57]
	v_mfma_f32_16x16x32_bf16 v[50:53], v[202:205], v[210:213], v[50:53]
	v_mfma_f32_16x16x32_bf16 v[38:41], v[194:197], v[218:221], v[38:41]
	v_mfma_f32_16x16x32_bf16 v[34:37], v[202:205], v[218:221], v[34:37]
	v_mfma_f32_16x16x32_bf16 v[22:25], v[194:197], v[226:229], v[22:25]
	v_mfma_f32_16x16x32_bf16 v[18:21], v[202:205], v[226:229], v[18:21]
	v_mfma_f32_16x16x32_bf16 v[6:9], v[194:197], v[238:241], v[6:9]
	v_mfma_f32_16x16x32_bf16 v[2:5], v[202:205], v[238:241], v[2:5]
	v_mfma_f32_16x16x32_bf16 v[54:57], v[198:201], v[214:217], v[54:57]
	v_mfma_f32_16x16x32_bf16 v[50:53], v[206:209], v[214:217], v[50:53]
	v_mfma_f32_16x16x32_bf16 v[38:41], v[198:201], v[222:225], v[38:41]
	v_mfma_f32_16x16x32_bf16 v[34:37], v[206:209], v[222:225], v[34:37]
	v_mfma_f32_16x16x32_bf16 v[22:25], v[198:201], v[234:237], v[22:25]
	v_mfma_f32_16x16x32_bf16 v[18:21], v[206:209], v[234:237], v[18:21]
	v_mfma_f32_16x16x32_bf16 v[6:9], v[198:201], v[242:245], v[6:9]
	v_mfma_f32_16x16x32_bf16 v[2:5], v[206:209], v[242:245], v[2:5]
	s_barrier
	s_add_i32 s63, s63, 2
	s_add_u32 s16, s16, 0x100
	s_addc_u32 s55, s55, 0
	s_cmp_gt_u32 s63, 41
	s_mov_b64 s[48:49], s[56:57]
	s_cbranch_scc0 .LBB0_1636
	s_and_b64 vcc, exec, s[42:43]
	s_cbranch_vccz .LBB0_1640
	s_barrier
	s_andn2_b64 vcc, exec, s[24:25]
	s_cbranch_vccz .LBB0_1641

.LBB0_2108:
	s_add_u32 s48, s8, 0xfffc0080
	s_addc_u32 s49, s9, -1
	s_add_i32 s85, 0, 0x10000
	s_cmp_eq_u32 s71, 12
	s_cselect_b32 s65, s7, s49
	s_cselect_b32 s64, s57, s48
	v_add_u32_e32 v128, s85, v173
	s_cselect_b32 s49, s59, s70
	s_cselect_b32 s48, s68, s69
	s_add_i32 s87, 0, 0x14000
	ds_read_b128 v[174:177], v128
	ds_read_b128 v[180:183], v128 offset:1024
	ds_read_b128 v[184:187], v128 offset:2048
	ds_read_b128 v[188:191], v128 offset:3072
	v_add_u32_e32 v128, s87, v173
	ds_read_b128 v[192:195], v128
	ds_read_b128 v[196:199], v128 offset:1024
	ds_read_b128 v[202:205], v128 offset:2048
	ds_read_b128 v[206:209], v128 offset:3072
	s_add_i32 m0, s67, 0xc000
	ds_read_b128 v[216:219], v200
	ds_read_b128 v[220:223], v200 offset:1024
	ds_read_b128 v[224:227], v200 offset:2048
	ds_read_b128 v[228:231], v200 offset:3072
	ds_read_b128 v[234:237], v200 offset:4096
	ds_read_b128 v[238:241], v200 offset:5120
	ds_read_b128 v[242:245], v200 offset:6144
	ds_read_b128 v[246:249], v200 offset:7168
	global_load_lds_dwordx4 v148, s[8:9]
	s_add_i32 m0, s67, 0xe000
	s_nop 0
	global_load_lds_dwordx4 v150, s[8:9]
	s_waitcnt vmcnt(8)
	s_waitcnt lgkmcnt(0)
	s_barrier
	s_waitcnt lgkmcnt(0)
	v_mfma_f32_16x16x32_bf16 v[124:127], v[174:177], v[216:219], v[124:127]
	v_mfma_f32_16x16x32_bf16 v[120:123], v[184:187], v[216:219], v[120:123]
	v_mfma_f32_16x16x32_bf16 v[108:111], v[174:177], v[224:227], v[108:111]
	v_mfma_f32_16x16x32_bf16 v[104:107], v[184:187], v[224:227], v[104:107]
	v_mfma_f32_16x16x32_bf16 v[92:95], v[174:177], v[234:237], v[92:95]
	v_mfma_f32_16x16x32_bf16 v[88:91], v[184:187], v[234:237], v[88:91]
	v_mfma_f32_16x16x32_bf16 v[76:79], v[174:177], v[242:245], v[76:79]
	v_mfma_f32_16x16x32_bf16 v[72:75], v[184:187], v[242:245], v[72:75]
	v_mfma_f32_16x16x32_bf16 v[124:127], v[180:183], v[220:223], v[124:127]
	v_mfma_f32_16x16x32_bf16 v[120:123], v[188:191], v[220:223], v[120:123]
	v_mfma_f32_16x16x32_bf16 v[108:111], v[180:183], v[228:231], v[108:111]
	v_mfma_f32_16x16x32_bf16 v[104:107], v[188:191], v[228:231], v[104:107]
	v_mfma_f32_16x16x32_bf16 v[92:95], v[180:183], v[238:241], v[92:95]
	v_mfma_f32_16x16x32_bf16 v[88:91], v[188:191], v[238:241], v[88:91]
	v_mfma_f32_16x16x32_bf16 v[76:79], v[180:183], v[246:249], v[76:79]
	v_mfma_f32_16x16x32_bf16 v[72:75], v[188:191], v[246:249], v[72:75]
	v_mfma_f32_16x16x32_bf16 v[116:119], v[192:195], v[216:219], v[116:119]
	v_mfma_f32_16x16x32_bf16 v[112:115], v[202:205], v[216:219], v[112:115]
	v_mfma_f32_16x16x32_bf16 v[100:103], v[192:195], v[224:227], v[100:103]
	v_mfma_f32_16x16x32_bf16 v[96:99], v[202:205], v[224:227], v[96:99]
	v_mfma_f32_16x16x32_bf16 v[84:87], v[192:195], v[234:237], v[84:87]
	v_mfma_f32_16x16x32_bf16 v[80:83], v[202:205], v[234:237], v[80:83]
	v_mfma_f32_16x16x32_bf16 v[68:71], v[192:195], v[242:245], v[68:71]
	v_mfma_f32_16x16x32_bf16 v[64:67], v[202:205], v[242:245], v[64:67]
	v_mfma_f32_16x16x32_bf16 v[116:119], v[196:199], v[220:223], v[116:119]
	v_mfma_f32_16x16x32_bf16 v[112:115], v[206:209], v[220:223], v[112:115]
	v_mfma_f32_16x16x32_bf16 v[100:103], v[196:199], v[228:231], v[100:103]
	v_mfma_f32_16x16x32_bf16 v[96:99], v[206:209], v[228:231], v[96:99]
	v_mfma_f32_16x16x32_bf16 v[84:87], v[196:199], v[238:241], v[84:87]
	v_mfma_f32_16x16x32_bf16 v[80:83], v[206:209], v[238:241], v[80:83]
	v_mfma_f32_16x16x32_bf16 v[68:71], v[196:199], v[246:249], v[68:71]
	v_mfma_f32_16x16x32_bf16 v[64:67], v[206:209], v[246:249], v[64:67]
	s_barrier
	s_add_i32 s85, s85, s77
	s_mov_b64 s[98:99], s[48:49]
	s_mov_b32 m0, s85
	ds_read_b128 v[216:219], v200 offset:16384
	ds_read_b128 v[220:223], v200 offset:17408
	ds_read_b128 v[224:227], v200 offset:18432
	ds_read_b128 v[228:231], v200 offset:19456
	ds_read_b128 v[234:237], v200 offset:20480
	ds_read_b128 v[238:241], v200 offset:21504
	ds_read_b128 v[242:245], v200 offset:22528
	ds_read_b128 v[246:249], v200 offset:23552
	global_load_lds_dwordx4 v136, s[48:49]
	s_add_i32 m0, s85, 0x2000
	s_add_u32 s88, s48, 0x40000
	s_addc_u32 s89, s49, 0
	s_add_i32 s85, s87, s77
	global_load_lds_dwordx4 v140, s[48:49]
	s_mov_b32 m0, s85
	s_mov_b64 s[100:101], s[64:65]
	global_load_lds_dwordx4 v136, s[88:89]
	s_add_i32 m0, s85, 0x2000
	s_nop 0
	global_load_lds_dwordx4 v140, s[88:89]
	s_mov_b32 m0, s67
	s_nop 0
	global_load_lds_dwordx4 v134, s[64:65]
	s_mov_b32 m0, s78
	s_nop 0
	global_load_lds_dwordx4 v138, s[64:65]
	s_waitcnt vmcnt(8)
	s_waitcnt lgkmcnt(0)
	s_barrier
	s_waitcnt lgkmcnt(0)
	v_mfma_f32_16x16x32_bf16 v[60:63], v[174:177], v[216:219], v[60:63]
	v_mfma_f32_16x16x32_bf16 v[56:59], v[184:187], v[216:219], v[56:59]
	v_mfma_f32_16x16x32_bf16 v[44:47], v[174:177], v[224:227], v[44:47]
	v_mfma_f32_16x16x32_bf16 v[40:43], v[184:187], v[224:227], v[40:43]
	v_mfma_f32_16x16x32_bf16 v[28:31], v[174:177], v[234:237], v[28:31]
	v_mfma_f32_16x16x32_bf16 v[24:27], v[184:187], v[234:237], v[24:27]
	v_mfma_f32_16x16x32_bf16 v[12:15], v[174:177], v[242:245], v[12:15]
	v_mfma_f32_16x16x32_bf16 v[8:11], v[184:187], v[242:245], v[8:11]
	v_mfma_f32_16x16x32_bf16 v[60:63], v[180:183], v[220:223], v[60:63]
	v_mfma_f32_16x16x32_bf16 v[56:59], v[188:191], v[220:223], v[56:59]
	v_mfma_f32_16x16x32_bf16 v[44:47], v[180:183], v[228:231], v[44:47]
	v_mfma_f32_16x16x32_bf16 v[40:43], v[188:191], v[228:231], v[40:43]
	v_mfma_f32_16x16x32_bf16 v[28:31], v[180:183], v[238:241], v[28:31]
	v_mfma_f32_16x16x32_bf16 v[24:27], v[188:191], v[238:241], v[24:27]
	v_mfma_f32_16x16x32_bf16 v[12:15], v[180:183], v[246:249], v[12:15]
	v_mfma_f32_16x16x32_bf16 v[8:11], v[188:191], v[246:249], v[8:11]
	v_mfma_f32_16x16x32_bf16 v[52:55], v[192:195], v[216:219], v[52:55]
	v_mfma_f32_16x16x32_bf16 v[48:51], v[202:205], v[216:219], v[48:51]
	v_mfma_f32_16x16x32_bf16 v[36:39], v[192:195], v[224:227], v[36:39]
	v_mfma_f32_16x16x32_bf16 v[32:35], v[202:205], v[224:227], v[32:35]
	v_mfma_f32_16x16x32_bf16 v[20:23], v[192:195], v[234:237], v[20:23]
	v_mfma_f32_16x16x32_bf16 v[16:19], v[202:205], v[234:237], v[16:19]
	v_mfma_f32_16x16x32_bf16 v[4:7], v[192:195], v[242:245], v[4:7]
	v_mfma_f32_16x16x32_bf16 v[0:3], v[202:205], v[242:245], v[0:3]
	v_mfma_f32_16x16x32_bf16 v[52:55], v[196:199], v[220:223], v[52:55]
	v_mfma_f32_16x16x32_bf16 v[48:51], v[206:209], v[220:223], v[48:51]
	v_mfma_f32_16x16x32_bf16 v[36:39], v[196:199], v[228:231], v[36:39]
	v_mfma_f32_16x16x32_bf16 v[32:35], v[206:209], v[228:231], v[32:35]
	v_mfma_f32_16x16x32_bf16 v[20:23], v[196:199], v[238:241], v[20:23]
	v_mfma_f32_16x16x32_bf16 v[16:19], v[206:209], v[238:241], v[16:19]
	v_mfma_f32_16x16x32_bf16 v[4:7], v[196:199], v[246:249], v[4:7]
	v_mfma_f32_16x16x32_bf16 v[0:3], v[206:209], v[246:249], v[0:3]
	s_barrier
	v_add_u32_e32 v128, s0, v173
	s_add_i32 s85, 0, 0x1c000
	ds_read_b128 v[174:177], v128
	ds_read_b128 v[180:183], v128 offset:1024
	ds_read_b128 v[184:187], v128 offset:2048
	ds_read_b128 v[188:191], v128 offset:3072
	v_add_u32_e32 v128, s85, v173
	ds_read_b128 v[192:195], v128
	ds_read_b128 v[196:199], v128 offset:1024
	ds_read_b128 v[202:205], v128 offset:2048
	ds_read_b128 v[206:209], v128 offset:3072
	s_add_u32 s64, s64, 0x40000
	s_addc_u32 s65, s65, 0
	s_mov_b32 m0, s79
	ds_read_b128 v[216:219], v200 offset:32768
	ds_read_b128 v[220:223], v200 offset:33792
	ds_read_b128 v[224:227], v200 offset:34816
	ds_read_b128 v[228:231], v200 offset:35840
	ds_read_b128 v[234:237], v200 offset:36864
	ds_read_b128 v[238:241], v200 offset:37888
	ds_read_b128 v[242:245], v200 offset:38912
	ds_read_b128 v[246:249], v200 offset:39936
	global_load_lds_dwordx4 v134, s[64:65]
	s_mov_b32 m0, s80
	s_nop 0
	global_load_lds_dwordx4 v138, s[64:65]
	s_waitcnt vmcnt(8)
	s_waitcnt lgkmcnt(0)
	s_barrier
	s_waitcnt lgkmcnt(0)
	v_mfma_f32_16x16x32_bf16 v[124:127], v[174:177], v[216:219], v[124:127]
	v_mfma_f32_16x16x32_bf16 v[120:123], v[184:187], v[216:219], v[120:123]
	v_mfma_f32_16x16x32_bf16 v[108:111], v[174:177], v[224:227], v[108:111]
	v_mfma_f32_16x16x32_bf16 v[104:107], v[184:187], v[224:227], v[104:107]
	v_mfma_f32_16x16x32_bf16 v[92:95], v[174:177], v[234:237], v[92:95]
	v_mfma_f32_16x16x32_bf16 v[88:91], v[184:187], v[234:237], v[88:91]
	v_mfma_f32_16x16x32_bf16 v[76:79], v[174:177], v[242:245], v[76:79]
	v_mfma_f32_16x16x32_bf16 v[72:75], v[184:187], v[242:245], v[72:75]
	v_mfma_f32_16x16x32_bf16 v[124:127], v[180:183], v[220:223], v[124:127]
	v_mfma_f32_16x16x32_bf16 v[120:123], v[188:191], v[220:223], v[120:123]
	v_mfma_f32_16x16x32_bf16 v[108:111], v[180:183], v[228:231], v[108:111]
	v_mfma_f32_16x16x32_bf16 v[104:107], v[188:191], v[228:231], v[104:107]
	v_mfma_f32_16x16x32_bf16 v[92:95], v[180:183], v[238:241], v[92:95]
	v_mfma_f32_16x16x32_bf16 v[88:91], v[188:191], v[238:241], v[88:91]
	v_mfma_f32_16x16x32_bf16 v[76:79], v[180:183], v[246:249], v[76:79]
	v_mfma_f32_16x16x32_bf16 v[72:75], v[188:191], v[246:249], v[72:75]
	v_mfma_f32_16x16x32_bf16 v[116:119], v[192:195], v[216:219], v[116:119]
	v_mfma_f32_16x16x32_bf16 v[112:115], v[202:205], v[216:219], v[112:115]
	v_mfma_f32_16x16x32_bf16 v[100:103], v[192:195], v[224:227], v[100:103]
	v_mfma_f32_16x16x32_bf16 v[96:99], v[202:205], v[224:227], v[96:99]
	v_mfma_f32_16x16x32_bf16 v[84:87], v[192:195], v[234:237], v[84:87]
	v_mfma_f32_16x16x32_bf16 v[80:83], v[202:205], v[234:237], v[80:83]
	v_mfma_f32_16x16x32_bf16 v[68:71], v[192:195], v[242:245], v[68:71]
	v_mfma_f32_16x16x32_bf16 v[64:67], v[202:205], v[242:245], v[64:67]
	v_mfma_f32_16x16x32_bf16 v[116:119], v[196:199], v[220:223], v[116:119]
	v_mfma_f32_16x16x32_bf16 v[112:115], v[206:209], v[220:223], v[112:115]
	v_mfma_f32_16x16x32_bf16 v[100:103], v[196:199], v[228:231], v[100:103]
	v_mfma_f32_16x16x32_bf16 v[96:99], v[206:209], v[228:231], v[96:99]
	v_mfma_f32_16x16x32_bf16 v[84:87], v[196:199], v[238:241], v[84:87]
	v_mfma_f32_16x16x32_bf16 v[80:83], v[206:209], v[238:241], v[80:83]
	v_mfma_f32_16x16x32_bf16 v[68:71], v[196:199], v[246:249], v[68:71]
	v_mfma_f32_16x16x32_bf16 v[64:67], v[206:209], v[246:249], v[64:67]
	s_barrier
	s_add_i32 s64, s0, s77
	s_add_u32 s98, s98, s14
	s_addc_u32 s99, s99, s15
	s_mov_b32 m0, s64
	ds_read_b128 v[216:219], v200 offset:49152
	ds_read_b128 v[220:223], v200 offset:50176
	ds_read_b128 v[224:227], v200 offset:51200
	ds_read_b128 v[228:231], v200 offset:52224
	ds_read_b128 v[234:237], v200 offset:53248
	ds_read_b128 v[238:241], v200 offset:54272
	ds_read_b128 v[242:245], v200 offset:55296
	ds_read_b128 v[246:249], v200 offset:56320
	global_load_lds_dwordx4 v136, s[98:99]
	s_add_i32 m0, s64, 0x2000
	s_add_u32 s48, s48, 0x40080
	s_addc_u32 s49, s49, 0
	s_add_i32 s64, s85, s77
	global_load_lds_dwordx4 v140, s[98:99]
	s_mov_b32 m0, s64
	s_nop 0
	global_load_lds_dwordx4 v136, s[48:49]
	s_add_i32 m0, s64, 0x2000
	s_nop 0
	global_load_lds_dwordx4 v140, s[48:49]
	s_add_u32 s100, s100, s14
	s_addc_u32 s101, s101, s15
	s_mov_b32 m0, s81
	s_nop 0
	global_load_lds_dwordx4 v134, s[100:101]
	s_mov_b32 m0, s82
	s_nop 0
	global_load_lds_dwordx4 v138, s[100:101]
	s_waitcnt vmcnt(8)
	s_waitcnt lgkmcnt(0)
	s_barrier
	s_waitcnt lgkmcnt(0)
	v_mfma_f32_16x16x32_bf16 v[60:63], v[174:177], v[216:219], v[60:63]
	v_mfma_f32_16x16x32_bf16 v[56:59], v[184:187], v[216:219], v[56:59]
	v_mfma_f32_16x16x32_bf16 v[44:47], v[174:177], v[224:227], v[44:47]
	v_mfma_f32_16x16x32_bf16 v[40:43], v[184:187], v[224:227], v[40:43]
	v_mfma_f32_16x16x32_bf16 v[28:31], v[174:177], v[234:237], v[28:31]
	v_mfma_f32_16x16x32_bf16 v[24:27], v[184:187], v[234:237], v[24:27]
	v_mfma_f32_16x16x32_bf16 v[12:15], v[174:177], v[242:245], v[12:15]
	v_mfma_f32_16x16x32_bf16 v[8:11], v[184:187], v[242:245], v[8:11]
	v_mfma_f32_16x16x32_bf16 v[60:63], v[180:183], v[220:223], v[60:63]
	v_mfma_f32_16x16x32_bf16 v[56:59], v[188:191], v[220:223], v[56:59]
	v_mfma_f32_16x16x32_bf16 v[44:47], v[180:183], v[228:231], v[44:47]
	v_mfma_f32_16x16x32_bf16 v[40:43], v[188:191], v[228:231], v[40:43]
	v_mfma_f32_16x16x32_bf16 v[28:31], v[180:183], v[238:241], v[28:31]
	v_mfma_f32_16x16x32_bf16 v[24:27], v[188:191], v[238:241], v[24:27]
	v_mfma_f32_16x16x32_bf16 v[12:15], v[180:183], v[246:249], v[12:15]
	v_mfma_f32_16x16x32_bf16 v[8:11], v[188:191], v[246:249], v[8:11]
	v_mfma_f32_16x16x32_bf16 v[52:55], v[192:195], v[216:219], v[52:55]
	v_mfma_f32_16x16x32_bf16 v[48:51], v[202:205], v[216:219], v[48:51]
	v_mfma_f32_16x16x32_bf16 v[36:39], v[192:195], v[224:227], v[36:39]
	v_mfma_f32_16x16x32_bf16 v[32:35], v[202:205], v[224:227], v[32:35]
	v_mfma_f32_16x16x32_bf16 v[20:23], v[192:195], v[234:237], v[20:23]
	v_mfma_f32_16x16x32_bf16 v[16:19], v[202:205], v[234:237], v[16:19]
	v_mfma_f32_16x16x32_bf16 v[4:7], v[192:195], v[242:245], v[4:7]
	v_mfma_f32_16x16x32_bf16 v[0:3], v[202:205], v[242:245], v[0:3]
	v_mfma_f32_16x16x32_bf16 v[52:55], v[196:199], v[220:223], v[52:55]
	v_mfma_f32_16x16x32_bf16 v[48:51], v[206:209], v[220:223], v[48:51]
	v_mfma_f32_16x16x32_bf16 v[36:39], v[196:199], v[228:231], v[36:39]
	v_mfma_f32_16x16x32_bf16 v[32:35], v[206:209], v[228:231], v[32:35]
	v_mfma_f32_16x16x32_bf16 v[20:23], v[196:199], v[238:241], v[20:23]
	v_mfma_f32_16x16x32_bf16 v[16:19], v[206:209], v[238:241], v[16:19]
	v_mfma_f32_16x16x32_bf16 v[4:7], v[196:199], v[246:249], v[4:7]
	v_mfma_f32_16x16x32_bf16 v[0:3], v[206:209], v[246:249], v[0:3]
	s_barrier
	s_add_i32 s71, s71, 2
	s_add_u32 s8, s8, 0x100
	s_addc_u32 s9, s9, 0
	s_add_u32 s69, s69, 0x100
	s_addc_u32 s70, s70, 0
	s_cmp_gt_u32 s71, 13
	s_cbranch_scc0 .LBB0_2108
	s_and_b64 vcc, exec, s[54:55]
	s_cbranch_vccz .LBB0_2111
	s_barrier

.LBB0_2189:
	s_add_u32 s68, s48, 0xfffe0080
	s_addc_u32 s69, s49, -1
	s_add_i32 s78, 0, 0x10000
	s_cmp_eq_u32 vcc_lo, 4
	s_cselect_b32 s73, s1, s69
	s_cselect_b32 s72, s7, s68
	s_cselect_b32 s69, s61, s75
	s_cselect_b32 s68, s63, s74
	s_add_i32 vcc_hi, 0, 0x14000
	v_add_u32_e32 v140, s78, v225
	v_add_u32_e32 v144, vcc_hi, v225
	ds_read_b128 v[128:131], v140
	ds_read_b128 v[132:135], v140 offset:1024
	ds_read_b128 v[136:139], v140 offset:2048
	ds_read_b128 v[140:143], v140 offset:3072
	ds_read_b128 v[172:175], v144
	ds_read_b128 v[176:179], v144 offset:1024
	ds_read_b128 v[180:183], v144 offset:2048
	ds_read_b128 v[184:187], v144 offset:3072
	s_add_i32 m0, s18, 0xc000
	ds_read_b128 v[188:191], v228
	ds_read_b128 v[192:195], v228 offset:1024
	ds_read_b128 v[196:199], v228 offset:2048
	ds_read_b128 v[200:203], v228 offset:3072
	ds_read_b128 v[204:207], v228 offset:4096
	ds_read_b128 v[208:211], v228 offset:5120
	ds_read_b128 v[234:237], v228 offset:6144
	ds_read_b128 v[238:241], v228 offset:7168
	global_load_lds_dwordx4 v166, s[48:49]
	s_add_i32 m0, s18, 0xe000
	s_nop 0
	global_load_lds_dwordx4 v168, s[48:49]
	s_waitcnt vmcnt(8)
	s_waitcnt lgkmcnt(0)
	s_barrier
	s_waitcnt lgkmcnt(0)
	v_mfma_i32_16x16x64_i8 v[124:127], v[128:131], v[188:191], v[124:127]
	v_mfma_i32_16x16x64_i8 v[120:123], v[136:139], v[188:191], v[120:123]
	v_mfma_i32_16x16x64_i8 v[116:119], v[128:131], v[196:199], v[116:119]
	v_mfma_i32_16x16x64_i8 v[112:115], v[136:139], v[196:199], v[112:115]
	v_mfma_i32_16x16x64_i8 v[108:111], v[128:131], v[204:207], v[108:111]
	v_mfma_i32_16x16x64_i8 v[104:107], v[136:139], v[204:207], v[104:107]
	v_mfma_i32_16x16x64_i8 v[100:103], v[128:131], v[234:237], v[100:103]
	v_mfma_i32_16x16x64_i8 v[96:99], v[136:139], v[234:237], v[96:99]
	v_mfma_i32_16x16x64_i8 v[124:127], v[132:135], v[192:195], v[124:127]
	v_mfma_i32_16x16x64_i8 v[120:123], v[140:143], v[192:195], v[120:123]
	v_mfma_i32_16x16x64_i8 v[116:119], v[132:135], v[200:203], v[116:119]
	v_mfma_i32_16x16x64_i8 v[112:115], v[140:143], v[200:203], v[112:115]
	v_mfma_i32_16x16x64_i8 v[108:111], v[132:135], v[208:211], v[108:111]
	v_mfma_i32_16x16x64_i8 v[104:107], v[140:143], v[208:211], v[104:107]
	v_mfma_i32_16x16x64_i8 v[100:103], v[132:135], v[238:241], v[100:103]
	v_mfma_i32_16x16x64_i8 v[96:99], v[140:143], v[238:241], v[96:99]
	v_mfma_i32_16x16x64_i8 v[92:95], v[172:175], v[188:191], v[92:95]
	v_mfma_i32_16x16x64_i8 v[88:91], v[180:183], v[188:191], v[88:91]
	v_mfma_i32_16x16x64_i8 v[84:87], v[172:175], v[196:199], v[84:87]
	v_mfma_i32_16x16x64_i8 v[80:83], v[180:183], v[196:199], v[80:83]
	v_mfma_i32_16x16x64_i8 v[76:79], v[172:175], v[204:207], v[76:79]
	v_mfma_i32_16x16x64_i8 v[72:75], v[180:183], v[204:207], v[72:75]
	v_mfma_i32_16x16x64_i8 v[68:71], v[172:175], v[234:237], v[68:71]
	v_mfma_i32_16x16x64_i8 v[64:67], v[180:183], v[234:237], v[64:67]
	v_mfma_i32_16x16x64_i8 v[92:95], v[176:179], v[192:195], v[92:95]
	v_mfma_i32_16x16x64_i8 v[88:91], v[184:187], v[192:195], v[88:91]
	v_mfma_i32_16x16x64_i8 v[84:87], v[176:179], v[200:203], v[84:87]
	v_mfma_i32_16x16x64_i8 v[80:83], v[184:187], v[200:203], v[80:83]
	v_mfma_i32_16x16x64_i8 v[76:79], v[176:179], v[208:211], v[76:79]
	v_mfma_i32_16x16x64_i8 v[72:75], v[184:187], v[208:211], v[72:75]
	v_mfma_i32_16x16x64_i8 v[68:71], v[176:179], v[238:241], v[68:71]
	v_mfma_i32_16x16x64_i8 v[64:67], v[184:187], v[238:241], v[64:67]
	s_barrier
	s_add_i32 s78, s78, s11
	s_mov_b64 s[98:99], s[68:69]
	s_mov_b32 m0, s78
	ds_read_b128 v[188:191], v228 offset:16384
	ds_read_b128 v[192:195], v228 offset:17408
	ds_read_b128 v[196:199], v228 offset:18432
	ds_read_b128 v[200:203], v228 offset:19456
	ds_read_b128 v[204:207], v228 offset:20480
	ds_read_b128 v[208:211], v228 offset:21504
	ds_read_b128 v[234:237], v228 offset:22528
	ds_read_b128 v[238:241], v228 offset:23552
	global_load_lds_dwordx4 v152, s[68:69]
	s_add_i32 m0, s78, 0x2000
	s_add_u32 s78, s68, 0x20000
	s_addc_u32 s79, s69, 0
	s_add_i32 vcc_hi, vcc_hi, s11
	global_load_lds_dwordx4 v156, s[68:69]
	s_mov_b32 m0, vcc_hi
	s_mov_b64 s[100:101], s[72:73]
	global_load_lds_dwordx4 v152, s[78:79]
	s_add_i32 m0, vcc_hi, 0x2000
	s_nop 0
	global_load_lds_dwordx4 v156, s[78:79]
	s_mov_b32 m0, s18
	s_nop 0
	global_load_lds_dwordx4 v150, s[72:73]
	s_mov_b32 m0, s19
	s_nop 0
	global_load_lds_dwordx4 v154, s[72:73]
	s_waitcnt vmcnt(8)
	s_waitcnt lgkmcnt(0)
	s_barrier
	s_waitcnt lgkmcnt(0)
	v_mfma_i32_16x16x64_i8 v[60:63], v[128:131], v[188:191], v[60:63]
	v_mfma_i32_16x16x64_i8 v[56:59], v[136:139], v[188:191], v[56:59]
	v_mfma_i32_16x16x64_i8 v[52:55], v[128:131], v[196:199], v[52:55]
	v_mfma_i32_16x16x64_i8 v[48:51], v[136:139], v[196:199], v[48:51]
	v_mfma_i32_16x16x64_i8 v[44:47], v[128:131], v[204:207], v[44:47]
	v_mfma_i32_16x16x64_i8 v[40:43], v[136:139], v[204:207], v[40:43]
	v_mfma_i32_16x16x64_i8 v[36:39], v[128:131], v[234:237], v[36:39]
	v_mfma_i32_16x16x64_i8 v[32:35], v[136:139], v[234:237], v[32:35]
	v_mfma_i32_16x16x64_i8 v[60:63], v[132:135], v[192:195], v[60:63]
	v_mfma_i32_16x16x64_i8 v[56:59], v[140:143], v[192:195], v[56:59]
	v_mfma_i32_16x16x64_i8 v[52:55], v[132:135], v[200:203], v[52:55]
	v_mfma_i32_16x16x64_i8 v[48:51], v[140:143], v[200:203], v[48:51]
	v_mfma_i32_16x16x64_i8 v[44:47], v[132:135], v[208:211], v[44:47]
	v_mfma_i32_16x16x64_i8 v[40:43], v[140:143], v[208:211], v[40:43]
	v_mfma_i32_16x16x64_i8 v[36:39], v[132:135], v[238:241], v[36:39]
	v_mfma_i32_16x16x64_i8 v[32:35], v[140:143], v[238:241], v[32:35]
	v_mfma_i32_16x16x64_i8 v[28:31], v[172:175], v[188:191], v[28:31]
	v_mfma_i32_16x16x64_i8 v[24:27], v[180:183], v[188:191], v[24:27]
	v_mfma_i32_16x16x64_i8 v[20:23], v[172:175], v[196:199], v[20:23]
	v_mfma_i32_16x16x64_i8 v[16:19], v[180:183], v[196:199], v[16:19]
	v_mfma_i32_16x16x64_i8 v[12:15], v[172:175], v[204:207], v[12:15]
	v_mfma_i32_16x16x64_i8 v[8:11], v[180:183], v[204:207], v[8:11]
	v_mfma_i32_16x16x64_i8 v[4:7], v[172:175], v[234:237], v[4:7]
	v_mfma_i32_16x16x64_i8 v[0:3], v[180:183], v[234:237], v[0:3]
	v_mfma_i32_16x16x64_i8 v[28:31], v[176:179], v[192:195], v[28:31]
	v_mfma_i32_16x16x64_i8 v[24:27], v[184:187], v[192:195], v[24:27]
	v_mfma_i32_16x16x64_i8 v[20:23], v[176:179], v[200:203], v[20:23]
	v_mfma_i32_16x16x64_i8 v[16:19], v[184:187], v[200:203], v[16:19]
	v_mfma_i32_16x16x64_i8 v[12:15], v[176:179], v[208:211], v[12:15]
	v_mfma_i32_16x16x64_i8 v[8:11], v[184:187], v[208:211], v[8:11]
	v_mfma_i32_16x16x64_i8 v[4:7], v[176:179], v[238:241], v[4:7]
	v_mfma_i32_16x16x64_i8 v[0:3], v[184:187], v[238:241], v[0:3]
	s_barrier
	s_add_i32 s78, 0, 0x1c000
	v_add_u32_e32 v140, s0, v225
	v_add_u32_e32 v144, s78, v225
	ds_read_b128 v[128:131], v140
	ds_read_b128 v[132:135], v140 offset:1024
	ds_read_b128 v[136:139], v140 offset:2048
	ds_read_b128 v[140:143], v140 offset:3072
	ds_read_b128 v[172:175], v144
	ds_read_b128 v[176:179], v144 offset:1024
	ds_read_b128 v[180:183], v144 offset:2048
	ds_read_b128 v[184:187], v144 offset:3072
	s_add_u32 s72, s72, 0x20000
	s_addc_u32 s73, s73, 0
	s_mov_b32 m0, s20
	ds_read_b128 v[188:191], v228 offset:32768
	ds_read_b128 v[192:195], v228 offset:33792
	ds_read_b128 v[196:199], v228 offset:34816
	ds_read_b128 v[200:203], v228 offset:35840
	ds_read_b128 v[204:207], v228 offset:36864
	ds_read_b128 v[208:211], v228 offset:37888
	ds_read_b128 v[234:237], v228 offset:38912
	ds_read_b128 v[238:241], v228 offset:39936
	global_load_lds_dwordx4 v150, s[72:73]
	s_mov_b32 m0, s21
	s_nop 0
	global_load_lds_dwordx4 v154, s[72:73]
	s_waitcnt vmcnt(8)
	s_waitcnt lgkmcnt(0)
	s_barrier
	s_waitcnt lgkmcnt(0)
	v_mfma_i32_16x16x64_i8 v[124:127], v[128:131], v[188:191], v[124:127]
	v_mfma_i32_16x16x64_i8 v[120:123], v[136:139], v[188:191], v[120:123]
	v_mfma_i32_16x16x64_i8 v[116:119], v[128:131], v[196:199], v[116:119]
	v_mfma_i32_16x16x64_i8 v[112:115], v[136:139], v[196:199], v[112:115]
	v_mfma_i32_16x16x64_i8 v[108:111], v[128:131], v[204:207], v[108:111]
	v_mfma_i32_16x16x64_i8 v[104:107], v[136:139], v[204:207], v[104:107]
	v_mfma_i32_16x16x64_i8 v[100:103], v[128:131], v[234:237], v[100:103]
	v_mfma_i32_16x16x64_i8 v[96:99], v[136:139], v[234:237], v[96:99]
	v_mfma_i32_16x16x64_i8 v[124:127], v[132:135], v[192:195], v[124:127]
	v_mfma_i32_16x16x64_i8 v[120:123], v[140:143], v[192:195], v[120:123]
	v_mfma_i32_16x16x64_i8 v[116:119], v[132:135], v[200:203], v[116:119]
	v_mfma_i32_16x16x64_i8 v[112:115], v[140:143], v[200:203], v[112:115]
	v_mfma_i32_16x16x64_i8 v[108:111], v[132:135], v[208:211], v[108:111]
	v_mfma_i32_16x16x64_i8 v[104:107], v[140:143], v[208:211], v[104:107]
	v_mfma_i32_16x16x64_i8 v[100:103], v[132:135], v[238:241], v[100:103]
	v_mfma_i32_16x16x64_i8 v[96:99], v[140:143], v[238:241], v[96:99]
	v_mfma_i32_16x16x64_i8 v[92:95], v[172:175], v[188:191], v[92:95]
	v_mfma_i32_16x16x64_i8 v[88:91], v[180:183], v[188:191], v[88:91]
	v_mfma_i32_16x16x64_i8 v[84:87], v[172:175], v[196:199], v[84:87]
	v_mfma_i32_16x16x64_i8 v[80:83], v[180:183], v[196:199], v[80:83]
	v_mfma_i32_16x16x64_i8 v[76:79], v[172:175], v[204:207], v[76:79]
	v_mfma_i32_16x16x64_i8 v[72:75], v[180:183], v[204:207], v[72:75]
	v_mfma_i32_16x16x64_i8 v[68:71], v[172:175], v[234:237], v[68:71]
	v_mfma_i32_16x16x64_i8 v[64:67], v[180:183], v[234:237], v[64:67]
	v_mfma_i32_16x16x64_i8 v[92:95], v[176:179], v[192:195], v[92:95]
	v_mfma_i32_16x16x64_i8 v[88:91], v[184:187], v[192:195], v[88:91]
	v_mfma_i32_16x16x64_i8 v[84:87], v[176:179], v[200:203], v[84:87]
	v_mfma_i32_16x16x64_i8 v[80:83], v[184:187], v[200:203], v[80:83]
	v_mfma_i32_16x16x64_i8 v[76:79], v[176:179], v[208:211], v[76:79]
	v_mfma_i32_16x16x64_i8 v[72:75], v[184:187], v[208:211], v[72:75]
	v_mfma_i32_16x16x64_i8 v[68:71], v[176:179], v[238:241], v[68:71]
	v_mfma_i32_16x16x64_i8 v[64:67], v[184:187], v[238:241], v[64:67]
	s_barrier
	s_add_i32 s72, s0, s11
	s_add_u32 s98, s98, s24
	s_addc_u32 s99, s99, s25
	s_mov_b32 m0, s72
	ds_read_b128 v[188:191], v228 offset:49152
	ds_read_b128 v[192:195], v228 offset:50176
	ds_read_b128 v[196:199], v228 offset:51200
	ds_read_b128 v[200:203], v228 offset:52224
	ds_read_b128 v[204:207], v228 offset:53248
	ds_read_b128 v[208:211], v228 offset:54272
	ds_read_b128 v[234:237], v228 offset:55296
	ds_read_b128 v[238:241], v228 offset:56320
	global_load_lds_dwordx4 v152, s[98:99]
	s_add_i32 m0, s72, 0x2000
	s_add_u32 s68, s68, 0x20080
	s_addc_u32 s69, s69, 0
	s_add_i32 s72, s78, s11
	global_load_lds_dwordx4 v156, s[98:99]
	s_mov_b32 m0, s72
	s_nop 0
	global_load_lds_dwordx4 v152, s[68:69]
	s_add_i32 m0, s72, 0x2000
	s_nop 0
	global_load_lds_dwordx4 v156, s[68:69]
	s_add_u32 s100, s100, s24
	s_addc_u32 s101, s101, s25
	s_mov_b32 m0, s77
	s_nop 0
	global_load_lds_dwordx4 v150, s[100:101]
	s_mov_b32 m0, s84
	s_nop 0
	global_load_lds_dwordx4 v154, s[100:101]
	s_waitcnt vmcnt(8)
	s_waitcnt lgkmcnt(0)
	s_barrier
	s_waitcnt lgkmcnt(0)
	v_mfma_i32_16x16x64_i8 v[60:63], v[128:131], v[188:191], v[60:63]
	v_mfma_i32_16x16x64_i8 v[56:59], v[136:139], v[188:191], v[56:59]
	v_mfma_i32_16x16x64_i8 v[52:55], v[128:131], v[196:199], v[52:55]
	v_mfma_i32_16x16x64_i8 v[48:51], v[136:139], v[196:199], v[48:51]
	v_mfma_i32_16x16x64_i8 v[44:47], v[128:131], v[204:207], v[44:47]
	v_mfma_i32_16x16x64_i8 v[40:43], v[136:139], v[204:207], v[40:43]
	v_mfma_i32_16x16x64_i8 v[36:39], v[128:131], v[234:237], v[36:39]
	v_mfma_i32_16x16x64_i8 v[32:35], v[136:139], v[234:237], v[32:35]
	v_mfma_i32_16x16x64_i8 v[60:63], v[132:135], v[192:195], v[60:63]
	v_mfma_i32_16x16x64_i8 v[56:59], v[140:143], v[192:195], v[56:59]
	v_mfma_i32_16x16x64_i8 v[52:55], v[132:135], v[200:203], v[52:55]
	v_mfma_i32_16x16x64_i8 v[48:51], v[140:143], v[200:203], v[48:51]
	v_mfma_i32_16x16x64_i8 v[44:47], v[132:135], v[208:211], v[44:47]
	v_mfma_i32_16x16x64_i8 v[40:43], v[140:143], v[208:211], v[40:43]
	v_mfma_i32_16x16x64_i8 v[36:39], v[132:135], v[238:241], v[36:39]
	v_mfma_i32_16x16x64_i8 v[32:35], v[140:143], v[238:241], v[32:35]
	v_mfma_i32_16x16x64_i8 v[28:31], v[172:175], v[188:191], v[28:31]
	v_mfma_i32_16x16x64_i8 v[24:27], v[180:183], v[188:191], v[24:27]
	v_mfma_i32_16x16x64_i8 v[20:23], v[172:175], v[196:199], v[20:23]
	v_mfma_i32_16x16x64_i8 v[16:19], v[180:183], v[196:199], v[16:19]
	v_mfma_i32_16x16x64_i8 v[12:15], v[172:175], v[204:207], v[12:15]
	v_mfma_i32_16x16x64_i8 v[8:11], v[180:183], v[204:207], v[8:11]
	v_mfma_i32_16x16x64_i8 v[4:7], v[172:175], v[234:237], v[4:7]
	v_mfma_i32_16x16x64_i8 v[0:3], v[180:183], v[234:237], v[0:3]
	v_mfma_i32_16x16x64_i8 v[28:31], v[176:179], v[192:195], v[28:31]
	v_mfma_i32_16x16x64_i8 v[24:27], v[184:187], v[192:195], v[24:27]
	v_mfma_i32_16x16x64_i8 v[20:23], v[176:179], v[200:203], v[20:23]
	v_mfma_i32_16x16x64_i8 v[16:19], v[184:187], v[200:203], v[16:19]
	v_mfma_i32_16x16x64_i8 v[12:15], v[176:179], v[208:211], v[12:15]
	v_mfma_i32_16x16x64_i8 v[8:11], v[184:187], v[208:211], v[8:11]
	v_mfma_i32_16x16x64_i8 v[4:7], v[176:179], v[238:241], v[4:7]
	v_mfma_i32_16x16x64_i8 v[0:3], v[184:187], v[238:241], v[0:3]
	s_barrier
	s_add_i32 vcc_lo, vcc_lo, 2
	s_add_u32 s48, s48, 0x100
	s_addc_u32 s49, s49, 0
	s_add_u32 s74, s74, 0x100
	s_addc_u32 s75, s75, 0
	s_cmp_gt_u32 vcc_lo, 5
	s_cbranch_scc0 .LBB0_2189
	s_and_b64 vcc, exec, s[58:59]
	s_cbranch_vccz .LBB0_2192
	s_barrier

.LBB0_2520:
	s_add_u32 s48, s8, 0xfffc0080
	s_addc_u32 s49, s9, -1
	s_add_i32 s84, 0, 0x10000
	s_cmp_eq_u32 s67, 12
	s_cselect_b32 s61, s7, s49
	s_cselect_b32 s60, s55, s48
	v_add_u32_e32 v128, s84, v173
	s_cselect_b32 s49, s53, s66
	s_cselect_b32 s48, s64, s65
	s_add_i32 s88, 0, 0x14000
	ds_read_b128 v[174:177], v128
	ds_read_b128 v[180:183], v128 offset:1024
	ds_read_b128 v[184:187], v128 offset:2048
	ds_read_b128 v[188:191], v128 offset:3072
	v_add_u32_e32 v128, s88, v173
	ds_read_b128 v[192:195], v128
	ds_read_b128 v[196:199], v128 offset:1024
	ds_read_b128 v[204:207], v128 offset:2048
	ds_read_b128 v[208:211], v128 offset:3072
	s_add_i32 m0, s63, 0xc000
	ds_read_b128 v[212:215], v203
	ds_read_b128 v[216:219], v203 offset:1024
	ds_read_b128 v[220:223], v203 offset:2048
	ds_read_b128 v[224:227], v203 offset:3072
	ds_read_b128 v[228:231], v203 offset:4096
	ds_read_b128 v[234:237], v203 offset:5120
	ds_read_b128 v[238:241], v203 offset:6144
	ds_read_b128 v[242:245], v203 offset:7168
	global_load_lds_dwordx4 v148, s[8:9]
	s_add_i32 m0, s63, 0xe000
	s_nop 0
	global_load_lds_dwordx4 v150, s[8:9]
	s_waitcnt vmcnt(8)
	s_waitcnt lgkmcnt(0)
	s_barrier
	s_waitcnt lgkmcnt(0)
	v_mfma_f32_16x16x32_bf16 v[124:127], v[174:177], v[212:215], v[124:127]
	v_mfma_f32_16x16x32_bf16 v[120:123], v[184:187], v[212:215], v[120:123]
	v_mfma_f32_16x16x32_bf16 v[108:111], v[174:177], v[220:223], v[108:111]
	v_mfma_f32_16x16x32_bf16 v[104:107], v[184:187], v[220:223], v[104:107]
	v_mfma_f32_16x16x32_bf16 v[92:95], v[174:177], v[228:231], v[92:95]
	v_mfma_f32_16x16x32_bf16 v[88:91], v[184:187], v[228:231], v[88:91]
	v_mfma_f32_16x16x32_bf16 v[76:79], v[174:177], v[238:241], v[76:79]
	v_mfma_f32_16x16x32_bf16 v[72:75], v[184:187], v[238:241], v[72:75]
	v_mfma_f32_16x16x32_bf16 v[124:127], v[180:183], v[216:219], v[124:127]
	v_mfma_f32_16x16x32_bf16 v[120:123], v[188:191], v[216:219], v[120:123]
	v_mfma_f32_16x16x32_bf16 v[108:111], v[180:183], v[224:227], v[108:111]
	v_mfma_f32_16x16x32_bf16 v[104:107], v[188:191], v[224:227], v[104:107]
	v_mfma_f32_16x16x32_bf16 v[92:95], v[180:183], v[234:237], v[92:95]
	v_mfma_f32_16x16x32_bf16 v[88:91], v[188:191], v[234:237], v[88:91]
	v_mfma_f32_16x16x32_bf16 v[76:79], v[180:183], v[242:245], v[76:79]
	v_mfma_f32_16x16x32_bf16 v[72:75], v[188:191], v[242:245], v[72:75]
	v_mfma_f32_16x16x32_bf16 v[116:119], v[192:195], v[212:215], v[116:119]
	v_mfma_f32_16x16x32_bf16 v[112:115], v[204:207], v[212:215], v[112:115]
	v_mfma_f32_16x16x32_bf16 v[100:103], v[192:195], v[220:223], v[100:103]
	v_mfma_f32_16x16x32_bf16 v[96:99], v[204:207], v[220:223], v[96:99]
	v_mfma_f32_16x16x32_bf16 v[84:87], v[192:195], v[228:231], v[84:87]
	v_mfma_f32_16x16x32_bf16 v[80:83], v[204:207], v[228:231], v[80:83]
	v_mfma_f32_16x16x32_bf16 v[68:71], v[192:195], v[238:241], v[68:71]
	v_mfma_f32_16x16x32_bf16 v[64:67], v[204:207], v[238:241], v[64:67]
	v_mfma_f32_16x16x32_bf16 v[116:119], v[196:199], v[216:219], v[116:119]
	v_mfma_f32_16x16x32_bf16 v[112:115], v[208:211], v[216:219], v[112:115]
	v_mfma_f32_16x16x32_bf16 v[100:103], v[196:199], v[224:227], v[100:103]
	v_mfma_f32_16x16x32_bf16 v[96:99], v[208:211], v[224:227], v[96:99]
	v_mfma_f32_16x16x32_bf16 v[84:87], v[196:199], v[234:237], v[84:87]
	v_mfma_f32_16x16x32_bf16 v[80:83], v[208:211], v[234:237], v[80:83]
	v_mfma_f32_16x16x32_bf16 v[68:71], v[196:199], v[242:245], v[68:71]
	v_mfma_f32_16x16x32_bf16 v[64:67], v[208:211], v[242:245], v[64:67]
	s_barrier
	s_add_i32 s84, s84, s75
	s_mov_b64 s[98:99], s[48:49]
	s_mov_b32 m0, s84
	ds_read_b128 v[212:215], v203 offset:16384
	ds_read_b128 v[216:219], v203 offset:17408
	ds_read_b128 v[220:223], v203 offset:18432
	ds_read_b128 v[224:227], v203 offset:19456
	ds_read_b128 v[228:231], v203 offset:20480
	ds_read_b128 v[234:237], v203 offset:21504
	ds_read_b128 v[238:241], v203 offset:22528
	ds_read_b128 v[242:245], v203 offset:23552
	global_load_lds_dwordx4 v136, s[48:49]
	s_add_i32 m0, s84, 0x2000
	s_add_u32 s86, s48, 0x40000
	s_addc_u32 s87, s49, 0
	s_add_i32 s84, s88, s75
	global_load_lds_dwordx4 v140, s[48:49]
	s_mov_b32 m0, s84
	s_mov_b64 s[100:101], s[60:61]
	global_load_lds_dwordx4 v136, s[86:87]
	s_add_i32 m0, s84, 0x2000
	s_nop 0
	global_load_lds_dwordx4 v140, s[86:87]
	s_mov_b32 m0, s63
	s_nop 0
	global_load_lds_dwordx4 v134, s[60:61]
	s_mov_b32 m0, s76
	s_nop 0
	global_load_lds_dwordx4 v138, s[60:61]
	s_waitcnt vmcnt(8)
	s_waitcnt lgkmcnt(0)
	s_barrier
	s_waitcnt lgkmcnt(0)
	v_mfma_f32_16x16x32_bf16 v[60:63], v[174:177], v[212:215], v[60:63]
	v_mfma_f32_16x16x32_bf16 v[56:59], v[184:187], v[212:215], v[56:59]
	v_mfma_f32_16x16x32_bf16 v[44:47], v[174:177], v[220:223], v[44:47]
	v_mfma_f32_16x16x32_bf16 v[40:43], v[184:187], v[220:223], v[40:43]
	v_mfma_f32_16x16x32_bf16 v[28:31], v[174:177], v[228:231], v[28:31]
	v_mfma_f32_16x16x32_bf16 v[24:27], v[184:187], v[228:231], v[24:27]
	v_mfma_f32_16x16x32_bf16 v[12:15], v[174:177], v[238:241], v[12:15]
	v_mfma_f32_16x16x32_bf16 v[8:11], v[184:187], v[238:241], v[8:11]
	v_mfma_f32_16x16x32_bf16 v[60:63], v[180:183], v[216:219], v[60:63]
	v_mfma_f32_16x16x32_bf16 v[56:59], v[188:191], v[216:219], v[56:59]
	v_mfma_f32_16x16x32_bf16 v[44:47], v[180:183], v[224:227], v[44:47]
	v_mfma_f32_16x16x32_bf16 v[40:43], v[188:191], v[224:227], v[40:43]
	v_mfma_f32_16x16x32_bf16 v[28:31], v[180:183], v[234:237], v[28:31]
	v_mfma_f32_16x16x32_bf16 v[24:27], v[188:191], v[234:237], v[24:27]
	v_mfma_f32_16x16x32_bf16 v[12:15], v[180:183], v[242:245], v[12:15]
	v_mfma_f32_16x16x32_bf16 v[8:11], v[188:191], v[242:245], v[8:11]
	v_mfma_f32_16x16x32_bf16 v[52:55], v[192:195], v[212:215], v[52:55]
	v_mfma_f32_16x16x32_bf16 v[48:51], v[204:207], v[212:215], v[48:51]
	v_mfma_f32_16x16x32_bf16 v[36:39], v[192:195], v[220:223], v[36:39]
	v_mfma_f32_16x16x32_bf16 v[32:35], v[204:207], v[220:223], v[32:35]
	v_mfma_f32_16x16x32_bf16 v[20:23], v[192:195], v[228:231], v[20:23]
	v_mfma_f32_16x16x32_bf16 v[16:19], v[204:207], v[228:231], v[16:19]
	v_mfma_f32_16x16x32_bf16 v[4:7], v[192:195], v[238:241], v[4:7]
	v_mfma_f32_16x16x32_bf16 v[0:3], v[204:207], v[238:241], v[0:3]
	v_mfma_f32_16x16x32_bf16 v[52:55], v[196:199], v[216:219], v[52:55]
	v_mfma_f32_16x16x32_bf16 v[48:51], v[208:211], v[216:219], v[48:51]
	v_mfma_f32_16x16x32_bf16 v[36:39], v[196:199], v[224:227], v[36:39]
	v_mfma_f32_16x16x32_bf16 v[32:35], v[208:211], v[224:227], v[32:35]
	v_mfma_f32_16x16x32_bf16 v[20:23], v[196:199], v[234:237], v[20:23]
	v_mfma_f32_16x16x32_bf16 v[16:19], v[208:211], v[234:237], v[16:19]
	v_mfma_f32_16x16x32_bf16 v[4:7], v[196:199], v[242:245], v[4:7]
	v_mfma_f32_16x16x32_bf16 v[0:3], v[208:211], v[242:245], v[0:3]
	s_barrier
	v_add_u32_e32 v128, s0, v173
	s_add_i32 s84, 0, 0x1c000
	ds_read_b128 v[174:177], v128
	ds_read_b128 v[180:183], v128 offset:1024
	ds_read_b128 v[184:187], v128 offset:2048
	ds_read_b128 v[188:191], v128 offset:3072
	v_add_u32_e32 v128, s84, v173
	ds_read_b128 v[192:195], v128
	ds_read_b128 v[196:199], v128 offset:1024
	ds_read_b128 v[204:207], v128 offset:2048
	ds_read_b128 v[208:211], v128 offset:3072
	s_add_u32 s60, s60, 0x40000
	s_addc_u32 s61, s61, 0
	s_mov_b32 m0, s77
	ds_read_b128 v[212:215], v203 offset:32768
	ds_read_b128 v[216:219], v203 offset:33792
	ds_read_b128 v[220:223], v203 offset:34816
	ds_read_b128 v[224:227], v203 offset:35840
	ds_read_b128 v[228:231], v203 offset:36864
	ds_read_b128 v[234:237], v203 offset:37888
	ds_read_b128 v[238:241], v203 offset:38912
	ds_read_b128 v[242:245], v203 offset:39936
	global_load_lds_dwordx4 v134, s[60:61]
	s_mov_b32 m0, s78
	s_nop 0
	global_load_lds_dwordx4 v138, s[60:61]
	s_waitcnt vmcnt(8)
	s_waitcnt lgkmcnt(0)
	s_barrier
	s_waitcnt lgkmcnt(0)
	v_mfma_f32_16x16x32_bf16 v[124:127], v[174:177], v[212:215], v[124:127]
	v_mfma_f32_16x16x32_bf16 v[120:123], v[184:187], v[212:215], v[120:123]
	v_mfma_f32_16x16x32_bf16 v[108:111], v[174:177], v[220:223], v[108:111]
	v_mfma_f32_16x16x32_bf16 v[104:107], v[184:187], v[220:223], v[104:107]
	v_mfma_f32_16x16x32_bf16 v[92:95], v[174:177], v[228:231], v[92:95]
	v_mfma_f32_16x16x32_bf16 v[88:91], v[184:187], v[228:231], v[88:91]
	v_mfma_f32_16x16x32_bf16 v[76:79], v[174:177], v[238:241], v[76:79]
	v_mfma_f32_16x16x32_bf16 v[72:75], v[184:187], v[238:241], v[72:75]
	v_mfma_f32_16x16x32_bf16 v[124:127], v[180:183], v[216:219], v[124:127]
	v_mfma_f32_16x16x32_bf16 v[120:123], v[188:191], v[216:219], v[120:123]
	v_mfma_f32_16x16x32_bf16 v[108:111], v[180:183], v[224:227], v[108:111]
	v_mfma_f32_16x16x32_bf16 v[104:107], v[188:191], v[224:227], v[104:107]
	v_mfma_f32_16x16x32_bf16 v[92:95], v[180:183], v[234:237], v[92:95]
	v_mfma_f32_16x16x32_bf16 v[88:91], v[188:191], v[234:237], v[88:91]
	v_mfma_f32_16x16x32_bf16 v[76:79], v[180:183], v[242:245], v[76:79]
	v_mfma_f32_16x16x32_bf16 v[72:75], v[188:191], v[242:245], v[72:75]
	v_mfma_f32_16x16x32_bf16 v[116:119], v[192:195], v[212:215], v[116:119]
	v_mfma_f32_16x16x32_bf16 v[112:115], v[204:207], v[212:215], v[112:115]
	v_mfma_f32_16x16x32_bf16 v[100:103], v[192:195], v[220:223], v[100:103]
	v_mfma_f32_16x16x32_bf16 v[96:99], v[204:207], v[220:223], v[96:99]
	v_mfma_f32_16x16x32_bf16 v[84:87], v[192:195], v[228:231], v[84:87]
	v_mfma_f32_16x16x32_bf16 v[80:83], v[204:207], v[228:231], v[80:83]
	v_mfma_f32_16x16x32_bf16 v[68:71], v[192:195], v[238:241], v[68:71]
	v_mfma_f32_16x16x32_bf16 v[64:67], v[204:207], v[238:241], v[64:67]
	v_mfma_f32_16x16x32_bf16 v[116:119], v[196:199], v[216:219], v[116:119]
	v_mfma_f32_16x16x32_bf16 v[112:115], v[208:211], v[216:219], v[112:115]
	v_mfma_f32_16x16x32_bf16 v[100:103], v[196:199], v[224:227], v[100:103]
	v_mfma_f32_16x16x32_bf16 v[96:99], v[208:211], v[224:227], v[96:99]
	v_mfma_f32_16x16x32_bf16 v[84:87], v[196:199], v[234:237], v[84:87]
	v_mfma_f32_16x16x32_bf16 v[80:83], v[208:211], v[234:237], v[80:83]
	v_mfma_f32_16x16x32_bf16 v[68:71], v[196:199], v[242:245], v[68:71]
	v_mfma_f32_16x16x32_bf16 v[64:67], v[208:211], v[242:245], v[64:67]
	s_barrier
	s_add_i32 s60, s0, s75
	s_add_u32 s98, s98, s12
	s_addc_u32 s99, s99, s13
	s_mov_b32 m0, s60
	ds_read_b128 v[212:215], v203 offset:49152
	ds_read_b128 v[216:219], v203 offset:50176
	ds_read_b128 v[220:223], v203 offset:51200
	ds_read_b128 v[224:227], v203 offset:52224
	ds_read_b128 v[228:231], v203 offset:53248
	ds_read_b128 v[234:237], v203 offset:54272
	ds_read_b128 v[238:241], v203 offset:55296
	ds_read_b128 v[242:245], v203 offset:56320
	global_load_lds_dwordx4 v136, s[98:99]
	s_add_i32 m0, s60, 0x2000
	s_add_u32 s48, s48, 0x40080
	s_addc_u32 s49, s49, 0
	s_add_i32 s60, s84, s75
	global_load_lds_dwordx4 v140, s[98:99]
	s_mov_b32 m0, s60
	s_nop 0
	global_load_lds_dwordx4 v136, s[48:49]
	s_add_i32 m0, s60, 0x2000
	s_nop 0
	global_load_lds_dwordx4 v140, s[48:49]
	s_add_u32 s100, s100, s12
	s_addc_u32 s101, s101, s13
	s_mov_b32 m0, s79
	s_nop 0
	global_load_lds_dwordx4 v134, s[100:101]
	s_mov_b32 m0, s80
	s_nop 0
	global_load_lds_dwordx4 v138, s[100:101]
	s_waitcnt vmcnt(8)
	s_waitcnt lgkmcnt(0)
	s_barrier
	s_waitcnt lgkmcnt(0)
	v_mfma_f32_16x16x32_bf16 v[60:63], v[174:177], v[212:215], v[60:63]
	v_mfma_f32_16x16x32_bf16 v[56:59], v[184:187], v[212:215], v[56:59]
	v_mfma_f32_16x16x32_bf16 v[44:47], v[174:177], v[220:223], v[44:47]
	v_mfma_f32_16x16x32_bf16 v[40:43], v[184:187], v[220:223], v[40:43]
	v_mfma_f32_16x16x32_bf16 v[28:31], v[174:177], v[228:231], v[28:31]
	v_mfma_f32_16x16x32_bf16 v[24:27], v[184:187], v[228:231], v[24:27]
	v_mfma_f32_16x16x32_bf16 v[12:15], v[174:177], v[238:241], v[12:15]
	v_mfma_f32_16x16x32_bf16 v[8:11], v[184:187], v[238:241], v[8:11]
	v_mfma_f32_16x16x32_bf16 v[60:63], v[180:183], v[216:219], v[60:63]
	v_mfma_f32_16x16x32_bf16 v[56:59], v[188:191], v[216:219], v[56:59]
	v_mfma_f32_16x16x32_bf16 v[44:47], v[180:183], v[224:227], v[44:47]
	v_mfma_f32_16x16x32_bf16 v[40:43], v[188:191], v[224:227], v[40:43]
	v_mfma_f32_16x16x32_bf16 v[28:31], v[180:183], v[234:237], v[28:31]
	v_mfma_f32_16x16x32_bf16 v[24:27], v[188:191], v[234:237], v[24:27]
	v_mfma_f32_16x16x32_bf16 v[12:15], v[180:183], v[242:245], v[12:15]
	v_mfma_f32_16x16x32_bf16 v[8:11], v[188:191], v[242:245], v[8:11]
	v_mfma_f32_16x16x32_bf16 v[52:55], v[192:195], v[212:215], v[52:55]
	v_mfma_f32_16x16x32_bf16 v[48:51], v[204:207], v[212:215], v[48:51]
	v_mfma_f32_16x16x32_bf16 v[36:39], v[192:195], v[220:223], v[36:39]
	v_mfma_f32_16x16x32_bf16 v[32:35], v[204:207], v[220:223], v[32:35]
	v_mfma_f32_16x16x32_bf16 v[20:23], v[192:195], v[228:231], v[20:23]
	v_mfma_f32_16x16x32_bf16 v[16:19], v[204:207], v[228:231], v[16:19]
	v_mfma_f32_16x16x32_bf16 v[4:7], v[192:195], v[238:241], v[4:7]
	v_mfma_f32_16x16x32_bf16 v[0:3], v[204:207], v[238:241], v[0:3]
	v_mfma_f32_16x16x32_bf16 v[52:55], v[196:199], v[216:219], v[52:55]
	v_mfma_f32_16x16x32_bf16 v[48:51], v[208:211], v[216:219], v[48:51]
	v_mfma_f32_16x16x32_bf16 v[36:39], v[196:199], v[224:227], v[36:39]
	v_mfma_f32_16x16x32_bf16 v[32:35], v[208:211], v[224:227], v[32:35]
	v_mfma_f32_16x16x32_bf16 v[20:23], v[196:199], v[234:237], v[20:23]
	v_mfma_f32_16x16x32_bf16 v[16:19], v[208:211], v[234:237], v[16:19]
	v_mfma_f32_16x16x32_bf16 v[4:7], v[196:199], v[242:245], v[4:7]
	v_mfma_f32_16x16x32_bf16 v[0:3], v[208:211], v[242:245], v[0:3]
	s_barrier
	s_add_i32 s67, s67, 2
	s_add_u32 s8, s8, 0x100
	s_addc_u32 s9, s9, 0
	s_add_u32 s65, s65, 0x100
	s_addc_u32 s66, s66, 0
	s_cmp_gt_u32 s67, 13
	s_cbranch_scc0 .LBB0_2520
	s_and_b64 vcc, exec, s[50:51]
	s_cbranch_vccz .LBB0_2523
	s_barrier

.LBB0_2602:
	s_add_u32 s56, s48, 0xfffe0080
	s_addc_u32 s57, s49, -1
	s_add_i32 s87, 0, 0x10000
	s_cmp_eq_u32 s86, 4
	s_cselect_b32 s61, s7, s57
	s_cselect_b32 s60, s51, s56
	s_cselect_b32 s57, s45, s85
	s_cselect_b32 s56, s62, s63
	s_add_i32 s90, 0, 0x14000
	v_add_u32_e32 v140, s87, v203
	v_add_u32_e32 v144, s90, v203
	ds_read_b128 v[128:131], v140
	ds_read_b128 v[132:135], v140 offset:1024
	ds_read_b128 v[136:139], v140 offset:2048
	ds_read_b128 v[140:143], v140 offset:3072
	ds_read_b128 v[172:175], v144
	ds_read_b128 v[176:179], v144 offset:1024
	ds_read_b128 v[180:183], v144 offset:2048
	ds_read_b128 v[184:187], v144 offset:3072
	s_add_i32 m0, s76, 0xc000
	ds_read_b128 v[188:191], v206
	ds_read_b128 v[208:211], v206 offset:1024
	ds_read_b128 v[212:215], v206 offset:2048
	ds_read_b128 v[216:219], v206 offset:3072
	ds_read_b128 v[220:223], v206 offset:4096
	ds_read_b128 v[224:227], v206 offset:5120
	ds_read_b128 v[228:231], v206 offset:6144
	ds_read_b128 v[234:237], v206 offset:7168
	global_load_lds_dwordx4 v166, s[48:49]
	s_add_i32 m0, s76, 0xe000
	s_nop 0
	global_load_lds_dwordx4 v168, s[48:49]
	s_waitcnt vmcnt(8)
	s_waitcnt lgkmcnt(0)
	s_barrier
	s_waitcnt lgkmcnt(0)
	v_mfma_i32_16x16x64_i8 v[124:127], v[128:131], v[188:191], v[124:127]
	v_mfma_i32_16x16x64_i8 v[120:123], v[136:139], v[188:191], v[120:123]
	v_mfma_i32_16x16x64_i8 v[116:119], v[128:131], v[212:215], v[116:119]
	v_mfma_i32_16x16x64_i8 v[112:115], v[136:139], v[212:215], v[112:115]
	v_mfma_i32_16x16x64_i8 v[108:111], v[128:131], v[220:223], v[108:111]
	v_mfma_i32_16x16x64_i8 v[104:107], v[136:139], v[220:223], v[104:107]
	v_mfma_i32_16x16x64_i8 v[100:103], v[128:131], v[228:231], v[100:103]
	v_mfma_i32_16x16x64_i8 v[96:99], v[136:139], v[228:231], v[96:99]
	v_mfma_i32_16x16x64_i8 v[124:127], v[132:135], v[208:211], v[124:127]
	v_mfma_i32_16x16x64_i8 v[120:123], v[140:143], v[208:211], v[120:123]
	v_mfma_i32_16x16x64_i8 v[116:119], v[132:135], v[216:219], v[116:119]
	v_mfma_i32_16x16x64_i8 v[112:115], v[140:143], v[216:219], v[112:115]
	v_mfma_i32_16x16x64_i8 v[108:111], v[132:135], v[224:227], v[108:111]
	v_mfma_i32_16x16x64_i8 v[104:107], v[140:143], v[224:227], v[104:107]
	v_mfma_i32_16x16x64_i8 v[100:103], v[132:135], v[234:237], v[100:103]
	v_mfma_i32_16x16x64_i8 v[96:99], v[140:143], v[234:237], v[96:99]
	v_mfma_i32_16x16x64_i8 v[92:95], v[172:175], v[188:191], v[92:95]
	v_mfma_i32_16x16x64_i8 v[88:91], v[180:183], v[188:191], v[88:91]
	v_mfma_i32_16x16x64_i8 v[84:87], v[172:175], v[212:215], v[84:87]
	v_mfma_i32_16x16x64_i8 v[80:83], v[180:183], v[212:215], v[80:83]
	v_mfma_i32_16x16x64_i8 v[76:79], v[172:175], v[220:223], v[76:79]
	v_mfma_i32_16x16x64_i8 v[72:75], v[180:183], v[220:223], v[72:75]
	v_mfma_i32_16x16x64_i8 v[68:71], v[172:175], v[228:231], v[68:71]
	v_mfma_i32_16x16x64_i8 v[64:67], v[180:183], v[228:231], v[64:67]
	v_mfma_i32_16x16x64_i8 v[92:95], v[176:179], v[208:211], v[92:95]
	v_mfma_i32_16x16x64_i8 v[88:91], v[184:187], v[208:211], v[88:91]
	v_mfma_i32_16x16x64_i8 v[84:87], v[176:179], v[216:219], v[84:87]
	v_mfma_i32_16x16x64_i8 v[80:83], v[184:187], v[216:219], v[80:83]
	v_mfma_i32_16x16x64_i8 v[76:79], v[176:179], v[224:227], v[76:79]
	v_mfma_i32_16x16x64_i8 v[72:75], v[184:187], v[224:227], v[72:75]
	v_mfma_i32_16x16x64_i8 v[68:71], v[176:179], v[234:237], v[68:71]
	v_mfma_i32_16x16x64_i8 v[64:67], v[184:187], v[234:237], v[64:67]
	s_barrier
	s_add_i32 s87, s87, s75
	s_mov_b64 s[98:99], s[56:57]
	s_mov_b32 m0, s87
	ds_read_b128 v[188:191], v206 offset:16384
	ds_read_b128 v[208:211], v206 offset:17408
	ds_read_b128 v[212:215], v206 offset:18432
	ds_read_b128 v[216:219], v206 offset:19456
	ds_read_b128 v[220:223], v206 offset:20480
	ds_read_b128 v[224:227], v206 offset:21504
	ds_read_b128 v[228:231], v206 offset:22528
	ds_read_b128 v[234:237], v206 offset:23552
	global_load_lds_dwordx4 v152, s[56:57]
	s_add_i32 m0, s87, 0x2000
	s_add_u32 s88, s56, 0x20000
	s_addc_u32 s89, s57, 0
	s_add_i32 s87, s90, s75
	global_load_lds_dwordx4 v156, s[56:57]
	s_mov_b32 m0, s87
	s_mov_b64 s[100:101], s[60:61]
	global_load_lds_dwordx4 v152, s[88:89]
	s_add_i32 m0, s87, 0x2000
	s_nop 0
	global_load_lds_dwordx4 v156, s[88:89]
	s_mov_b32 m0, s76
	s_nop 0
	global_load_lds_dwordx4 v150, s[60:61]
	s_mov_b32 m0, s77
	s_nop 0
	global_load_lds_dwordx4 v154, s[60:61]
	s_waitcnt vmcnt(8)
	s_waitcnt lgkmcnt(0)
	s_barrier
	s_waitcnt lgkmcnt(0)
	v_mfma_i32_16x16x64_i8 v[60:63], v[128:131], v[188:191], v[60:63]
	v_mfma_i32_16x16x64_i8 v[56:59], v[136:139], v[188:191], v[56:59]
	v_mfma_i32_16x16x64_i8 v[52:55], v[128:131], v[212:215], v[52:55]
	v_mfma_i32_16x16x64_i8 v[48:51], v[136:139], v[212:215], v[48:51]
	v_mfma_i32_16x16x64_i8 v[44:47], v[128:131], v[220:223], v[44:47]
	v_mfma_i32_16x16x64_i8 v[40:43], v[136:139], v[220:223], v[40:43]
	v_mfma_i32_16x16x64_i8 v[36:39], v[128:131], v[228:231], v[36:39]
	v_mfma_i32_16x16x64_i8 v[32:35], v[136:139], v[228:231], v[32:35]
	v_mfma_i32_16x16x64_i8 v[60:63], v[132:135], v[208:211], v[60:63]
	v_mfma_i32_16x16x64_i8 v[56:59], v[140:143], v[208:211], v[56:59]
	v_mfma_i32_16x16x64_i8 v[52:55], v[132:135], v[216:219], v[52:55]
	v_mfma_i32_16x16x64_i8 v[48:51], v[140:143], v[216:219], v[48:51]
	v_mfma_i32_16x16x64_i8 v[44:47], v[132:135], v[224:227], v[44:47]
	v_mfma_i32_16x16x64_i8 v[40:43], v[140:143], v[224:227], v[40:43]
	v_mfma_i32_16x16x64_i8 v[36:39], v[132:135], v[234:237], v[36:39]
	v_mfma_i32_16x16x64_i8 v[32:35], v[140:143], v[234:237], v[32:35]
	v_mfma_i32_16x16x64_i8 v[28:31], v[172:175], v[188:191], v[28:31]
	v_mfma_i32_16x16x64_i8 v[24:27], v[180:183], v[188:191], v[24:27]
	v_mfma_i32_16x16x64_i8 v[20:23], v[172:175], v[212:215], v[20:23]
	v_mfma_i32_16x16x64_i8 v[16:19], v[180:183], v[212:215], v[16:19]
	v_mfma_i32_16x16x64_i8 v[12:15], v[172:175], v[220:223], v[12:15]
	v_mfma_i32_16x16x64_i8 v[8:11], v[180:183], v[220:223], v[8:11]
	v_mfma_i32_16x16x64_i8 v[4:7], v[172:175], v[228:231], v[4:7]
	v_mfma_i32_16x16x64_i8 v[0:3], v[180:183], v[228:231], v[0:3]
	v_mfma_i32_16x16x64_i8 v[28:31], v[176:179], v[208:211], v[28:31]
	v_mfma_i32_16x16x64_i8 v[24:27], v[184:187], v[208:211], v[24:27]
	v_mfma_i32_16x16x64_i8 v[20:23], v[176:179], v[216:219], v[20:23]
	v_mfma_i32_16x16x64_i8 v[16:19], v[184:187], v[216:219], v[16:19]
	v_mfma_i32_16x16x64_i8 v[12:15], v[176:179], v[224:227], v[12:15]
	v_mfma_i32_16x16x64_i8 v[8:11], v[184:187], v[224:227], v[8:11]
	v_mfma_i32_16x16x64_i8 v[4:7], v[176:179], v[234:237], v[4:7]
	v_mfma_i32_16x16x64_i8 v[0:3], v[184:187], v[234:237], v[0:3]
	s_barrier
	s_add_i32 s87, 0, 0x1c000
	v_add_u32_e32 v140, s0, v203
	v_add_u32_e32 v144, s87, v203
	ds_read_b128 v[128:131], v140
	ds_read_b128 v[132:135], v140 offset:1024
	ds_read_b128 v[136:139], v140 offset:2048
	ds_read_b128 v[140:143], v140 offset:3072
	ds_read_b128 v[172:175], v144
	ds_read_b128 v[176:179], v144 offset:1024
	ds_read_b128 v[180:183], v144 offset:2048
	ds_read_b128 v[184:187], v144 offset:3072
	s_add_u32 s60, s60, 0x20000
	s_addc_u32 s61, s61, 0
	s_mov_b32 m0, s78
	ds_read_b128 v[188:191], v206 offset:32768
	ds_read_b128 v[208:211], v206 offset:33792
	ds_read_b128 v[212:215], v206 offset:34816
	ds_read_b128 v[216:219], v206 offset:35840
	ds_read_b128 v[220:223], v206 offset:36864
	ds_read_b128 v[224:227], v206 offset:37888
	ds_read_b128 v[228:231], v206 offset:38912
	ds_read_b128 v[234:237], v206 offset:39936
	global_load_lds_dwordx4 v150, s[60:61]
	s_mov_b32 m0, s79
	s_nop 0
	global_load_lds_dwordx4 v154, s[60:61]
	s_waitcnt vmcnt(8)
	s_waitcnt lgkmcnt(0)
	s_barrier
	s_waitcnt lgkmcnt(0)
	v_mfma_i32_16x16x64_i8 v[124:127], v[128:131], v[188:191], v[124:127]
	v_mfma_i32_16x16x64_i8 v[120:123], v[136:139], v[188:191], v[120:123]
	v_mfma_i32_16x16x64_i8 v[116:119], v[128:131], v[212:215], v[116:119]
	v_mfma_i32_16x16x64_i8 v[112:115], v[136:139], v[212:215], v[112:115]
	v_mfma_i32_16x16x64_i8 v[108:111], v[128:131], v[220:223], v[108:111]
	v_mfma_i32_16x16x64_i8 v[104:107], v[136:139], v[220:223], v[104:107]
	v_mfma_i32_16x16x64_i8 v[100:103], v[128:131], v[228:231], v[100:103]
	v_mfma_i32_16x16x64_i8 v[96:99], v[136:139], v[228:231], v[96:99]
	v_mfma_i32_16x16x64_i8 v[124:127], v[132:135], v[208:211], v[124:127]
	v_mfma_i32_16x16x64_i8 v[120:123], v[140:143], v[208:211], v[120:123]
	v_mfma_i32_16x16x64_i8 v[116:119], v[132:135], v[216:219], v[116:119]
	v_mfma_i32_16x16x64_i8 v[112:115], v[140:143], v[216:219], v[112:115]
	v_mfma_i32_16x16x64_i8 v[108:111], v[132:135], v[224:227], v[108:111]
	v_mfma_i32_16x16x64_i8 v[104:107], v[140:143], v[224:227], v[104:107]
	v_mfma_i32_16x16x64_i8 v[100:103], v[132:135], v[234:237], v[100:103]
	v_mfma_i32_16x16x64_i8 v[96:99], v[140:143], v[234:237], v[96:99]
	v_mfma_i32_16x16x64_i8 v[92:95], v[172:175], v[188:191], v[92:95]
	v_mfma_i32_16x16x64_i8 v[88:91], v[180:183], v[188:191], v[88:91]
	v_mfma_i32_16x16x64_i8 v[84:87], v[172:175], v[212:215], v[84:87]
	v_mfma_i32_16x16x64_i8 v[80:83], v[180:183], v[212:215], v[80:83]
	v_mfma_i32_16x16x64_i8 v[76:79], v[172:175], v[220:223], v[76:79]
	v_mfma_i32_16x16x64_i8 v[72:75], v[180:183], v[220:223], v[72:75]
	v_mfma_i32_16x16x64_i8 v[68:71], v[172:175], v[228:231], v[68:71]
	v_mfma_i32_16x16x64_i8 v[64:67], v[180:183], v[228:231], v[64:67]
	v_mfma_i32_16x16x64_i8 v[92:95], v[176:179], v[208:211], v[92:95]
	v_mfma_i32_16x16x64_i8 v[88:91], v[184:187], v[208:211], v[88:91]
	v_mfma_i32_16x16x64_i8 v[84:87], v[176:179], v[216:219], v[84:87]
	v_mfma_i32_16x16x64_i8 v[80:83], v[184:187], v[216:219], v[80:83]
	v_mfma_i32_16x16x64_i8 v[76:79], v[176:179], v[224:227], v[76:79]
	v_mfma_i32_16x16x64_i8 v[72:75], v[184:187], v[224:227], v[72:75]
	v_mfma_i32_16x16x64_i8 v[68:71], v[176:179], v[234:237], v[68:71]
	v_mfma_i32_16x16x64_i8 v[64:67], v[184:187], v[234:237], v[64:67]
	s_barrier
	s_add_i32 s60, s0, s75
	s_add_u32 s98, s98, s10
	s_addc_u32 s99, s99, s11
	s_mov_b32 m0, s60
	ds_read_b128 v[188:191], v206 offset:49152
	ds_read_b128 v[208:211], v206 offset:50176
	ds_read_b128 v[212:215], v206 offset:51200
	ds_read_b128 v[216:219], v206 offset:52224
	ds_read_b128 v[220:223], v206 offset:53248
	ds_read_b128 v[224:227], v206 offset:54272
	ds_read_b128 v[228:231], v206 offset:55296
	ds_read_b128 v[234:237], v206 offset:56320
	global_load_lds_dwordx4 v152, s[98:99]
	s_add_i32 m0, s60, 0x2000
	s_add_u32 s56, s56, 0x20080
	s_addc_u32 s57, s57, 0
	s_add_i32 s60, s87, s75
	global_load_lds_dwordx4 v156, s[98:99]
	s_mov_b32 m0, s60
	s_nop 0
	global_load_lds_dwordx4 v152, s[56:57]
	s_add_i32 m0, s60, 0x2000
	s_nop 0
	global_load_lds_dwordx4 v156, s[56:57]
	s_add_u32 s100, s100, s10
	s_addc_u32 s101, s101, s11
	s_mov_b32 m0, s80
	s_nop 0
	global_load_lds_dwordx4 v150, s[100:101]
	s_mov_b32 m0, s81
	s_nop 0
	global_load_lds_dwordx4 v154, s[100:101]
	s_waitcnt vmcnt(8)
	s_waitcnt lgkmcnt(0)
	s_barrier
	s_waitcnt lgkmcnt(0)
	v_mfma_i32_16x16x64_i8 v[60:63], v[128:131], v[188:191], v[60:63]
	v_mfma_i32_16x16x64_i8 v[56:59], v[136:139], v[188:191], v[56:59]
	v_mfma_i32_16x16x64_i8 v[52:55], v[128:131], v[212:215], v[52:55]
	v_mfma_i32_16x16x64_i8 v[48:51], v[136:139], v[212:215], v[48:51]
	v_mfma_i32_16x16x64_i8 v[44:47], v[128:131], v[220:223], v[44:47]
	v_mfma_i32_16x16x64_i8 v[40:43], v[136:139], v[220:223], v[40:43]
	v_mfma_i32_16x16x64_i8 v[36:39], v[128:131], v[228:231], v[36:39]
	v_mfma_i32_16x16x64_i8 v[32:35], v[136:139], v[228:231], v[32:35]
	v_mfma_i32_16x16x64_i8 v[60:63], v[132:135], v[208:211], v[60:63]
	v_mfma_i32_16x16x64_i8 v[56:59], v[140:143], v[208:211], v[56:59]
	v_mfma_i32_16x16x64_i8 v[52:55], v[132:135], v[216:219], v[52:55]
	v_mfma_i32_16x16x64_i8 v[48:51], v[140:143], v[216:219], v[48:51]
	v_mfma_i32_16x16x64_i8 v[44:47], v[132:135], v[224:227], v[44:47]
	v_mfma_i32_16x16x64_i8 v[40:43], v[140:143], v[224:227], v[40:43]
	v_mfma_i32_16x16x64_i8 v[36:39], v[132:135], v[234:237], v[36:39]
	v_mfma_i32_16x16x64_i8 v[32:35], v[140:143], v[234:237], v[32:35]
	v_mfma_i32_16x16x64_i8 v[28:31], v[172:175], v[188:191], v[28:31]
	v_mfma_i32_16x16x64_i8 v[24:27], v[180:183], v[188:191], v[24:27]
	v_mfma_i32_16x16x64_i8 v[20:23], v[172:175], v[212:215], v[20:23]
	v_mfma_i32_16x16x64_i8 v[16:19], v[180:183], v[212:215], v[16:19]
	v_mfma_i32_16x16x64_i8 v[12:15], v[172:175], v[220:223], v[12:15]
	v_mfma_i32_16x16x64_i8 v[8:11], v[180:183], v[220:223], v[8:11]
	v_mfma_i32_16x16x64_i8 v[4:7], v[172:175], v[228:231], v[4:7]
	v_mfma_i32_16x16x64_i8 v[0:3], v[180:183], v[228:231], v[0:3]
	v_mfma_i32_16x16x64_i8 v[28:31], v[176:179], v[208:211], v[28:31]
	v_mfma_i32_16x16x64_i8 v[24:27], v[184:187], v[208:211], v[24:27]
	v_mfma_i32_16x16x64_i8 v[20:23], v[176:179], v[216:219], v[20:23]
	v_mfma_i32_16x16x64_i8 v[16:19], v[184:187], v[216:219], v[16:19]
	v_mfma_i32_16x16x64_i8 v[12:15], v[176:179], v[224:227], v[12:15]
	v_mfma_i32_16x16x64_i8 v[8:11], v[184:187], v[224:227], v[8:11]
	v_mfma_i32_16x16x64_i8 v[4:7], v[176:179], v[234:237], v[4:7]
	v_mfma_i32_16x16x64_i8 v[0:3], v[184:187], v[234:237], v[0:3]
	s_barrier
	s_add_i32 s86, s86, 2
	s_add_u32 s48, s48, 0x100
	s_addc_u32 s49, s49, 0
	s_add_u32 s63, s63, 0x100
	s_addc_u32 s85, s85, 0
	s_cmp_gt_u32 s86, 5
	s_cbranch_scc0 .LBB0_2602
	s_and_b64 vcc, exec, s[42:43]
	s_cbranch_vccz .LBB0_2605
	s_barrier

.LBB0_2985:
	s_add_u32 s58, s56, 0xfffe0080
	s_addc_u32 s59, s57, -1
	s_add_i32 s85, 0, 0x10000
	s_cmp_eq_u32 s84, 4
	s_cselect_b32 s61, s51, s59
	s_cselect_b32 s60, s81, s58
	s_cselect_b32 s59, s43, s83
	s_cselect_b32 s58, s45, s82
	s_add_i32 s88, 0, 0x14000
	v_add_u32_e32 v150, s85, v182
	v_add_u32_e32 v154, s88, v182
	ds_read_b128 v[138:141], v150
	ds_read_b128 v[142:145], v150 offset:1024
	ds_read_b128 v[146:149], v150 offset:2048
	ds_read_b128 v[150:153], v150 offset:3072
	ds_read_b128 v[166:169], v154
	ds_read_b128 v[190:193], v154 offset:1024
	ds_read_b128 v[194:197], v154 offset:2048
	ds_read_b128 v[198:201], v154 offset:3072
	s_add_i32 m0, s12, 0xc000
	ds_read_b128 v[202:205], v185
	ds_read_b128 v[206:209], v185 offset:1024
	ds_read_b128 v[210:213], v185 offset:2048
	ds_read_b128 v[214:217], v185 offset:3072
	ds_read_b128 v[218:221], v185 offset:4096
	ds_read_b128 v[222:225], v185 offset:5120
	ds_read_b128 v[226:229], v185 offset:6144
	ds_read_b128 v[234:237], v185 offset:7168
	global_load_lds_dwordx4 v134, s[56:57]
	s_add_i32 m0, s12, 0xe000
	s_nop 0
	global_load_lds_dwordx4 v136, s[56:57]
	s_waitcnt vmcnt(8)
	s_waitcnt lgkmcnt(0)
	s_barrier
	s_waitcnt lgkmcnt(0)
	v_mfma_i32_16x16x64_i8 v[126:129], v[138:141], v[202:205], v[126:129]
	v_mfma_i32_16x16x64_i8 v[122:125], v[146:149], v[202:205], v[122:125]
	v_mfma_i32_16x16x64_i8 v[110:113], v[138:141], v[210:213], v[110:113]
	v_mfma_i32_16x16x64_i8 v[106:109], v[146:149], v[210:213], v[106:109]
	v_mfma_i32_16x16x64_i8 v[94:97], v[138:141], v[218:221], v[94:97]
	v_mfma_i32_16x16x64_i8 v[90:93], v[146:149], v[218:221], v[90:93]
	v_mfma_i32_16x16x64_i8 v[78:81], v[138:141], v[226:229], v[78:81]
	v_mfma_i32_16x16x64_i8 v[74:77], v[146:149], v[226:229], v[74:77]
	v_mfma_i32_16x16x64_i8 v[126:129], v[142:145], v[206:209], v[126:129]
	v_mfma_i32_16x16x64_i8 v[122:125], v[150:153], v[206:209], v[122:125]
	v_mfma_i32_16x16x64_i8 v[110:113], v[142:145], v[214:217], v[110:113]
	v_mfma_i32_16x16x64_i8 v[106:109], v[150:153], v[214:217], v[106:109]
	v_mfma_i32_16x16x64_i8 v[94:97], v[142:145], v[222:225], v[94:97]
	v_mfma_i32_16x16x64_i8 v[90:93], v[150:153], v[222:225], v[90:93]
	v_mfma_i32_16x16x64_i8 v[78:81], v[142:145], v[234:237], v[78:81]
	v_mfma_i32_16x16x64_i8 v[74:77], v[150:153], v[234:237], v[74:77]
	v_mfma_i32_16x16x64_i8 v[118:121], v[166:169], v[202:205], v[118:121]
	v_mfma_i32_16x16x64_i8 v[114:117], v[194:197], v[202:205], v[114:117]
	v_mfma_i32_16x16x64_i8 v[102:105], v[166:169], v[210:213], v[102:105]
	v_mfma_i32_16x16x64_i8 v[98:101], v[194:197], v[210:213], v[98:101]
	v_mfma_i32_16x16x64_i8 v[86:89], v[166:169], v[218:221], v[86:89]
	v_mfma_i32_16x16x64_i8 v[82:85], v[194:197], v[218:221], v[82:85]
	v_mfma_i32_16x16x64_i8 v[70:73], v[166:169], v[226:229], v[70:73]
	v_mfma_i32_16x16x64_i8 v[66:69], v[194:197], v[226:229], v[66:69]
	v_mfma_i32_16x16x64_i8 v[118:121], v[190:193], v[206:209], v[118:121]
	v_mfma_i32_16x16x64_i8 v[114:117], v[198:201], v[206:209], v[114:117]
	v_mfma_i32_16x16x64_i8 v[102:105], v[190:193], v[214:217], v[102:105]
	v_mfma_i32_16x16x64_i8 v[98:101], v[198:201], v[214:217], v[98:101]
	v_mfma_i32_16x16x64_i8 v[86:89], v[190:193], v[222:225], v[86:89]
	v_mfma_i32_16x16x64_i8 v[82:85], v[198:201], v[222:225], v[82:85]
	v_mfma_i32_16x16x64_i8 v[70:73], v[190:193], v[234:237], v[70:73]
	v_mfma_i32_16x16x64_i8 v[66:69], v[198:201], v[234:237], v[66:69]
	s_barrier
	s_add_i32 s85, s85, s71
	s_mov_b64 s[98:99], s[58:59]
	s_mov_b32 m0, s85
	ds_read_b128 v[202:205], v185 offset:16384
	ds_read_b128 v[206:209], v185 offset:17408
	ds_read_b128 v[210:213], v185 offset:18432
	ds_read_b128 v[214:217], v185 offset:19456
	ds_read_b128 v[218:221], v185 offset:20480
	ds_read_b128 v[222:225], v185 offset:21504
	ds_read_b128 v[226:229], v185 offset:22528
	ds_read_b128 v[234:237], v185 offset:23552
	global_load_lds_dwordx4 v0, s[58:59]
	s_add_i32 m0, s85, 0x2000
	s_add_u32 s86, s58, 0x20000
	s_addc_u32 s87, s59, 0
	s_add_i32 s85, s88, s71
	global_load_lds_dwordx4 v164, s[58:59]
	s_mov_b32 m0, s85
	s_mov_b64 s[100:101], s[60:61]
	global_load_lds_dwordx4 v0, s[86:87]
	s_add_i32 m0, s85, 0x2000
	s_nop 0
	global_load_lds_dwordx4 v164, s[86:87]
	s_mov_b32 m0, s12
	s_nop 0
	global_load_lds_dwordx4 v160, s[60:61]
	s_mov_b32 m0, s49
	s_nop 0
	global_load_lds_dwordx4 v162, s[60:61]
	s_waitcnt vmcnt(8)
	s_waitcnt lgkmcnt(0)
	s_barrier
	s_waitcnt lgkmcnt(0)
	v_mfma_i32_16x16x64_i8 v[62:65], v[138:141], v[202:205], v[62:65]
	v_mfma_i32_16x16x64_i8 v[58:61], v[146:149], v[202:205], v[58:61]
	v_mfma_i32_16x16x64_i8 v[46:49], v[138:141], v[210:213], v[46:49]
	v_mfma_i32_16x16x64_i8 v[42:45], v[146:149], v[210:213], v[42:45]
	v_mfma_i32_16x16x64_i8 v[30:33], v[138:141], v[218:221], v[30:33]
	v_mfma_i32_16x16x64_i8 v[26:29], v[146:149], v[218:221], v[26:29]
	v_mfma_i32_16x16x64_i8 v[10:13], v[138:141], v[226:229], v[10:13]
	v_mfma_i32_16x16x64_i8 v[2:5], v[146:149], v[226:229], v[2:5]
	v_mfma_i32_16x16x64_i8 v[62:65], v[142:145], v[206:209], v[62:65]
	v_mfma_i32_16x16x64_i8 v[58:61], v[150:153], v[206:209], v[58:61]
	v_mfma_i32_16x16x64_i8 v[46:49], v[142:145], v[214:217], v[46:49]
	v_mfma_i32_16x16x64_i8 v[42:45], v[150:153], v[214:217], v[42:45]
	v_mfma_i32_16x16x64_i8 v[30:33], v[142:145], v[222:225], v[30:33]
	v_mfma_i32_16x16x64_i8 v[26:29], v[150:153], v[222:225], v[26:29]
	v_mfma_i32_16x16x64_i8 v[10:13], v[142:145], v[234:237], v[10:13]
	v_mfma_i32_16x16x64_i8 v[2:5], v[150:153], v[234:237], v[2:5]
	v_mfma_i32_16x16x64_i8 v[54:57], v[166:169], v[202:205], v[54:57]
	v_mfma_i32_16x16x64_i8 v[50:53], v[194:197], v[202:205], v[50:53]
	v_mfma_i32_16x16x64_i8 v[38:41], v[166:169], v[210:213], v[38:41]
	v_mfma_i32_16x16x64_i8 v[34:37], v[194:197], v[210:213], v[34:37]
	v_mfma_i32_16x16x64_i8 v[22:25], v[166:169], v[218:221], v[22:25]
	v_mfma_i32_16x16x64_i8 v[18:21], v[194:197], v[218:221], v[18:21]
	v_mfma_i32_16x16x64_i8 v[14:17], v[166:169], v[226:229], v[14:17]
	v_mfma_i32_16x16x64_i8 v[6:9], v[194:197], v[226:229], v[6:9]
	v_mfma_i32_16x16x64_i8 v[54:57], v[190:193], v[206:209], v[54:57]
	v_mfma_i32_16x16x64_i8 v[50:53], v[198:201], v[206:209], v[50:53]
	v_mfma_i32_16x16x64_i8 v[38:41], v[190:193], v[214:217], v[38:41]
	v_mfma_i32_16x16x64_i8 v[34:37], v[198:201], v[214:217], v[34:37]
	v_mfma_i32_16x16x64_i8 v[22:25], v[190:193], v[222:225], v[22:25]
	v_mfma_i32_16x16x64_i8 v[18:21], v[198:201], v[222:225], v[18:21]
	v_mfma_i32_16x16x64_i8 v[14:17], v[190:193], v[234:237], v[14:17]
	v_mfma_i32_16x16x64_i8 v[6:9], v[198:201], v[234:237], v[6:9]
	s_barrier
	s_add_i32 s85, 0, 0x18000
	s_add_i32 s86, 0, 0x1c000
	v_add_u32_e32 v150, s85, v182
	v_add_u32_e32 v189, s86, v182
	ds_read_b128 v[138:141], v150
	ds_read_b128 v[142:145], v150 offset:1024
	ds_read_b128 v[146:149], v150 offset:2048
	ds_read_b128 v[150:153], v150 offset:3072
	ds_read_b128 v[166:169], v189
	ds_read_b128 v[190:193], v189 offset:1024
	ds_read_b128 v[194:197], v189 offset:2048
	ds_read_b128 v[198:201], v189 offset:3072
	s_add_u32 s60, s60, 0x20000
	s_addc_u32 s61, s61, 0
	s_mov_b32 m0, s72
	ds_read_b128 v[202:205], v185 offset:32768
	ds_read_b128 v[206:209], v185 offset:33792
	ds_read_b128 v[210:213], v185 offset:34816
	ds_read_b128 v[214:217], v185 offset:35840
	ds_read_b128 v[218:221], v185 offset:36864
	ds_read_b128 v[222:225], v185 offset:37888
	ds_read_b128 v[226:229], v185 offset:38912
	ds_read_b128 v[234:237], v185 offset:39936
	global_load_lds_dwordx4 v160, s[60:61]
	s_mov_b32 m0, s73
	s_nop 0
	global_load_lds_dwordx4 v162, s[60:61]
	s_waitcnt vmcnt(8)
	s_waitcnt lgkmcnt(0)
	s_barrier
	s_waitcnt lgkmcnt(0)
	v_mfma_i32_16x16x64_i8 v[126:129], v[138:141], v[202:205], v[126:129]
	v_mfma_i32_16x16x64_i8 v[122:125], v[146:149], v[202:205], v[122:125]
	v_mfma_i32_16x16x64_i8 v[110:113], v[138:141], v[210:213], v[110:113]
	v_mfma_i32_16x16x64_i8 v[106:109], v[146:149], v[210:213], v[106:109]
	v_mfma_i32_16x16x64_i8 v[94:97], v[138:141], v[218:221], v[94:97]
	v_mfma_i32_16x16x64_i8 v[90:93], v[146:149], v[218:221], v[90:93]
	v_mfma_i32_16x16x64_i8 v[78:81], v[138:141], v[226:229], v[78:81]
	v_mfma_i32_16x16x64_i8 v[74:77], v[146:149], v[226:229], v[74:77]
	v_mfma_i32_16x16x64_i8 v[126:129], v[142:145], v[206:209], v[126:129]
	v_mfma_i32_16x16x64_i8 v[122:125], v[150:153], v[206:209], v[122:125]
	v_mfma_i32_16x16x64_i8 v[110:113], v[142:145], v[214:217], v[110:113]
	v_mfma_i32_16x16x64_i8 v[106:109], v[150:153], v[214:217], v[106:109]
	v_mfma_i32_16x16x64_i8 v[94:97], v[142:145], v[222:225], v[94:97]
	v_mfma_i32_16x16x64_i8 v[90:93], v[150:153], v[222:225], v[90:93]
	v_mfma_i32_16x16x64_i8 v[78:81], v[142:145], v[234:237], v[78:81]
	v_mfma_i32_16x16x64_i8 v[74:77], v[150:153], v[234:237], v[74:77]
	v_mfma_i32_16x16x64_i8 v[118:121], v[166:169], v[202:205], v[118:121]
	v_mfma_i32_16x16x64_i8 v[114:117], v[194:197], v[202:205], v[114:117]
	v_mfma_i32_16x16x64_i8 v[102:105], v[166:169], v[210:213], v[102:105]
	v_mfma_i32_16x16x64_i8 v[98:101], v[194:197], v[210:213], v[98:101]
	v_mfma_i32_16x16x64_i8 v[86:89], v[166:169], v[218:221], v[86:89]
	v_mfma_i32_16x16x64_i8 v[82:85], v[194:197], v[218:221], v[82:85]
	v_mfma_i32_16x16x64_i8 v[70:73], v[166:169], v[226:229], v[70:73]
	v_mfma_i32_16x16x64_i8 v[66:69], v[194:197], v[226:229], v[66:69]
	v_mfma_i32_16x16x64_i8 v[118:121], v[190:193], v[206:209], v[118:121]
	v_mfma_i32_16x16x64_i8 v[114:117], v[198:201], v[206:209], v[114:117]
	v_mfma_i32_16x16x64_i8 v[102:105], v[190:193], v[214:217], v[102:105]
	v_mfma_i32_16x16x64_i8 v[98:101], v[198:201], v[214:217], v[98:101]
	v_mfma_i32_16x16x64_i8 v[86:89], v[190:193], v[222:225], v[86:89]
	v_mfma_i32_16x16x64_i8 v[82:85], v[198:201], v[222:225], v[82:85]
	v_mfma_i32_16x16x64_i8 v[70:73], v[190:193], v[234:237], v[70:73]
	v_mfma_i32_16x16x64_i8 v[66:69], v[198:201], v[234:237], v[66:69]
	s_barrier
	s_add_i32 s60, s85, s71
	s_add_u32 s98, s98, s14
	s_addc_u32 s99, s99, s15
	s_mov_b32 m0, s60
	ds_read_b128 v[202:205], v185 offset:49152
	ds_read_b128 v[206:209], v185 offset:50176
	ds_read_b128 v[210:213], v185 offset:51200
	ds_read_b128 v[214:217], v185 offset:52224
	ds_read_b128 v[218:221], v185 offset:53248
	ds_read_b128 v[222:225], v185 offset:54272
	ds_read_b128 v[226:229], v185 offset:55296
	ds_read_b128 v[234:237], v185 offset:56320
	global_load_lds_dwordx4 v0, s[98:99]
	s_add_i32 m0, s60, 0x2000
	s_add_u32 s58, s58, 0x20080
	s_addc_u32 s59, s59, 0
	s_add_i32 s60, s86, s71
	global_load_lds_dwordx4 v164, s[98:99]
	s_mov_b32 m0, s60
	s_nop 0
	global_load_lds_dwordx4 v0, s[58:59]
	s_add_i32 m0, s60, 0x2000
	s_nop 0
	global_load_lds_dwordx4 v164, s[58:59]
	s_add_u32 s100, s100, s14
	s_addc_u32 s101, s101, s15
	s_mov_b32 m0, s74
	s_nop 0
	global_load_lds_dwordx4 v160, s[100:101]
	s_mov_b32 m0, s75
	s_nop 0
	global_load_lds_dwordx4 v162, s[100:101]
	s_waitcnt vmcnt(8)
	s_waitcnt lgkmcnt(0)
	s_barrier
	s_waitcnt lgkmcnt(0)
	v_mfma_i32_16x16x64_i8 v[62:65], v[138:141], v[202:205], v[62:65]
	v_mfma_i32_16x16x64_i8 v[58:61], v[146:149], v[202:205], v[58:61]
	v_mfma_i32_16x16x64_i8 v[46:49], v[138:141], v[210:213], v[46:49]
	v_mfma_i32_16x16x64_i8 v[42:45], v[146:149], v[210:213], v[42:45]
	v_mfma_i32_16x16x64_i8 v[30:33], v[138:141], v[218:221], v[30:33]
	v_mfma_i32_16x16x64_i8 v[26:29], v[146:149], v[218:221], v[26:29]
	v_mfma_i32_16x16x64_i8 v[10:13], v[138:141], v[226:229], v[10:13]
	v_mfma_i32_16x16x64_i8 v[2:5], v[146:149], v[226:229], v[2:5]
	v_mfma_i32_16x16x64_i8 v[62:65], v[142:145], v[206:209], v[62:65]
	v_mfma_i32_16x16x64_i8 v[58:61], v[150:153], v[206:209], v[58:61]
	v_mfma_i32_16x16x64_i8 v[46:49], v[142:145], v[214:217], v[46:49]
	v_mfma_i32_16x16x64_i8 v[42:45], v[150:153], v[214:217], v[42:45]
	v_mfma_i32_16x16x64_i8 v[30:33], v[142:145], v[222:225], v[30:33]
	v_mfma_i32_16x16x64_i8 v[26:29], v[150:153], v[222:225], v[26:29]
	v_mfma_i32_16x16x64_i8 v[10:13], v[142:145], v[234:237], v[10:13]
	v_mfma_i32_16x16x64_i8 v[2:5], v[150:153], v[234:237], v[2:5]
	v_mfma_i32_16x16x64_i8 v[54:57], v[166:169], v[202:205], v[54:57]
	v_mfma_i32_16x16x64_i8 v[50:53], v[194:197], v[202:205], v[50:53]
	v_mfma_i32_16x16x64_i8 v[38:41], v[166:169], v[210:213], v[38:41]
	v_mfma_i32_16x16x64_i8 v[34:37], v[194:197], v[210:213], v[34:37]
	v_mfma_i32_16x16x64_i8 v[22:25], v[166:169], v[218:221], v[22:25]
	v_mfma_i32_16x16x64_i8 v[18:21], v[194:197], v[218:221], v[18:21]
	v_mfma_i32_16x16x64_i8 v[14:17], v[166:169], v[226:229], v[14:17]
	v_mfma_i32_16x16x64_i8 v[6:9], v[194:197], v[226:229], v[6:9]
	v_mfma_i32_16x16x64_i8 v[54:57], v[190:193], v[206:209], v[54:57]
	v_mfma_i32_16x16x64_i8 v[50:53], v[198:201], v[206:209], v[50:53]
	v_mfma_i32_16x16x64_i8 v[38:41], v[190:193], v[214:217], v[38:41]
	v_mfma_i32_16x16x64_i8 v[34:37], v[198:201], v[214:217], v[34:37]
	v_mfma_i32_16x16x64_i8 v[22:25], v[190:193], v[222:225], v[22:25]
	v_mfma_i32_16x16x64_i8 v[18:21], v[198:201], v[222:225], v[18:21]
	v_mfma_i32_16x16x64_i8 v[14:17], v[190:193], v[234:237], v[14:17]
	v_mfma_i32_16x16x64_i8 v[6:9], v[198:201], v[234:237], v[6:9]
	s_barrier
	s_add_i32 s84, s84, 2
	s_add_u32 s56, s56, 0x100
	s_addc_u32 s57, s57, 0
	s_add_u32 s82, s82, 0x100
	s_addc_u32 s83, s83, 0
	s_cmp_gt_u32 s84, 5
	s_cbranch_scc0 .LBB0_2985
	s_and_b64 vcc, exec, s[40:41]
	s_cbranch_vccz .LBB0_2988
	s_barrier

.LBB0_3015:
	s_add_u32 s8, s6, 0xfffe0080
	s_addc_u32 s9, s7, -1
	s_add_i32 s72, 0, 0x10000
	s_cmp_eq_u32 s71, 4
	s_cselect_b32 s55, s43, s9
	s_cselect_b32 s54, s49, s8
	v_add_u32_e32 v0, s72, v188
	s_cselect_b32 s9, s39, s70
	s_cselect_b32 s8, s41, s69
	s_add_i32 s74, 0, 0x14000
	ds_read_b128 v[132:135], v0
	ds_read_b128 v[136:139], v0 offset:1024
	ds_read_b128 v[140:143], v0 offset:2048
	ds_read_b128 v[144:147], v0 offset:3072
	v_add_u32_e32 v0, s74, v188
	ds_read_b128 v[148:151], v0
	ds_read_b128 v[152:155], v0 offset:1024
	ds_read_b128 v[176:179], v0 offset:2048
	ds_read_b128 v[180:183], v0 offset:3072
	s_add_i32 m0, s45, 0xc000
	ds_read_b128 v[198:201], v196
	ds_read_b128 v[202:205], v196 offset:1024
	ds_read_b128 v[206:209], v196 offset:2048
	ds_read_b128 v[210:213], v196 offset:3072
	ds_read_b128 v[214:217], v196 offset:4096
	ds_read_b128 v[218:221], v196 offset:5120
	ds_read_b128 v[222:225], v196 offset:6144
	ds_read_b128 v[226:229], v196 offset:7168
	global_load_lds_dwordx4 v172, s[6:7]
	s_add_i32 m0, s45, 0xe000
	s_nop 0
	global_load_lds_dwordx4 v174, s[6:7]
	s_waitcnt vmcnt(8)
	s_waitcnt lgkmcnt(0)
	s_barrier
	s_waitcnt lgkmcnt(0)
	v_mfma_f32_16x16x32_bf16 v[128:131], v[132:135], v[198:201], v[128:131]
	v_mfma_f32_16x16x32_bf16 v[124:127], v[140:143], v[198:201], v[124:127]
	v_mfma_f32_16x16x32_bf16 v[120:123], v[132:135], v[206:209], v[120:123]
	v_mfma_f32_16x16x32_bf16 v[116:119], v[140:143], v[206:209], v[116:119]
	v_mfma_f32_16x16x32_bf16 v[112:115], v[132:135], v[214:217], v[112:115]
	v_mfma_f32_16x16x32_bf16 v[108:111], v[140:143], v[214:217], v[108:111]
	v_mfma_f32_16x16x32_bf16 v[104:107], v[132:135], v[222:225], v[104:107]
	v_mfma_f32_16x16x32_bf16 v[100:103], v[140:143], v[222:225], v[100:103]
	v_mfma_f32_16x16x32_bf16 v[128:131], v[136:139], v[202:205], v[128:131]
	v_mfma_f32_16x16x32_bf16 v[124:127], v[144:147], v[202:205], v[124:127]
	v_mfma_f32_16x16x32_bf16 v[120:123], v[136:139], v[210:213], v[120:123]
	v_mfma_f32_16x16x32_bf16 v[116:119], v[144:147], v[210:213], v[116:119]
	v_mfma_f32_16x16x32_bf16 v[112:115], v[136:139], v[218:221], v[112:115]
	v_mfma_f32_16x16x32_bf16 v[108:111], v[144:147], v[218:221], v[108:111]
	v_mfma_f32_16x16x32_bf16 v[104:107], v[136:139], v[226:229], v[104:107]
	v_mfma_f32_16x16x32_bf16 v[100:103], v[144:147], v[226:229], v[100:103]
	v_mfma_f32_16x16x32_bf16 v[96:99], v[148:151], v[198:201], v[96:99]
	v_mfma_f32_16x16x32_bf16 v[92:95], v[176:179], v[198:201], v[92:95]
	v_mfma_f32_16x16x32_bf16 v[88:91], v[148:151], v[206:209], v[88:91]
	v_mfma_f32_16x16x32_bf16 v[84:87], v[176:179], v[206:209], v[84:87]
	v_mfma_f32_16x16x32_bf16 v[80:83], v[148:151], v[214:217], v[80:83]
	v_mfma_f32_16x16x32_bf16 v[76:79], v[176:179], v[214:217], v[76:79]
	v_mfma_f32_16x16x32_bf16 v[72:75], v[148:151], v[222:225], v[72:75]
	v_mfma_f32_16x16x32_bf16 v[68:71], v[176:179], v[222:225], v[68:71]
	v_mfma_f32_16x16x32_bf16 v[96:99], v[152:155], v[202:205], v[96:99]
	v_mfma_f32_16x16x32_bf16 v[92:95], v[180:183], v[202:205], v[92:95]
	v_mfma_f32_16x16x32_bf16 v[88:91], v[152:155], v[210:213], v[88:91]
	v_mfma_f32_16x16x32_bf16 v[84:87], v[180:183], v[210:213], v[84:87]
	v_mfma_f32_16x16x32_bf16 v[80:83], v[152:155], v[218:221], v[80:83]
	v_mfma_f32_16x16x32_bf16 v[76:79], v[180:183], v[218:221], v[76:79]
	v_mfma_f32_16x16x32_bf16 v[72:75], v[152:155], v[226:229], v[72:75]
	v_mfma_f32_16x16x32_bf16 v[68:71], v[180:183], v[226:229], v[68:71]
	s_barrier
	s_add_i32 s72, s72, s60
	s_mov_b64 s[98:99], s[8:9]
	s_mov_b32 m0, s72
	ds_read_b128 v[198:201], v196 offset:16384
	ds_read_b128 v[202:205], v196 offset:17408
	ds_read_b128 v[206:209], v196 offset:18432
	ds_read_b128 v[210:213], v196 offset:19456
	ds_read_b128 v[214:217], v196 offset:20480
	ds_read_b128 v[218:221], v196 offset:21504
	ds_read_b128 v[222:225], v196 offset:22528
	ds_read_b128 v[226:229], v196 offset:23552
	global_load_lds_dwordx4 v166, s[8:9]
	s_add_i32 m0, s72, 0x2000
	s_add_u32 s72, s8, 0x20000
	s_addc_u32 s73, s9, 0
	s_add_i32 s74, s74, s60
	global_load_lds_dwordx4 v164, s[8:9]
	s_mov_b32 m0, s74
	s_mov_b64 s[100:101], s[54:55]
	global_load_lds_dwordx4 v166, s[72:73]
	s_add_i32 m0, s74, 0x2000
	s_nop 0
	global_load_lds_dwordx4 v164, s[72:73]
	s_mov_b32 m0, s45
	s_nop 0
	global_load_lds_dwordx4 v160, s[54:55]
	s_mov_b32 m0, s61
	s_nop 0
	global_load_lds_dwordx4 v162, s[54:55]
	s_waitcnt vmcnt(8)
	s_waitcnt lgkmcnt(0)
	s_barrier
	s_waitcnt lgkmcnt(0)
	v_mfma_f32_16x16x32_bf16 v[64:67], v[132:135], v[198:201], v[64:67]
	v_mfma_f32_16x16x32_bf16 v[60:63], v[140:143], v[198:201], v[60:63]
	v_mfma_f32_16x16x32_bf16 v[56:59], v[132:135], v[206:209], v[56:59]
	v_mfma_f32_16x16x32_bf16 v[52:55], v[140:143], v[206:209], v[52:55]
	v_mfma_f32_16x16x32_bf16 v[48:51], v[132:135], v[214:217], v[48:51]
	v_mfma_f32_16x16x32_bf16 v[44:47], v[140:143], v[214:217], v[44:47]
	v_mfma_f32_16x16x32_bf16 v[40:43], v[132:135], v[222:225], v[40:43]
	v_mfma_f32_16x16x32_bf16 v[36:39], v[140:143], v[222:225], v[36:39]
	v_mfma_f32_16x16x32_bf16 v[64:67], v[136:139], v[202:205], v[64:67]
	v_mfma_f32_16x16x32_bf16 v[60:63], v[144:147], v[202:205], v[60:63]
	v_mfma_f32_16x16x32_bf16 v[56:59], v[136:139], v[210:213], v[56:59]
	v_mfma_f32_16x16x32_bf16 v[52:55], v[144:147], v[210:213], v[52:55]
	v_mfma_f32_16x16x32_bf16 v[48:51], v[136:139], v[218:221], v[48:51]
	v_mfma_f32_16x16x32_bf16 v[44:47], v[144:147], v[218:221], v[44:47]
	v_mfma_f32_16x16x32_bf16 v[40:43], v[136:139], v[226:229], v[40:43]
	v_mfma_f32_16x16x32_bf16 v[36:39], v[144:147], v[226:229], v[36:39]
	v_mfma_f32_16x16x32_bf16 v[32:35], v[148:151], v[198:201], v[32:35]
	v_mfma_f32_16x16x32_bf16 v[28:31], v[176:179], v[198:201], v[28:31]
	v_mfma_f32_16x16x32_bf16 v[24:27], v[148:151], v[206:209], v[24:27]
	v_mfma_f32_16x16x32_bf16 v[20:23], v[176:179], v[206:209], v[20:23]
	v_mfma_f32_16x16x32_bf16 v[16:19], v[148:151], v[214:217], v[16:19]
	v_mfma_f32_16x16x32_bf16 v[12:15], v[176:179], v[214:217], v[12:15]
	v_mfma_f32_16x16x32_bf16 v[8:11], v[148:151], v[222:225], v[8:11]
	v_mfma_f32_16x16x32_bf16 v[2:5], v[176:179], v[222:225], v[4:7]
	v_mfma_f32_16x16x32_bf16 v[32:35], v[152:155], v[202:205], v[32:35]
	v_mfma_f32_16x16x32_bf16 v[28:31], v[180:183], v[202:205], v[28:31]
	v_mfma_f32_16x16x32_bf16 v[24:27], v[152:155], v[210:213], v[24:27]
	v_mfma_f32_16x16x32_bf16 v[20:23], v[180:183], v[210:213], v[20:23]
	v_mfma_f32_16x16x32_bf16 v[16:19], v[152:155], v[218:221], v[16:19]
	v_mfma_f32_16x16x32_bf16 v[12:15], v[180:183], v[218:221], v[12:15]
	v_mfma_f32_16x16x32_bf16 v[8:11], v[152:155], v[226:229], v[8:11]
	v_mfma_f32_16x16x32_bf16 v[2:5], v[180:183], v[226:229], v[2:5]
	s_barrier
	s_add_i32 s72, 0, 0x18000
	v_add_u32_e32 v0, s72, v188
	s_add_i32 s73, 0, 0x1c000
	ds_read_b128 v[132:135], v0
	ds_read_b128 v[136:139], v0 offset:1024
	ds_read_b128 v[140:143], v0 offset:2048
	ds_read_b128 v[144:147], v0 offset:3072
	v_add_u32_e32 v0, s73, v188
	ds_read_b128 v[148:151], v0
	ds_read_b128 v[152:155], v0 offset:1024
	ds_read_b128 v[176:179], v0 offset:2048
	ds_read_b128 v[180:183], v0 offset:3072
	s_add_u32 s54, s54, 0x20000
	s_addc_u32 s55, s55, 0
	s_mov_b32 m0, s62
	ds_read_b128 v[198:201], v196 offset:32768
	ds_read_b128 v[202:205], v196 offset:33792
	ds_read_b128 v[206:209], v196 offset:34816
	ds_read_b128 v[210:213], v196 offset:35840
	ds_read_b128 v[214:217], v196 offset:36864
	ds_read_b128 v[218:221], v196 offset:37888
	ds_read_b128 v[222:225], v196 offset:38912
	ds_read_b128 v[226:229], v196 offset:39936
	global_load_lds_dwordx4 v160, s[54:55]
	s_mov_b32 m0, s63
	s_nop 0
	global_load_lds_dwordx4 v162, s[54:55]
	s_waitcnt vmcnt(8)
	s_waitcnt lgkmcnt(0)
	s_barrier
	s_waitcnt lgkmcnt(0)
	v_mfma_f32_16x16x32_bf16 v[128:131], v[132:135], v[198:201], v[128:131]
	v_mfma_f32_16x16x32_bf16 v[124:127], v[140:143], v[198:201], v[124:127]
	v_mfma_f32_16x16x32_bf16 v[120:123], v[132:135], v[206:209], v[120:123]
	v_mfma_f32_16x16x32_bf16 v[116:119], v[140:143], v[206:209], v[116:119]
	v_mfma_f32_16x16x32_bf16 v[112:115], v[132:135], v[214:217], v[112:115]
	v_mfma_f32_16x16x32_bf16 v[108:111], v[140:143], v[214:217], v[108:111]
	v_mfma_f32_16x16x32_bf16 v[104:107], v[132:135], v[222:225], v[104:107]
	v_mfma_f32_16x16x32_bf16 v[100:103], v[140:143], v[222:225], v[100:103]
	v_mfma_f32_16x16x32_bf16 v[128:131], v[136:139], v[202:205], v[128:131]
	v_mfma_f32_16x16x32_bf16 v[124:127], v[144:147], v[202:205], v[124:127]
	v_mfma_f32_16x16x32_bf16 v[120:123], v[136:139], v[210:213], v[120:123]
	v_mfma_f32_16x16x32_bf16 v[116:119], v[144:147], v[210:213], v[116:119]
	v_mfma_f32_16x16x32_bf16 v[112:115], v[136:139], v[218:221], v[112:115]
	v_mfma_f32_16x16x32_bf16 v[108:111], v[144:147], v[218:221], v[108:111]
	v_mfma_f32_16x16x32_bf16 v[104:107], v[136:139], v[226:229], v[104:107]
	v_mfma_f32_16x16x32_bf16 v[100:103], v[144:147], v[226:229], v[100:103]
	v_mfma_f32_16x16x32_bf16 v[96:99], v[148:151], v[198:201], v[96:99]
	v_mfma_f32_16x16x32_bf16 v[92:95], v[176:179], v[198:201], v[92:95]
	v_mfma_f32_16x16x32_bf16 v[88:91], v[148:151], v[206:209], v[88:91]
	v_mfma_f32_16x16x32_bf16 v[84:87], v[176:179], v[206:209], v[84:87]
	v_mfma_f32_16x16x32_bf16 v[80:83], v[148:151], v[214:217], v[80:83]
	v_mfma_f32_16x16x32_bf16 v[76:79], v[176:179], v[214:217], v[76:79]
	v_mfma_f32_16x16x32_bf16 v[72:75], v[148:151], v[222:225], v[72:75]
	v_mfma_f32_16x16x32_bf16 v[68:71], v[176:179], v[222:225], v[68:71]
	v_mfma_f32_16x16x32_bf16 v[96:99], v[152:155], v[202:205], v[96:99]
	v_mfma_f32_16x16x32_bf16 v[92:95], v[180:183], v[202:205], v[92:95]
	v_mfma_f32_16x16x32_bf16 v[88:91], v[152:155], v[210:213], v[88:91]
	v_mfma_f32_16x16x32_bf16 v[84:87], v[180:183], v[210:213], v[84:87]
	v_mfma_f32_16x16x32_bf16 v[80:83], v[152:155], v[218:221], v[80:83]
	v_mfma_f32_16x16x32_bf16 v[76:79], v[180:183], v[218:221], v[76:79]
	v_mfma_f32_16x16x32_bf16 v[72:75], v[152:155], v[226:229], v[72:75]
	v_mfma_f32_16x16x32_bf16 v[68:71], v[180:183], v[226:229], v[68:71]
	s_barrier
	s_add_i32 s54, s72, s60
	s_add_u32 s98, s98, s14
	s_addc_u32 s99, s99, s15
	s_mov_b32 m0, s54
	ds_read_b128 v[198:201], v196 offset:49152
	ds_read_b128 v[202:205], v196 offset:50176
	ds_read_b128 v[206:209], v196 offset:51200
	ds_read_b128 v[210:213], v196 offset:52224
	ds_read_b128 v[214:217], v196 offset:53248
	ds_read_b128 v[218:221], v196 offset:54272
	ds_read_b128 v[222:225], v196 offset:55296
	ds_read_b128 v[226:229], v196 offset:56320
	global_load_lds_dwordx4 v166, s[98:99]
	s_add_i32 m0, s54, 0x2000
	s_add_u32 s8, s8, 0x20080
	s_addc_u32 s9, s9, 0
	s_add_i32 s54, s73, s60
	global_load_lds_dwordx4 v164, s[98:99]
	s_mov_b32 m0, s54
	s_nop 0
	global_load_lds_dwordx4 v166, s[8:9]
	s_add_i32 m0, s54, 0x2000
	s_nop 0
	global_load_lds_dwordx4 v164, s[8:9]
	s_add_u32 s100, s100, s14
	s_addc_u32 s101, s101, s15
	s_mov_b32 m0, s65
	s_nop 0
	global_load_lds_dwordx4 v160, s[100:101]
	s_mov_b32 m0, s66
	s_nop 0
	global_load_lds_dwordx4 v162, s[100:101]
	s_waitcnt vmcnt(8)
	s_waitcnt lgkmcnt(0)
	s_barrier
	s_waitcnt lgkmcnt(0)
	v_mfma_f32_16x16x32_bf16 v[64:67], v[132:135], v[198:201], v[64:67]
	v_mfma_f32_16x16x32_bf16 v[60:63], v[140:143], v[198:201], v[60:63]
	v_mfma_f32_16x16x32_bf16 v[56:59], v[132:135], v[206:209], v[56:59]
	v_mfma_f32_16x16x32_bf16 v[52:55], v[140:143], v[206:209], v[52:55]
	v_mfma_f32_16x16x32_bf16 v[48:51], v[132:135], v[214:217], v[48:51]
	v_mfma_f32_16x16x32_bf16 v[44:47], v[140:143], v[214:217], v[44:47]
	v_mfma_f32_16x16x32_bf16 v[40:43], v[132:135], v[222:225], v[40:43]
	v_mfma_f32_16x16x32_bf16 v[36:39], v[140:143], v[222:225], v[36:39]
	v_mfma_f32_16x16x32_bf16 v[64:67], v[136:139], v[202:205], v[64:67]
	v_mfma_f32_16x16x32_bf16 v[60:63], v[144:147], v[202:205], v[60:63]
	v_mfma_f32_16x16x32_bf16 v[56:59], v[136:139], v[210:213], v[56:59]
	v_mfma_f32_16x16x32_bf16 v[52:55], v[144:147], v[210:213], v[52:55]
	v_mfma_f32_16x16x32_bf16 v[48:51], v[136:139], v[218:221], v[48:51]
	v_mfma_f32_16x16x32_bf16 v[44:47], v[144:147], v[218:221], v[44:47]
	v_mfma_f32_16x16x32_bf16 v[40:43], v[136:139], v[226:229], v[40:43]
	v_mfma_f32_16x16x32_bf16 v[36:39], v[144:147], v[226:229], v[36:39]
	v_mfma_f32_16x16x32_bf16 v[32:35], v[148:151], v[198:201], v[32:35]
	v_mfma_f32_16x16x32_bf16 v[28:31], v[176:179], v[198:201], v[28:31]
	v_mfma_f32_16x16x32_bf16 v[24:27], v[148:151], v[206:209], v[24:27]
	v_mfma_f32_16x16x32_bf16 v[20:23], v[176:179], v[206:209], v[20:23]
	v_mfma_f32_16x16x32_bf16 v[16:19], v[148:151], v[214:217], v[16:19]
	v_mfma_f32_16x16x32_bf16 v[12:15], v[176:179], v[214:217], v[12:15]
	v_mfma_f32_16x16x32_bf16 v[6:9], v[148:151], v[222:225], v[8:11]
	v_mfma_f32_16x16x32_bf16 v[2:5], v[176:179], v[222:225], v[2:5]
	v_mfma_f32_16x16x32_bf16 v[32:35], v[152:155], v[202:205], v[32:35]
	v_mfma_f32_16x16x32_bf16 v[28:31], v[180:183], v[202:205], v[28:31]
	v_mfma_f32_16x16x32_bf16 v[24:27], v[152:155], v[210:213], v[24:27]
	v_mfma_f32_16x16x32_bf16 v[20:23], v[180:183], v[210:213], v[20:23]
	v_mfma_f32_16x16x32_bf16 v[16:19], v[152:155], v[218:221], v[16:19]
	v_mfma_f32_16x16x32_bf16 v[12:15], v[180:183], v[218:221], v[12:15]
	v_mfma_f32_16x16x32_bf16 v[8:11], v[152:155], v[226:229], v[6:9]
	v_mfma_f32_16x16x32_bf16 v[4:7], v[180:183], v[226:229], v[2:5]
	s_barrier
	s_add_i32 s71, s71, 2
	s_add_u32 s6, s6, 0x100
	s_addc_u32 s7, s7, 0
	s_add_u32 s69, s69, 0x100
	s_addc_u32 s70, s70, 0
	s_cmp_gt_u32 s71, 5
	s_cbranch_scc0 .LBB0_3015
	s_and_b64 vcc, exec, s[36:37]
	s_cbranch_vccz .LBB0_3018
	s_barrier

.LBB0_3227:
	s_add_u32 s58, s48, 0xfffc0080
	s_addc_u32 s59, s49, -1
	s_add_i32 s64, 0, 0x10000
	s_cmp_eq_u32 s63, 12
	s_cselect_b32 s61, s14, s59
	s_cselect_b32 s60, s45, s58
	v_add_u32_e32 v0, s64, v169
	s_cselect_b32 s59, s43, s62
	s_cselect_b32 s58, s55, s57
	s_add_i32 s66, 0, 0x14000
	ds_read_b128 v[148:151], v0
	ds_read_b128 v[152:155], v0 offset:1024
	ds_read_b128 v[156:159], v0 offset:2048
	ds_read_b128 v[190:193], v0 offset:3072
	v_add_u32_e32 v0, s66, v169
	ds_read_b128 v[194:197], v0
	ds_read_b128 v[198:201], v0 offset:1024
	ds_read_b128 v[202:205], v0 offset:2048
	ds_read_b128 v[206:209], v0 offset:3072
	s_add_i32 m0, s80, 0xc000
	ds_read_b128 v[210:213], v188
	ds_read_b128 v[214:217], v188 offset:1024
	ds_read_b128 v[218:221], v188 offset:2048
	ds_read_b128 v[222:225], v188 offset:3072
	ds_read_b128 v[226:229], v188 offset:4096
	ds_read_b128 v[234:237], v188 offset:5120
	ds_read_b128 v[238:241], v188 offset:6144
	ds_read_b128 v[242:245], v188 offset:7168
	global_load_lds_dwordx4 v144, s[48:49]
	s_add_i32 m0, s80, 0xe000
	s_nop 0
	global_load_lds_dwordx4 v146, s[48:49]
	s_waitcnt vmcnt(8)
	s_waitcnt lgkmcnt(0)
	s_barrier
	s_waitcnt lgkmcnt(0)
	v_mfma_f32_16x16x32_bf16 v[126:129], v[148:151], v[210:213], v[126:129]
	v_mfma_f32_16x16x32_bf16 v[122:125], v[156:159], v[210:213], v[122:125]
	v_mfma_f32_16x16x32_bf16 v[110:113], v[148:151], v[218:221], v[110:113]
	v_mfma_f32_16x16x32_bf16 v[106:109], v[156:159], v[218:221], v[106:109]
	v_mfma_f32_16x16x32_bf16 v[94:97], v[148:151], v[226:229], v[94:97]
	v_mfma_f32_16x16x32_bf16 v[90:93], v[156:159], v[226:229], v[90:93]
	v_mfma_f32_16x16x32_bf16 v[78:81], v[148:151], v[238:241], v[78:81]
	v_mfma_f32_16x16x32_bf16 v[74:77], v[156:159], v[238:241], v[74:77]
	v_mfma_f32_16x16x32_bf16 v[126:129], v[152:155], v[214:217], v[126:129]
	v_mfma_f32_16x16x32_bf16 v[122:125], v[190:193], v[214:217], v[122:125]
	v_mfma_f32_16x16x32_bf16 v[110:113], v[152:155], v[222:225], v[110:113]
	v_mfma_f32_16x16x32_bf16 v[106:109], v[190:193], v[222:225], v[106:109]
	v_mfma_f32_16x16x32_bf16 v[94:97], v[152:155], v[234:237], v[94:97]
	v_mfma_f32_16x16x32_bf16 v[90:93], v[190:193], v[234:237], v[90:93]
	v_mfma_f32_16x16x32_bf16 v[78:81], v[152:155], v[242:245], v[78:81]
	v_mfma_f32_16x16x32_bf16 v[74:77], v[190:193], v[242:245], v[74:77]
	v_mfma_f32_16x16x32_bf16 v[118:121], v[194:197], v[210:213], v[118:121]
	v_mfma_f32_16x16x32_bf16 v[114:117], v[202:205], v[210:213], v[114:117]
	v_mfma_f32_16x16x32_bf16 v[102:105], v[194:197], v[218:221], v[102:105]
	v_mfma_f32_16x16x32_bf16 v[98:101], v[202:205], v[218:221], v[98:101]
	v_mfma_f32_16x16x32_bf16 v[86:89], v[194:197], v[226:229], v[86:89]
	v_mfma_f32_16x16x32_bf16 v[82:85], v[202:205], v[226:229], v[82:85]
	v_mfma_f32_16x16x32_bf16 v[70:73], v[194:197], v[238:241], v[70:73]
	v_mfma_f32_16x16x32_bf16 v[66:69], v[202:205], v[238:241], v[66:69]
	v_mfma_f32_16x16x32_bf16 v[118:121], v[198:201], v[214:217], v[118:121]
	v_mfma_f32_16x16x32_bf16 v[114:117], v[206:209], v[214:217], v[114:117]
	v_mfma_f32_16x16x32_bf16 v[102:105], v[198:201], v[222:225], v[102:105]
	v_mfma_f32_16x16x32_bf16 v[98:101], v[206:209], v[222:225], v[98:101]
	v_mfma_f32_16x16x32_bf16 v[86:89], v[198:201], v[234:237], v[86:89]
	v_mfma_f32_16x16x32_bf16 v[82:85], v[206:209], v[234:237], v[82:85]
	v_mfma_f32_16x16x32_bf16 v[70:73], v[198:201], v[242:245], v[70:73]
	v_mfma_f32_16x16x32_bf16 v[66:69], v[206:209], v[242:245], v[66:69]
	s_barrier
	s_add_i32 s64, s64, s79
	s_mov_b64 s[98:99], s[58:59]
	s_mov_b32 m0, s64
	ds_read_b128 v[210:213], v188 offset:16384
	ds_read_b128 v[214:217], v188 offset:17408
	ds_read_b128 v[218:221], v188 offset:18432
	ds_read_b128 v[222:225], v188 offset:19456
	ds_read_b128 v[226:229], v188 offset:20480
	ds_read_b128 v[234:237], v188 offset:21504
	ds_read_b128 v[238:241], v188 offset:22528
	ds_read_b128 v[242:245], v188 offset:23552
	global_load_lds_dwordx4 v136, s[58:59]
	s_add_i32 m0, s64, 0x2000
	s_add_u32 s64, s58, 0x40000
	s_addc_u32 s65, s59, 0
	s_add_i32 s66, s66, s79
	global_load_lds_dwordx4 v140, s[58:59]
	s_mov_b32 m0, s66
	s_mov_b64 s[100:101], s[60:61]
	global_load_lds_dwordx4 v136, s[64:65]
	s_add_i32 m0, s66, 0x2000
	s_nop 0
	global_load_lds_dwordx4 v140, s[64:65]
	s_mov_b32 m0, s80
	s_nop 0
	global_load_lds_dwordx4 v134, s[60:61]
	s_mov_b32 m0, s81
	s_nop 0
	global_load_lds_dwordx4 v138, s[60:61]
	s_waitcnt vmcnt(8)
	s_waitcnt lgkmcnt(0)
	s_barrier
	s_waitcnt lgkmcnt(0)
	v_mfma_f32_16x16x32_bf16 v[62:65], v[148:151], v[210:213], v[62:65]
	v_mfma_f32_16x16x32_bf16 v[58:61], v[156:159], v[210:213], v[58:61]
	v_mfma_f32_16x16x32_bf16 v[46:49], v[148:151], v[218:221], v[46:49]
	v_mfma_f32_16x16x32_bf16 v[42:45], v[156:159], v[218:221], v[42:45]
	v_mfma_f32_16x16x32_bf16 v[30:33], v[148:151], v[226:229], v[30:33]
	v_mfma_f32_16x16x32_bf16 v[26:29], v[156:159], v[226:229], v[26:29]
	v_mfma_f32_16x16x32_bf16 v[14:17], v[148:151], v[238:241], v[14:17]
	v_mfma_f32_16x16x32_bf16 v[10:13], v[156:159], v[238:241], v[10:13]
	v_mfma_f32_16x16x32_bf16 v[62:65], v[152:155], v[214:217], v[62:65]
	v_mfma_f32_16x16x32_bf16 v[58:61], v[190:193], v[214:217], v[58:61]
	v_mfma_f32_16x16x32_bf16 v[46:49], v[152:155], v[222:225], v[46:49]
	v_mfma_f32_16x16x32_bf16 v[42:45], v[190:193], v[222:225], v[42:45]
	v_mfma_f32_16x16x32_bf16 v[30:33], v[152:155], v[234:237], v[30:33]
	v_mfma_f32_16x16x32_bf16 v[26:29], v[190:193], v[234:237], v[26:29]
	v_mfma_f32_16x16x32_bf16 v[14:17], v[152:155], v[242:245], v[14:17]
	v_mfma_f32_16x16x32_bf16 v[10:13], v[190:193], v[242:245], v[10:13]
	v_mfma_f32_16x16x32_bf16 v[54:57], v[194:197], v[210:213], v[54:57]
	v_mfma_f32_16x16x32_bf16 v[50:53], v[202:205], v[210:213], v[50:53]
	v_mfma_f32_16x16x32_bf16 v[38:41], v[194:197], v[218:221], v[38:41]
	v_mfma_f32_16x16x32_bf16 v[34:37], v[202:205], v[218:221], v[34:37]
	v_mfma_f32_16x16x32_bf16 v[22:25], v[194:197], v[226:229], v[22:25]
	v_mfma_f32_16x16x32_bf16 v[18:21], v[202:205], v[226:229], v[18:21]
	v_mfma_f32_16x16x32_bf16 v[6:9], v[194:197], v[238:241], v[6:9]
	v_mfma_f32_16x16x32_bf16 v[2:5], v[202:205], v[238:241], v[2:5]
	v_mfma_f32_16x16x32_bf16 v[54:57], v[198:201], v[214:217], v[54:57]
	v_mfma_f32_16x16x32_bf16 v[50:53], v[206:209], v[214:217], v[50:53]
	v_mfma_f32_16x16x32_bf16 v[38:41], v[198:201], v[222:225], v[38:41]
	v_mfma_f32_16x16x32_bf16 v[34:37], v[206:209], v[222:225], v[34:37]
	v_mfma_f32_16x16x32_bf16 v[22:25], v[198:201], v[234:237], v[22:25]
	v_mfma_f32_16x16x32_bf16 v[18:21], v[206:209], v[234:237], v[18:21]
	v_mfma_f32_16x16x32_bf16 v[6:9], v[198:201], v[242:245], v[6:9]
	v_mfma_f32_16x16x32_bf16 v[2:5], v[206:209], v[242:245], v[2:5]
	s_barrier
	s_add_i32 s64, 0, 0x18000
	v_add_u32_e32 v0, s64, v169
	s_add_i32 s65, 0, 0x1c000
	ds_read_b128 v[148:151], v0
	ds_read_b128 v[152:155], v0 offset:1024
	ds_read_b128 v[156:159], v0 offset:2048
	ds_read_b128 v[190:193], v0 offset:3072
	v_add_u32_e32 v0, s65, v169
	ds_read_b128 v[194:197], v0
	ds_read_b128 v[198:201], v0 offset:1024
	ds_read_b128 v[202:205], v0 offset:2048
	ds_read_b128 v[206:209], v0 offset:3072
	s_add_u32 s60, s60, 0x40000
	s_addc_u32 s61, s61, 0
	s_mov_b32 m0, s82
	ds_read_b128 v[210:213], v188 offset:32768
	ds_read_b128 v[214:217], v188 offset:33792
	ds_read_b128 v[218:221], v188 offset:34816
	ds_read_b128 v[222:225], v188 offset:35840
	ds_read_b128 v[226:229], v188 offset:36864
	ds_read_b128 v[234:237], v188 offset:37888
	ds_read_b128 v[238:241], v188 offset:38912
	ds_read_b128 v[242:245], v188 offset:39936
	global_load_lds_dwordx4 v134, s[60:61]
	s_mov_b32 m0, s83
	s_nop 0
	global_load_lds_dwordx4 v138, s[60:61]
	s_waitcnt vmcnt(8)
	s_waitcnt lgkmcnt(0)
	s_barrier
	s_waitcnt lgkmcnt(0)
	v_mfma_f32_16x16x32_bf16 v[126:129], v[148:151], v[210:213], v[126:129]
	v_mfma_f32_16x16x32_bf16 v[122:125], v[156:159], v[210:213], v[122:125]
	v_mfma_f32_16x16x32_bf16 v[110:113], v[148:151], v[218:221], v[110:113]
	v_mfma_f32_16x16x32_bf16 v[106:109], v[156:159], v[218:221], v[106:109]
	v_mfma_f32_16x16x32_bf16 v[94:97], v[148:151], v[226:229], v[94:97]
	v_mfma_f32_16x16x32_bf16 v[90:93], v[156:159], v[226:229], v[90:93]
	v_mfma_f32_16x16x32_bf16 v[78:81], v[148:151], v[238:241], v[78:81]
	v_mfma_f32_16x16x32_bf16 v[74:77], v[156:159], v[238:241], v[74:77]
	v_mfma_f32_16x16x32_bf16 v[126:129], v[152:155], v[214:217], v[126:129]
	v_mfma_f32_16x16x32_bf16 v[122:125], v[190:193], v[214:217], v[122:125]
	v_mfma_f32_16x16x32_bf16 v[110:113], v[152:155], v[222:225], v[110:113]
	v_mfma_f32_16x16x32_bf16 v[106:109], v[190:193], v[222:225], v[106:109]
	v_mfma_f32_16x16x32_bf16 v[94:97], v[152:155], v[234:237], v[94:97]
	v_mfma_f32_16x16x32_bf16 v[90:93], v[190:193], v[234:237], v[90:93]
	v_mfma_f32_16x16x32_bf16 v[78:81], v[152:155], v[242:245], v[78:81]
	v_mfma_f32_16x16x32_bf16 v[74:77], v[190:193], v[242:245], v[74:77]
	v_mfma_f32_16x16x32_bf16 v[118:121], v[194:197], v[210:213], v[118:121]
	v_mfma_f32_16x16x32_bf16 v[114:117], v[202:205], v[210:213], v[114:117]
	v_mfma_f32_16x16x32_bf16 v[102:105], v[194:197], v[218:221], v[102:105]
	v_mfma_f32_16x16x32_bf16 v[98:101], v[202:205], v[218:221], v[98:101]
	v_mfma_f32_16x16x32_bf16 v[86:89], v[194:197], v[226:229], v[86:89]
	v_mfma_f32_16x16x32_bf16 v[82:85], v[202:205], v[226:229], v[82:85]
	v_mfma_f32_16x16x32_bf16 v[70:73], v[194:197], v[238:241], v[70:73]
	v_mfma_f32_16x16x32_bf16 v[66:69], v[202:205], v[238:241], v[66:69]
	v_mfma_f32_16x16x32_bf16 v[118:121], v[198:201], v[214:217], v[118:121]
	v_mfma_f32_16x16x32_bf16 v[114:117], v[206:209], v[214:217], v[114:117]
	v_mfma_f32_16x16x32_bf16 v[102:105], v[198:201], v[222:225], v[102:105]
	v_mfma_f32_16x16x32_bf16 v[98:101], v[206:209], v[222:225], v[98:101]
	v_mfma_f32_16x16x32_bf16 v[86:89], v[198:201], v[234:237], v[86:89]
	v_mfma_f32_16x16x32_bf16 v[82:85], v[206:209], v[234:237], v[82:85]
	v_mfma_f32_16x16x32_bf16 v[70:73], v[198:201], v[242:245], v[70:73]
	v_mfma_f32_16x16x32_bf16 v[66:69], v[206:209], v[242:245], v[66:69]
	s_barrier
	s_add_i32 s60, s64, s79
	s_add_u32 s98, s98, s16
	s_addc_u32 s99, s99, s17
	s_mov_b32 m0, s60
	ds_read_b128 v[210:213], v188 offset:49152
	ds_read_b128 v[214:217], v188 offset:50176
	ds_read_b128 v[218:221], v188 offset:51200
	ds_read_b128 v[222:225], v188 offset:52224
	ds_read_b128 v[226:229], v188 offset:53248
	ds_read_b128 v[234:237], v188 offset:54272
	ds_read_b128 v[238:241], v188 offset:55296
	ds_read_b128 v[242:245], v188 offset:56320
	global_load_lds_dwordx4 v136, s[98:99]
	s_add_i32 m0, s60, 0x2000
	s_add_u32 s58, s58, 0x40080
	s_addc_u32 s59, s59, 0
	s_add_i32 s60, s65, s79
	global_load_lds_dwordx4 v140, s[98:99]
	s_mov_b32 m0, s60
	s_nop 0
	global_load_lds_dwordx4 v136, s[58:59]
	s_add_i32 m0, s60, 0x2000
	s_nop 0
	global_load_lds_dwordx4 v140, s[58:59]
	s_add_u32 s100, s100, s16
	s_addc_u32 s101, s101, s17
	s_mov_b32 m0, s86
	s_nop 0
	global_load_lds_dwordx4 v134, s[100:101]
	s_mov_b32 m0, s87
	s_nop 0
	global_load_lds_dwordx4 v138, s[100:101]
	s_waitcnt vmcnt(8)
	s_waitcnt lgkmcnt(0)
	s_barrier
	s_waitcnt lgkmcnt(0)
	v_mfma_f32_16x16x32_bf16 v[62:65], v[148:151], v[210:213], v[62:65]
	v_mfma_f32_16x16x32_bf16 v[58:61], v[156:159], v[210:213], v[58:61]
	v_mfma_f32_16x16x32_bf16 v[46:49], v[148:151], v[218:221], v[46:49]
	v_mfma_f32_16x16x32_bf16 v[42:45], v[156:159], v[218:221], v[42:45]
	v_mfma_f32_16x16x32_bf16 v[30:33], v[148:151], v[226:229], v[30:33]
	v_mfma_f32_16x16x32_bf16 v[26:29], v[156:159], v[226:229], v[26:29]
	v_mfma_f32_16x16x32_bf16 v[14:17], v[148:151], v[238:241], v[14:17]
	v_mfma_f32_16x16x32_bf16 v[10:13], v[156:159], v[238:241], v[10:13]
	v_mfma_f32_16x16x32_bf16 v[62:65], v[152:155], v[214:217], v[62:65]
	v_mfma_f32_16x16x32_bf16 v[58:61], v[190:193], v[214:217], v[58:61]
	v_mfma_f32_16x16x32_bf16 v[46:49], v[152:155], v[222:225], v[46:49]
	v_mfma_f32_16x16x32_bf16 v[42:45], v[190:193], v[222:225], v[42:45]
	v_mfma_f32_16x16x32_bf16 v[30:33], v[152:155], v[234:237], v[30:33]
	v_mfma_f32_16x16x32_bf16 v[26:29], v[190:193], v[234:237], v[26:29]
	v_mfma_f32_16x16x32_bf16 v[14:17], v[152:155], v[242:245], v[14:17]
	v_mfma_f32_16x16x32_bf16 v[10:13], v[190:193], v[242:245], v[10:13]
	v_mfma_f32_16x16x32_bf16 v[54:57], v[194:197], v[210:213], v[54:57]
	v_mfma_f32_16x16x32_bf16 v[50:53], v[202:205], v[210:213], v[50:53]
	v_mfma_f32_16x16x32_bf16 v[38:41], v[194:197], v[218:221], v[38:41]
	v_mfma_f32_16x16x32_bf16 v[34:37], v[202:205], v[218:221], v[34:37]
	v_mfma_f32_16x16x32_bf16 v[22:25], v[194:197], v[226:229], v[22:25]
	v_mfma_f32_16x16x32_bf16 v[18:21], v[202:205], v[226:229], v[18:21]
	v_mfma_f32_16x16x32_bf16 v[6:9], v[194:197], v[238:241], v[6:9]
	v_mfma_f32_16x16x32_bf16 v[2:5], v[202:205], v[238:241], v[2:5]
	v_mfma_f32_16x16x32_bf16 v[54:57], v[198:201], v[214:217], v[54:57]
	v_mfma_f32_16x16x32_bf16 v[50:53], v[206:209], v[214:217], v[50:53]
	v_mfma_f32_16x16x32_bf16 v[38:41], v[198:201], v[222:225], v[38:41]
	v_mfma_f32_16x16x32_bf16 v[34:37], v[206:209], v[222:225], v[34:37]
	v_mfma_f32_16x16x32_bf16 v[22:25], v[198:201], v[234:237], v[22:25]
	v_mfma_f32_16x16x32_bf16 v[18:21], v[206:209], v[234:237], v[18:21]
	v_mfma_f32_16x16x32_bf16 v[6:9], v[198:201], v[242:245], v[6:9]
	v_mfma_f32_16x16x32_bf16 v[2:5], v[206:209], v[242:245], v[2:5]
	s_barrier
	s_add_i32 s63, s63, 2
	s_add_u32 s48, s48, 0x100
	s_addc_u32 s49, s49, 0
	s_add_u32 s57, s57, 0x100
	s_addc_u32 s62, s62, 0
	s_cmp_gt_u32 s63, 13
	s_cbranch_scc0 .LBB0_3227
	s_and_b64 vcc, exec, s[36:37]
	s_cbranch_vccz .LBB0_3231
	s_barrier
	s_andn2_b64 vcc, exec, s[20:21]
	s_cbranch_vccz .LBB0_3232

.LBB0_3538:
	s_add_i32 m0, s49, 0xc000
	s_and_b64 vcc, exec, s[6:7]
	global_load_lds_dwordx4 v210, s[54:55]
	s_add_i32 m0, s49, 0xe000
	s_nop 0
	global_load_lds_dwordx4 v212, s[54:55]
	s_waitcnt vmcnt(8)
	s_waitcnt lgkmcnt(0)
	s_barrier
	s_cbranch_vccnz .LBB0_3540
	s_waitcnt lgkmcnt(0)
	v_mfma_i32_16x16x64_i8 v[176:179], v[180:183], v[4:7], v[176:179]
	v_mfma_i32_16x16x64_i8 v[168:171], v[188:191], v[4:7], v[168:171]
	v_mfma_i32_16x16x64_i8 v[160:163], v[180:183], v[12:15], v[160:163]
	v_mfma_i32_16x16x64_i8 v[152:155], v[188:191], v[12:15], v[152:155]
	v_mfma_i32_16x16x64_i8 v[144:147], v[180:183], v[20:23], v[144:147]
	v_mfma_i32_16x16x64_i8 v[136:139], v[188:191], v[20:23], v[136:139]
	v_mfma_i32_16x16x64_i8 v[120:123], v[180:183], v[28:31], v[120:123]
	v_mfma_i32_16x16x64_i8 v[104:107], v[188:191], v[28:31], v[104:107]
	v_mfma_i32_16x16x64_i8 v[176:179], v[184:187], v[8:11], v[176:179]
	v_mfma_i32_16x16x64_i8 v[168:171], v[192:195], v[8:11], v[168:171]
	v_mfma_i32_16x16x64_i8 v[160:163], v[184:187], v[16:19], v[160:163]
	v_mfma_i32_16x16x64_i8 v[152:155], v[192:195], v[16:19], v[152:155]
	v_mfma_i32_16x16x64_i8 v[144:147], v[184:187], v[24:27], v[144:147]
	v_mfma_i32_16x16x64_i8 v[136:139], v[192:195], v[24:27], v[136:139]
	v_mfma_i32_16x16x64_i8 v[120:123], v[184:187], v[32:35], v[120:123]
	v_mfma_i32_16x16x64_i8 v[104:107], v[192:195], v[32:35], v[104:107]
	v_mfma_i32_16x16x64_i8 v[172:175], v[108:111], v[4:7], v[172:175]
	v_mfma_i32_16x16x64_i8 v[164:167], v[124:127], v[4:7], v[164:167]
	v_mfma_i32_16x16x64_i8 v[156:159], v[108:111], v[12:15], v[156:159]
	v_mfma_i32_16x16x64_i8 v[148:151], v[124:127], v[12:15], v[148:151]
	v_mfma_i32_16x16x64_i8 v[140:143], v[108:111], v[20:23], v[140:143]
	v_mfma_i32_16x16x64_i8 v[132:135], v[124:127], v[20:23], v[132:135]
	v_mfma_i32_16x16x64_i8 v[116:119], v[108:111], v[28:31], v[116:119]
	v_mfma_i32_16x16x64_i8 v[100:103], v[124:127], v[28:31], v[100:103]
	v_mfma_i32_16x16x64_i8 v[172:175], v[112:115], v[8:11], v[172:175]
	v_mfma_i32_16x16x64_i8 v[164:167], v[128:131], v[8:11], v[164:167]
	v_mfma_i32_16x16x64_i8 v[156:159], v[112:115], v[16:19], v[156:159]
	v_mfma_i32_16x16x64_i8 v[148:151], v[128:131], v[16:19], v[148:151]
	v_mfma_i32_16x16x64_i8 v[140:143], v[112:115], v[24:27], v[140:143]
	v_mfma_i32_16x16x64_i8 v[132:135], v[128:131], v[24:27], v[132:135]
	v_mfma_i32_16x16x64_i8 v[116:119], v[112:115], v[32:35], v[116:119]
	v_mfma_i32_16x16x64_i8 v[100:103], v[128:131], v[32:35], v[100:103]

.LBB0_3542:
	s_add_u32 s56, s54, 0xfffe0080
	s_addc_u32 s57, s55, -1
	s_cmp_eq_u32 s97, 4
	s_cselect_b32 s59, s39, s57
	s_cselect_b32 s58, s93, s56
	s_cselect_b32 s57, s37, s96
	s_cselect_b32 s56, s94, s95
	s_mov_b32 m0, s51
	s_mov_b64 s[98:99], s[56:57]
	s_add_u32 vcc_lo, s56, 0x20000
	global_load_lds_dwordx4 v200, s[56:57]
	s_mov_b32 m0, s73
	s_addc_u32 vcc_hi, s57, 0
	global_load_lds_dwordx4 v204, s[56:57]
	v_lshl_add_u64 v[216:217], vcc, 0, v[200:201]
	s_mov_b32 m0, s74
	s_mov_b64 s[100:101], s[58:59]
	global_load_lds_dwordx4 v[216:217], off
	v_lshl_add_u64 v[216:217], vcc, 0, v[204:205]
	s_mov_b32 m0, s75
	s_and_b64 vcc, exec, s[4:5]
	global_load_lds_dwordx4 v[216:217], off
	s_mov_b32 m0, s49
	s_nop 0
	global_load_lds_dwordx4 v198, s[58:59]
	s_mov_b32 m0, s76
	s_nop 0
	global_load_lds_dwordx4 v202, s[58:59]
	s_waitcnt vmcnt(8)
	s_waitcnt lgkmcnt(0)
	s_barrier
	s_cbranch_vccnz .LBB0_3544
	s_waitcnt lgkmcnt(0)
	v_mfma_i32_16x16x64_i8 v[96:99], v[180:183], v[4:7], v[96:99]
	v_mfma_i32_16x16x64_i8 v[88:91], v[188:191], v[4:7], v[88:91]
	v_mfma_i32_16x16x64_i8 v[80:83], v[180:183], v[12:15], v[80:83]
	v_mfma_i32_16x16x64_i8 v[72:75], v[188:191], v[12:15], v[72:75]
	v_mfma_i32_16x16x64_i8 v[64:67], v[180:183], v[20:23], v[64:67]
	v_mfma_i32_16x16x64_i8 v[56:59], v[188:191], v[20:23], v[56:59]
	v_mfma_i32_16x16x64_i8 v[48:51], v[180:183], v[28:31], v[48:51]
	v_mfma_i32_16x16x64_i8 v[40:43], v[188:191], v[28:31], v[40:43]
	v_mfma_i32_16x16x64_i8 v[96:99], v[184:187], v[8:11], v[96:99]
	v_mfma_i32_16x16x64_i8 v[88:91], v[192:195], v[8:11], v[88:91]
	v_mfma_i32_16x16x64_i8 v[80:83], v[184:187], v[16:19], v[80:83]
	v_mfma_i32_16x16x64_i8 v[72:75], v[192:195], v[16:19], v[72:75]
	v_mfma_i32_16x16x64_i8 v[64:67], v[184:187], v[24:27], v[64:67]
	v_mfma_i32_16x16x64_i8 v[56:59], v[192:195], v[24:27], v[56:59]
	v_mfma_i32_16x16x64_i8 v[48:51], v[184:187], v[32:35], v[48:51]
	v_mfma_i32_16x16x64_i8 v[40:43], v[192:195], v[32:35], v[40:43]
	v_mfma_i32_16x16x64_i8 v[92:95], v[108:111], v[4:7], v[92:95]
	v_mfma_i32_16x16x64_i8 v[84:87], v[124:127], v[4:7], v[84:87]
	v_mfma_i32_16x16x64_i8 v[76:79], v[108:111], v[12:15], v[76:79]
	v_mfma_i32_16x16x64_i8 v[68:71], v[124:127], v[12:15], v[68:71]
	v_mfma_i32_16x16x64_i8 v[60:63], v[108:111], v[20:23], v[60:63]
	v_mfma_i32_16x16x64_i8 v[52:55], v[124:127], v[20:23], v[52:55]
	v_mfma_i32_16x16x64_i8 v[44:47], v[108:111], v[28:31], v[44:47]
	v_mfma_i32_16x16x64_i8 v[36:39], v[124:127], v[28:31], v[36:39]
	v_mfma_i32_16x16x64_i8 v[92:95], v[112:115], v[8:11], v[92:95]
	v_mfma_i32_16x16x64_i8 v[84:87], v[128:131], v[8:11], v[84:87]
	v_mfma_i32_16x16x64_i8 v[76:79], v[112:115], v[16:19], v[76:79]
	v_mfma_i32_16x16x64_i8 v[68:71], v[128:131], v[16:19], v[68:71]
	v_mfma_i32_16x16x64_i8 v[60:63], v[112:115], v[24:27], v[60:63]
	v_mfma_i32_16x16x64_i8 v[52:55], v[128:131], v[24:27], v[52:55]
	v_mfma_i32_16x16x64_i8 v[44:47], v[112:115], v[32:35], v[44:47]
	v_mfma_i32_16x16x64_i8 v[36:39], v[128:131], v[32:35], v[36:39]

.LBB0_3546:
	s_add_u32 s58, s58, 0x20000
	s_addc_u32 s59, s59, 0
	s_mov_b32 m0, s77
	s_nop 0
	global_load_lds_dwordx4 v198, s[58:59]
	s_mov_b32 m0, s78
	s_and_b64 vcc, exec, s[6:7]
	global_load_lds_dwordx4 v202, s[58:59]
	s_waitcnt vmcnt(8)
	s_waitcnt lgkmcnt(0)
	s_barrier
	s_cbranch_vccnz .LBB0_3548
	s_waitcnt lgkmcnt(0)
	v_mfma_i32_16x16x64_i8 v[176:179], v[180:183], v[4:7], v[176:179]
	v_mfma_i32_16x16x64_i8 v[168:171], v[188:191], v[4:7], v[168:171]
	v_mfma_i32_16x16x64_i8 v[160:163], v[180:183], v[12:15], v[160:163]
	v_mfma_i32_16x16x64_i8 v[152:155], v[188:191], v[12:15], v[152:155]
	v_mfma_i32_16x16x64_i8 v[144:147], v[180:183], v[20:23], v[144:147]
	v_mfma_i32_16x16x64_i8 v[136:139], v[188:191], v[20:23], v[136:139]
	v_mfma_i32_16x16x64_i8 v[120:123], v[180:183], v[28:31], v[120:123]
	v_mfma_i32_16x16x64_i8 v[104:107], v[188:191], v[28:31], v[104:107]
	v_mfma_i32_16x16x64_i8 v[176:179], v[184:187], v[8:11], v[176:179]
	v_mfma_i32_16x16x64_i8 v[168:171], v[192:195], v[8:11], v[168:171]
	v_mfma_i32_16x16x64_i8 v[160:163], v[184:187], v[16:19], v[160:163]
	v_mfma_i32_16x16x64_i8 v[152:155], v[192:195], v[16:19], v[152:155]
	v_mfma_i32_16x16x64_i8 v[144:147], v[184:187], v[24:27], v[144:147]
	v_mfma_i32_16x16x64_i8 v[136:139], v[192:195], v[24:27], v[136:139]
	v_mfma_i32_16x16x64_i8 v[120:123], v[184:187], v[32:35], v[120:123]
	v_mfma_i32_16x16x64_i8 v[104:107], v[192:195], v[32:35], v[104:107]
	v_mfma_i32_16x16x64_i8 v[172:175], v[108:111], v[4:7], v[172:175]
	v_mfma_i32_16x16x64_i8 v[164:167], v[124:127], v[4:7], v[164:167]
	v_mfma_i32_16x16x64_i8 v[156:159], v[108:111], v[12:15], v[156:159]
	v_mfma_i32_16x16x64_i8 v[148:151], v[124:127], v[12:15], v[148:151]
	v_mfma_i32_16x16x64_i8 v[140:143], v[108:111], v[20:23], v[140:143]
	v_mfma_i32_16x16x64_i8 v[132:135], v[124:127], v[20:23], v[132:135]
	v_mfma_i32_16x16x64_i8 v[116:119], v[108:111], v[28:31], v[116:119]
	v_mfma_i32_16x16x64_i8 v[100:103], v[124:127], v[28:31], v[100:103]
	v_mfma_i32_16x16x64_i8 v[172:175], v[112:115], v[8:11], v[172:175]
	v_mfma_i32_16x16x64_i8 v[164:167], v[128:131], v[8:11], v[164:167]
	v_mfma_i32_16x16x64_i8 v[156:159], v[112:115], v[16:19], v[156:159]
	v_mfma_i32_16x16x64_i8 v[148:151], v[128:131], v[16:19], v[148:151]
	v_mfma_i32_16x16x64_i8 v[140:143], v[112:115], v[24:27], v[140:143]
	v_mfma_i32_16x16x64_i8 v[132:135], v[128:131], v[24:27], v[132:135]
	v_mfma_i32_16x16x64_i8 v[116:119], v[112:115], v[32:35], v[116:119]
	v_mfma_i32_16x16x64_i8 v[100:103], v[128:131], v[32:35], v[100:103]

.LBB0_3550:
	s_mov_b32 m0, s80
	s_add_u32 s98, s98, s18
	s_addc_u32 s99, s99, s19
	s_add_u32 s6, s56, 0x20080
	global_load_lds_dwordx4 v200, s[98:99]
	s_mov_b32 m0, s81
	s_addc_u32 s7, s57, 0
	global_load_lds_dwordx4 v204, s[98:99]
	s_mov_b32 m0, s84
	s_and_b64 vcc, exec, s[4:5]
	global_load_lds_dwordx4 v200, s[6:7]
	s_mov_b32 m0, s85
	s_nop 0
	global_load_lds_dwordx4 v204, s[6:7]
	s_add_u32 s100, s100, s18
	s_addc_u32 s101, s101, s19
	s_mov_b32 m0, s82
	s_nop 0
	global_load_lds_dwordx4 v198, s[100:101]
	s_mov_b32 m0, s83
	s_nop 0
	global_load_lds_dwordx4 v202, s[100:101]
	s_waitcnt vmcnt(8)
	s_waitcnt lgkmcnt(0)
	s_barrier
	s_cbranch_vccnz .LBB0_3535
	s_waitcnt lgkmcnt(0)
	v_mfma_i32_16x16x64_i8 v[96:99], v[180:183], v[4:7], v[96:99]
	v_mfma_i32_16x16x64_i8 v[88:91], v[188:191], v[4:7], v[88:91]
	v_mfma_i32_16x16x64_i8 v[80:83], v[180:183], v[12:15], v[80:83]
	v_mfma_i32_16x16x64_i8 v[72:75], v[188:191], v[12:15], v[72:75]
	v_mfma_i32_16x16x64_i8 v[64:67], v[180:183], v[20:23], v[64:67]
	v_mfma_i32_16x16x64_i8 v[56:59], v[188:191], v[20:23], v[56:59]
	v_mfma_i32_16x16x64_i8 v[48:51], v[180:183], v[28:31], v[48:51]
	v_mfma_i32_16x16x64_i8 v[40:43], v[188:191], v[28:31], v[40:43]
	v_mfma_i32_16x16x64_i8 v[96:99], v[184:187], v[8:11], v[96:99]
	v_mfma_i32_16x16x64_i8 v[88:91], v[192:195], v[8:11], v[88:91]
	v_mfma_i32_16x16x64_i8 v[80:83], v[184:187], v[16:19], v[80:83]
	v_mfma_i32_16x16x64_i8 v[72:75], v[192:195], v[16:19], v[72:75]
	v_mfma_i32_16x16x64_i8 v[64:67], v[184:187], v[24:27], v[64:67]
	v_mfma_i32_16x16x64_i8 v[56:59], v[192:195], v[24:27], v[56:59]
	v_mfma_i32_16x16x64_i8 v[48:51], v[184:187], v[32:35], v[48:51]
	v_mfma_i32_16x16x64_i8 v[40:43], v[192:195], v[32:35], v[40:43]
	v_mfma_i32_16x16x64_i8 v[92:95], v[108:111], v[4:7], v[92:95]
	v_mfma_i32_16x16x64_i8 v[84:87], v[124:127], v[4:7], v[84:87]
	v_mfma_i32_16x16x64_i8 v[76:79], v[108:111], v[12:15], v[76:79]
	v_mfma_i32_16x16x64_i8 v[68:71], v[124:127], v[12:15], v[68:71]
	v_mfma_i32_16x16x64_i8 v[60:63], v[108:111], v[20:23], v[60:63]
	v_mfma_i32_16x16x64_i8 v[52:55], v[124:127], v[20:23], v[52:55]
	v_mfma_i32_16x16x64_i8 v[44:47], v[108:111], v[28:31], v[44:47]
	v_mfma_i32_16x16x64_i8 v[36:39], v[124:127], v[28:31], v[36:39]
	v_mfma_i32_16x16x64_i8 v[92:95], v[112:115], v[8:11], v[92:95]
	v_mfma_i32_16x16x64_i8 v[84:87], v[128:131], v[8:11], v[84:87]
	v_mfma_i32_16x16x64_i8 v[76:79], v[112:115], v[16:19], v[76:79]
	v_mfma_i32_16x16x64_i8 v[68:71], v[128:131], v[16:19], v[68:71]
	v_mfma_i32_16x16x64_i8 v[60:63], v[112:115], v[24:27], v[60:63]
	v_mfma_i32_16x16x64_i8 v[52:55], v[128:131], v[24:27], v[52:55]
	v_mfma_i32_16x16x64_i8 v[44:47], v[112:115], v[32:35], v[44:47]
	v_mfma_i32_16x16x64_i8 v[36:39], v[128:131], v[32:35], v[36:39]
	s_branch .LBB0_3535

.LBB0_3694:
	s_add_u32 s22, s20, 0xfff50080
	s_addc_u32 s23, s21, -1
	s_add_i32 s57, 0, 0x10000
	s_cmp_eq_u32 s56, 40
	s_cselect_b32 s25, s5, s23
	s_cselect_b32 s24, s4, s22
	v_add_u32_e32 v153, s57, v151
	s_cselect_b32 s23, s19, s55
	s_cselect_b32 s22, s18, s54
	s_add_i32 s60, 0, 0x14000
	ds_read_b128 v[146:149], v153
	ds_read_b128 v[154:157], v153 offset:1024
	ds_read_b128 v[158:161], v153 offset:2048
	ds_read_b128 v[162:165], v153 offset:3072
	v_add_u32_e32 v153, s60, v151
	ds_read_b128 v[166:169], v153
	ds_read_b128 v[170:173], v153 offset:1024
	ds_read_b128 v[174:177], v153 offset:2048
	ds_read_b128 v[178:181], v153 offset:3072
	s_add_i32 m0, s41, 0xc000
	ds_read_b128 v[182:185], v152
	ds_read_b128 v[186:189], v152 offset:1024
	ds_read_b128 v[190:193], v152 offset:2048
	ds_read_b128 v[194:197], v152 offset:3072
	ds_read_b128 v[198:201], v152 offset:4096
	ds_read_b128 v[202:205], v152 offset:5120
	ds_read_b128 v[206:209], v152 offset:6144
	ds_read_b128 v[210:213], v152 offset:7168
	global_load_lds_dwordx4 v142, s[20:21]
	s_add_i32 m0, s41, 0xe000
	s_nop 0
	global_load_lds_dwordx4 v144, s[20:21]
	s_waitcnt vmcnt(8)
	s_waitcnt lgkmcnt(0)
	s_barrier
	s_waitcnt lgkmcnt(0)
	v_mfma_f32_16x16x32_bf16 v[124:127], v[146:149], v[182:185], v[124:127]
	v_mfma_f32_16x16x32_bf16 v[120:123], v[158:161], v[182:185], v[120:123]
	v_mfma_f32_16x16x32_bf16 v[108:111], v[146:149], v[190:193], v[108:111]
	v_mfma_f32_16x16x32_bf16 v[104:107], v[158:161], v[190:193], v[104:107]
	v_mfma_f32_16x16x32_bf16 v[92:95], v[146:149], v[198:201], v[92:95]
	v_mfma_f32_16x16x32_bf16 v[88:91], v[158:161], v[198:201], v[88:91]
	v_mfma_f32_16x16x32_bf16 v[76:79], v[146:149], v[206:209], v[76:79]
	v_mfma_f32_16x16x32_bf16 v[72:75], v[158:161], v[206:209], v[72:75]
	v_mfma_f32_16x16x32_bf16 v[124:127], v[154:157], v[186:189], v[124:127]
	v_mfma_f32_16x16x32_bf16 v[120:123], v[162:165], v[186:189], v[120:123]
	v_mfma_f32_16x16x32_bf16 v[108:111], v[154:157], v[194:197], v[108:111]
	v_mfma_f32_16x16x32_bf16 v[104:107], v[162:165], v[194:197], v[104:107]
	v_mfma_f32_16x16x32_bf16 v[92:95], v[154:157], v[202:205], v[92:95]
	v_mfma_f32_16x16x32_bf16 v[88:91], v[162:165], v[202:205], v[88:91]
	v_mfma_f32_16x16x32_bf16 v[76:79], v[154:157], v[210:213], v[76:79]
	v_mfma_f32_16x16x32_bf16 v[72:75], v[162:165], v[210:213], v[72:75]
	v_mfma_f32_16x16x32_bf16 v[116:119], v[166:169], v[182:185], v[116:119]
	v_mfma_f32_16x16x32_bf16 v[112:115], v[174:177], v[182:185], v[112:115]
	v_mfma_f32_16x16x32_bf16 v[100:103], v[166:169], v[190:193], v[100:103]
	v_mfma_f32_16x16x32_bf16 v[96:99], v[174:177], v[190:193], v[96:99]
	v_mfma_f32_16x16x32_bf16 v[84:87], v[166:169], v[198:201], v[84:87]
	v_mfma_f32_16x16x32_bf16 v[80:83], v[174:177], v[198:201], v[80:83]
	v_mfma_f32_16x16x32_bf16 v[68:71], v[166:169], v[206:209], v[68:71]
	v_mfma_f32_16x16x32_bf16 v[64:67], v[174:177], v[206:209], v[64:67]
	v_mfma_f32_16x16x32_bf16 v[116:119], v[170:173], v[186:189], v[116:119]
	v_mfma_f32_16x16x32_bf16 v[112:115], v[178:181], v[186:189], v[112:115]
	v_mfma_f32_16x16x32_bf16 v[100:103], v[170:173], v[194:197], v[100:103]
	v_mfma_f32_16x16x32_bf16 v[96:99], v[178:181], v[194:197], v[96:99]
	v_mfma_f32_16x16x32_bf16 v[84:87], v[170:173], v[202:205], v[84:87]
	v_mfma_f32_16x16x32_bf16 v[80:83], v[178:181], v[202:205], v[80:83]
	v_mfma_f32_16x16x32_bf16 v[68:71], v[170:173], v[210:213], v[68:71]
	v_mfma_f32_16x16x32_bf16 v[64:67], v[178:181], v[210:213], v[64:67]
	s_barrier
	s_add_i32 s57, s57, s40
	s_mov_b64 s[98:99], s[22:23]
	s_mov_b32 m0, s57
	ds_read_b128 v[182:185], v152 offset:16384
	ds_read_b128 v[186:189], v152 offset:17408
	ds_read_b128 v[190:193], v152 offset:18432
	ds_read_b128 v[194:197], v152 offset:19456
	ds_read_b128 v[198:201], v152 offset:20480
	ds_read_b128 v[202:205], v152 offset:21504
	ds_read_b128 v[206:209], v152 offset:22528
	ds_read_b128 v[210:213], v152 offset:23552
	global_load_lds_dwordx4 v128, s[22:23]
	s_add_i32 m0, s57, 0x2000
	s_add_u32 s58, s22, 0xb0000
	s_addc_u32 s59, s23, 0
	s_add_i32 s57, s60, s40
	global_load_lds_dwordx4 v138, s[22:23]
	s_mov_b32 m0, s57
	s_mov_b64 s[100:101], s[24:25]
	global_load_lds_dwordx4 v128, s[58:59]
	s_add_i32 m0, s57, 0x2000
	s_nop 0
	global_load_lds_dwordx4 v138, s[58:59]
	s_mov_b32 m0, s41
	s_nop 0
	global_load_lds_dwordx4 v134, s[24:25]
	s_mov_b32 m0, s42
	s_nop 0
	global_load_lds_dwordx4 v136, s[24:25]
	s_waitcnt vmcnt(8)
	s_waitcnt lgkmcnt(0)
	s_barrier
	s_waitcnt lgkmcnt(0)
	v_mfma_f32_16x16x32_bf16 v[60:63], v[146:149], v[182:185], v[60:63]
	v_mfma_f32_16x16x32_bf16 v[56:59], v[158:161], v[182:185], v[56:59]
	v_mfma_f32_16x16x32_bf16 v[44:47], v[146:149], v[190:193], v[44:47]
	v_mfma_f32_16x16x32_bf16 v[40:43], v[158:161], v[190:193], v[40:43]
	v_mfma_f32_16x16x32_bf16 v[28:31], v[146:149], v[198:201], v[28:31]
	v_mfma_f32_16x16x32_bf16 v[24:27], v[158:161], v[198:201], v[24:27]
	v_mfma_f32_16x16x32_bf16 v[12:15], v[146:149], v[206:209], v[12:15]
	v_mfma_f32_16x16x32_bf16 v[8:11], v[158:161], v[206:209], v[8:11]
	v_mfma_f32_16x16x32_bf16 v[60:63], v[154:157], v[186:189], v[60:63]
	v_mfma_f32_16x16x32_bf16 v[56:59], v[162:165], v[186:189], v[56:59]
	v_mfma_f32_16x16x32_bf16 v[44:47], v[154:157], v[194:197], v[44:47]
	v_mfma_f32_16x16x32_bf16 v[40:43], v[162:165], v[194:197], v[40:43]
	v_mfma_f32_16x16x32_bf16 v[28:31], v[154:157], v[202:205], v[28:31]
	v_mfma_f32_16x16x32_bf16 v[24:27], v[162:165], v[202:205], v[24:27]
	v_mfma_f32_16x16x32_bf16 v[12:15], v[154:157], v[210:213], v[12:15]
	v_mfma_f32_16x16x32_bf16 v[8:11], v[162:165], v[210:213], v[8:11]
	v_mfma_f32_16x16x32_bf16 v[52:55], v[166:169], v[182:185], v[52:55]
	v_mfma_f32_16x16x32_bf16 v[48:51], v[174:177], v[182:185], v[48:51]
	v_mfma_f32_16x16x32_bf16 v[36:39], v[166:169], v[190:193], v[36:39]
	v_mfma_f32_16x16x32_bf16 v[32:35], v[174:177], v[190:193], v[32:35]
	v_mfma_f32_16x16x32_bf16 v[20:23], v[166:169], v[198:201], v[20:23]
	v_mfma_f32_16x16x32_bf16 v[16:19], v[174:177], v[198:201], v[16:19]
	v_mfma_f32_16x16x32_bf16 v[4:7], v[166:169], v[206:209], v[4:7]
	v_mfma_f32_16x16x32_bf16 v[0:3], v[174:177], v[206:209], v[0:3]
	v_mfma_f32_16x16x32_bf16 v[52:55], v[170:173], v[186:189], v[52:55]
	v_mfma_f32_16x16x32_bf16 v[48:51], v[178:181], v[186:189], v[48:51]
	v_mfma_f32_16x16x32_bf16 v[36:39], v[170:173], v[194:197], v[36:39]
	v_mfma_f32_16x16x32_bf16 v[32:35], v[178:181], v[194:197], v[32:35]
	v_mfma_f32_16x16x32_bf16 v[20:23], v[170:173], v[202:205], v[20:23]
	v_mfma_f32_16x16x32_bf16 v[16:19], v[178:181], v[202:205], v[16:19]
	v_mfma_f32_16x16x32_bf16 v[4:7], v[170:173], v[210:213], v[4:7]
	v_mfma_f32_16x16x32_bf16 v[0:3], v[178:181], v[210:213], v[0:3]
	s_barrier
	s_add_i32 s57, 0, 0x18000
	v_add_u32_e32 v153, s57, v151
	s_add_i32 s58, 0, 0x1c000
	ds_read_b128 v[146:149], v153
	ds_read_b128 v[154:157], v153 offset:1024
	ds_read_b128 v[158:161], v153 offset:2048
	ds_read_b128 v[162:165], v153 offset:3072
	v_add_u32_e32 v153, s58, v151
	ds_read_b128 v[166:169], v153
	ds_read_b128 v[170:173], v153 offset:1024
	ds_read_b128 v[174:177], v153 offset:2048
	ds_read_b128 v[178:181], v153 offset:3072
	s_add_u32 s24, s24, 0xb0000
	s_addc_u32 s25, s25, 0
	s_mov_b32 m0, s43
	ds_read_b128 v[182:185], v152 offset:32768
	ds_read_b128 v[186:189], v152 offset:33792
	ds_read_b128 v[190:193], v152 offset:34816
	ds_read_b128 v[194:197], v152 offset:35840
	ds_read_b128 v[198:201], v152 offset:36864
	ds_read_b128 v[202:205], v152 offset:37888
	ds_read_b128 v[206:209], v152 offset:38912
	ds_read_b128 v[210:213], v152 offset:39936
	global_load_lds_dwordx4 v134, s[24:25]
	s_mov_b32 m0, s44
	s_nop 0
	global_load_lds_dwordx4 v136, s[24:25]
	s_waitcnt vmcnt(8)
	s_waitcnt lgkmcnt(0)
	s_barrier
	s_waitcnt lgkmcnt(0)
	v_mfma_f32_16x16x32_bf16 v[124:127], v[146:149], v[182:185], v[124:127]
	v_mfma_f32_16x16x32_bf16 v[120:123], v[158:161], v[182:185], v[120:123]
	v_mfma_f32_16x16x32_bf16 v[108:111], v[146:149], v[190:193], v[108:111]
	v_mfma_f32_16x16x32_bf16 v[104:107], v[158:161], v[190:193], v[104:107]
	v_mfma_f32_16x16x32_bf16 v[92:95], v[146:149], v[198:201], v[92:95]
	v_mfma_f32_16x16x32_bf16 v[88:91], v[158:161], v[198:201], v[88:91]
	v_mfma_f32_16x16x32_bf16 v[76:79], v[146:149], v[206:209], v[76:79]
	v_mfma_f32_16x16x32_bf16 v[72:75], v[158:161], v[206:209], v[72:75]
	v_mfma_f32_16x16x32_bf16 v[124:127], v[154:157], v[186:189], v[124:127]
	v_mfma_f32_16x16x32_bf16 v[120:123], v[162:165], v[186:189], v[120:123]
	v_mfma_f32_16x16x32_bf16 v[108:111], v[154:157], v[194:197], v[108:111]
	v_mfma_f32_16x16x32_bf16 v[104:107], v[162:165], v[194:197], v[104:107]
	v_mfma_f32_16x16x32_bf16 v[92:95], v[154:157], v[202:205], v[92:95]
	v_mfma_f32_16x16x32_bf16 v[88:91], v[162:165], v[202:205], v[88:91]
	v_mfma_f32_16x16x32_bf16 v[76:79], v[154:157], v[210:213], v[76:79]
	v_mfma_f32_16x16x32_bf16 v[72:75], v[162:165], v[210:213], v[72:75]
	v_mfma_f32_16x16x32_bf16 v[116:119], v[166:169], v[182:185], v[116:119]
	v_mfma_f32_16x16x32_bf16 v[112:115], v[174:177], v[182:185], v[112:115]
	v_mfma_f32_16x16x32_bf16 v[100:103], v[166:169], v[190:193], v[100:103]
	v_mfma_f32_16x16x32_bf16 v[96:99], v[174:177], v[190:193], v[96:99]
	v_mfma_f32_16x16x32_bf16 v[84:87], v[166:169], v[198:201], v[84:87]
	v_mfma_f32_16x16x32_bf16 v[80:83], v[174:177], v[198:201], v[80:83]
	v_mfma_f32_16x16x32_bf16 v[68:71], v[166:169], v[206:209], v[68:71]
	v_mfma_f32_16x16x32_bf16 v[64:67], v[174:177], v[206:209], v[64:67]
	v_mfma_f32_16x16x32_bf16 v[116:119], v[170:173], v[186:189], v[116:119]
	v_mfma_f32_16x16x32_bf16 v[112:115], v[178:181], v[186:189], v[112:115]
	v_mfma_f32_16x16x32_bf16 v[100:103], v[170:173], v[194:197], v[100:103]
	v_mfma_f32_16x16x32_bf16 v[96:99], v[178:181], v[194:197], v[96:99]
	v_mfma_f32_16x16x32_bf16 v[84:87], v[170:173], v[202:205], v[84:87]
	v_mfma_f32_16x16x32_bf16 v[80:83], v[178:181], v[202:205], v[80:83]
	v_mfma_f32_16x16x32_bf16 v[68:71], v[170:173], v[210:213], v[68:71]
	v_mfma_f32_16x16x32_bf16 v[64:67], v[178:181], v[210:213], v[64:67]
	s_barrier
	s_add_i32 s24, s57, s40
	s_add_u32 s98, s98, s6
	s_addc_u32 s99, s99, s7
	s_mov_b32 m0, s24
	ds_read_b128 v[182:185], v152 offset:49152
	ds_read_b128 v[186:189], v152 offset:50176
	ds_read_b128 v[190:193], v152 offset:51200
	ds_read_b128 v[194:197], v152 offset:52224
	ds_read_b128 v[198:201], v152 offset:53248
	ds_read_b128 v[202:205], v152 offset:54272
	ds_read_b128 v[206:209], v152 offset:55296
	ds_read_b128 v[210:213], v152 offset:56320
	global_load_lds_dwordx4 v128, s[98:99]
	s_add_i32 m0, s24, 0x2000
	s_add_u32 s22, s22, 0xb0080
	s_addc_u32 s23, s23, 0
	s_add_i32 s24, s58, s40
	global_load_lds_dwordx4 v138, s[98:99]
	s_mov_b32 m0, s24
	s_nop 0
	global_load_lds_dwordx4 v128, s[22:23]
	s_add_i32 m0, s24, 0x2000
	s_nop 0
	global_load_lds_dwordx4 v138, s[22:23]
	s_add_u32 s100, s100, s6
	s_addc_u32 s101, s101, s7
	s_mov_b32 m0, s45
	s_nop 0
	global_load_lds_dwordx4 v134, s[100:101]
	s_mov_b32 m0, s48
	s_nop 0
	global_load_lds_dwordx4 v136, s[100:101]
	s_waitcnt vmcnt(8)
	s_waitcnt lgkmcnt(0)
	s_barrier
	s_waitcnt lgkmcnt(0)
	v_mfma_f32_16x16x32_bf16 v[60:63], v[146:149], v[182:185], v[60:63]
	v_mfma_f32_16x16x32_bf16 v[56:59], v[158:161], v[182:185], v[56:59]
	v_mfma_f32_16x16x32_bf16 v[44:47], v[146:149], v[190:193], v[44:47]
	v_mfma_f32_16x16x32_bf16 v[40:43], v[158:161], v[190:193], v[40:43]
	v_mfma_f32_16x16x32_bf16 v[28:31], v[146:149], v[198:201], v[28:31]
	v_mfma_f32_16x16x32_bf16 v[24:27], v[158:161], v[198:201], v[24:27]
	v_mfma_f32_16x16x32_bf16 v[12:15], v[146:149], v[206:209], v[12:15]
	v_mfma_f32_16x16x32_bf16 v[8:11], v[158:161], v[206:209], v[8:11]
	v_mfma_f32_16x16x32_bf16 v[60:63], v[154:157], v[186:189], v[60:63]
	v_mfma_f32_16x16x32_bf16 v[56:59], v[162:165], v[186:189], v[56:59]
	v_mfma_f32_16x16x32_bf16 v[44:47], v[154:157], v[194:197], v[44:47]
	v_mfma_f32_16x16x32_bf16 v[40:43], v[162:165], v[194:197], v[40:43]
	v_mfma_f32_16x16x32_bf16 v[28:31], v[154:157], v[202:205], v[28:31]
	v_mfma_f32_16x16x32_bf16 v[24:27], v[162:165], v[202:205], v[24:27]
	v_mfma_f32_16x16x32_bf16 v[12:15], v[154:157], v[210:213], v[12:15]
	v_mfma_f32_16x16x32_bf16 v[8:11], v[162:165], v[210:213], v[8:11]
	v_mfma_f32_16x16x32_bf16 v[52:55], v[166:169], v[182:185], v[52:55]
	v_mfma_f32_16x16x32_bf16 v[48:51], v[174:177], v[182:185], v[48:51]
	v_mfma_f32_16x16x32_bf16 v[36:39], v[166:169], v[190:193], v[36:39]
	v_mfma_f32_16x16x32_bf16 v[32:35], v[174:177], v[190:193], v[32:35]
	v_mfma_f32_16x16x32_bf16 v[20:23], v[166:169], v[198:201], v[20:23]
	v_mfma_f32_16x16x32_bf16 v[16:19], v[174:177], v[198:201], v[16:19]
	v_mfma_f32_16x16x32_bf16 v[4:7], v[166:169], v[206:209], v[4:7]
	v_mfma_f32_16x16x32_bf16 v[0:3], v[174:177], v[206:209], v[0:3]
	v_mfma_f32_16x16x32_bf16 v[52:55], v[170:173], v[186:189], v[52:55]
	v_mfma_f32_16x16x32_bf16 v[48:51], v[178:181], v[186:189], v[48:51]
	v_mfma_f32_16x16x32_bf16 v[36:39], v[170:173], v[194:197], v[36:39]
	v_mfma_f32_16x16x32_bf16 v[32:35], v[178:181], v[194:197], v[32:35]
	v_mfma_f32_16x16x32_bf16 v[20:23], v[170:173], v[202:205], v[20:23]
	v_mfma_f32_16x16x32_bf16 v[16:19], v[178:181], v[202:205], v[16:19]
	v_mfma_f32_16x16x32_bf16 v[4:7], v[170:173], v[210:213], v[4:7]
	v_mfma_f32_16x16x32_bf16 v[0:3], v[178:181], v[210:213], v[0:3]
	s_barrier
	s_add_i32 s56, s56, 2
	s_add_u32 s20, s20, 0x100
	s_addc_u32 s21, s21, 0
	s_add_u32 s54, s54, 0x100
	s_addc_u32 s55, s55, 0
	s_cmp_gt_u32 s56, 41
	s_cbranch_scc0 .LBB0_3694
	s_and_b64 vcc, exec, s[16:17]
	s_cbranch_vccz .LBB0_3698
	s_barrier
	s_andn2_b64 vcc, exec, s[12:13]
	s_cbranch_vccz .LBB0_3699
